# GEMM K-loops: s_setprio 1 moved ahead of the pre-MFMA barrier and s_setprio 0 behind the post-MFMA barrier, redundant lgkmcnt(0) after the barrier dropped (fewer issue slots between barrier release an
# speedup vs baseline: 1.0083x; 1.0036x over previous
; #define PG8_STAGE(bufoff, gbase, voff) do { _Pragma("unroll") for (int _i = 0; _i < 2; ++_i) \
;         __builtin_amdgcn_global_load_lds((const unsigned*)((const char*)(gbase) + (voff)[_i]), (PG8_LAS unsigned*)(lds + (bufoff) + ldsw + _i * 8192), 16, 0, 0); } while (0)
; #define PG8_LDA(dst, b, h) do { _Pragma("unroll") for (int m = 0; m < 4; ++m) _Pragma("unroll") for (int k = 0; k < 2; ++k) dst[m][k] = *(const PG8_LAS bf16x8*)(lds + PG8_SA(b, h) + aoff + m * 2048 + k * 1024); } while (0)
; #define PG8_LDB(dst, b, h) do { _Pragma("unroll") for (int n = 0; n < 2; ++n) _Pragma("unroll") for (int k = 0; k < 2; ++k) dst[n][k] = *(const PG8_LAS bf16x8*)(lds + PG8_SB(b, h) + boff + n * 2048 + k * 1024); } while (0)
; #define PG8_MMA(ai, bj, At, Bt) do { __builtin_amdgcn_s_setprio(1); _Pragma("unroll") for (int m = 0; m < 4; ++m) _Pragma("unroll") for (int n = 0; n < 2; ++n) _Pragma("unroll") for (int k = 0; k < 2; ++k) \
;         acc[ai][bj][m][n] = __builtin_amdgcn_mfma_f32_16x16x32_bf16(Bt[n][k], At[m][k], acc[ai][bj][m][n], 0, 0, 0); __builtin_amdgcn_s_setprio(0); } while (0)
; #define PG8_WAIT_V(n) asm volatile("s_waitcnt vmcnt(" #n ")" ::: "memory")
; #define PG8_WAIT_L(n) asm volatile("s_waitcnt lgkmcnt(" #n ")" ::: "memory")
; #define PG8_BAR __builtin_amdgcn_s_barrier()
; #define PG8_SCHED __builtin_amdgcn_sched_barrier(0)
; template <class Epi, class Sched, bool ALIGN_EPI = false, bool SP2 = false>
; __device__ __forceinline__ void gemm_phase(PG8_LAS unsigned char* lds, const Gemm g, const Sched& S, const Epi& E, const int wid) {
;     ...
;             PG8_LDB(B0, 0, 0); PG8_LDB(B1, 0, 1); PG8_SCHED; PG8_LDA(At, 0, 0); PG8_STAGE(PG8_SA(1, 1), a1 + hstep, voffA);
;             PG8_WAIT_V(8); PG8_WAIT_L(0); PG8_BAR; PG8_MMA(0, 0, At, B0); PG8_MMA(0, 1, At, B1); PG8_BAR; PG8_SCHED;
;             PG8_LDA(At, 0, 1); PG8_STAGE(PG8_SB(0, 0), b2, voffB); PG8_STAGE(PG8_SB(0, 1), b2 + hstep, voffB); PG8_STAGE(PG8_SA(0, 0), a2, voffA);
.LBB0_335:
	ds_read_b128 v[146:149], v157
	ds_read_b128 v[150:153], v157 offset:1024
	ds_read_b128 v[162:165], v157 offset:2048
	ds_read_b128 v[166:169], v157 offset:3072
	ds_read_b128 v[170:173], v158
	ds_read_b128 v[174:177], v158 offset:1024
	ds_read_b128 v[178:181], v158 offset:2048
	ds_read_b128 v[182:185], v158 offset:3072
	s_add_u32 s48, s12, 0xfff80080
	s_addc_u32 s49, s13, -1
	s_cmp_eq_u32 s69, 28
	s_cselect_b32 s51, s9, s49
	s_cselect_b32 s50, s11, s48
	s_cselect_b32 s49, s31, s68
	s_cselect_b32 s48, s43, s67
	v_lshl_add_u64 v[218:219], s[12:13], 0, v[138:139]
	s_add_i32 m0, s41, 0xc000
	ds_read_b128 v[186:189], v159
	ds_read_b128 v[190:193], v159 offset:1024
	ds_read_b128 v[194:197], v159 offset:2048
	ds_read_b128 v[198:201], v159 offset:3072
	ds_read_b128 v[202:205], v159 offset:4096
	ds_read_b128 v[206:209], v159 offset:5120
	ds_read_b128 v[210:213], v159 offset:6144
	ds_read_b128 v[214:217], v159 offset:7168
	global_load_lds_dwordx4 v[218:219], off
	v_lshl_add_u64 v[218:219], s[12:13], 0, v[140:141]
	s_add_i32 m0, s41, 0xe000
	s_nop 0
	global_load_lds_dwordx4 v[218:219], off
	s_waitcnt vmcnt(8)
	s_waitcnt lgkmcnt(0)
	s_setprio 1
	s_barrier
	v_mfma_f32_16x16x32_bf16 v[124:127], v[146:149], v[186:189], v[124:127]
	v_mfma_f32_16x16x32_bf16 v[120:123], v[162:165], v[186:189], v[120:123]
	v_mfma_f32_16x16x32_bf16 v[108:111], v[146:149], v[194:197], v[108:111]
	v_mfma_f32_16x16x32_bf16 v[104:107], v[162:165], v[194:197], v[104:107]
	v_mfma_f32_16x16x32_bf16 v[92:95], v[146:149], v[202:205], v[92:95]
	v_mfma_f32_16x16x32_bf16 v[88:91], v[162:165], v[202:205], v[88:91]
	v_mfma_f32_16x16x32_bf16 v[76:79], v[146:149], v[210:213], v[76:79]
	v_mfma_f32_16x16x32_bf16 v[72:75], v[162:165], v[210:213], v[72:75]
	v_mfma_f32_16x16x32_bf16 v[124:127], v[150:153], v[190:193], v[124:127]
	v_mfma_f32_16x16x32_bf16 v[120:123], v[166:169], v[190:193], v[120:123]
	v_mfma_f32_16x16x32_bf16 v[108:111], v[150:153], v[198:201], v[108:111]
	v_mfma_f32_16x16x32_bf16 v[104:107], v[166:169], v[198:201], v[104:107]
	v_mfma_f32_16x16x32_bf16 v[92:95], v[150:153], v[206:209], v[92:95]
	v_mfma_f32_16x16x32_bf16 v[88:91], v[166:169], v[206:209], v[88:91]
	v_mfma_f32_16x16x32_bf16 v[76:79], v[150:153], v[214:217], v[76:79]
	v_mfma_f32_16x16x32_bf16 v[72:75], v[166:169], v[214:217], v[72:75]
	s_setprio 0
	s_setprio 1
	v_mfma_f32_16x16x32_bf16 v[112:115], v[170:173], v[186:189], v[112:115]
	v_mfma_f32_16x16x32_bf16 v[116:119], v[178:181], v[186:189], v[116:119]
	v_mfma_f32_16x16x32_bf16 v[96:99], v[170:173], v[194:197], v[96:99]
	v_mfma_f32_16x16x32_bf16 v[100:103], v[178:181], v[194:197], v[100:103]
	v_mfma_f32_16x16x32_bf16 v[80:83], v[170:173], v[202:205], v[80:83]
	v_mfma_f32_16x16x32_bf16 v[84:87], v[178:181], v[202:205], v[84:87]
	v_mfma_f32_16x16x32_bf16 v[64:67], v[170:173], v[210:213], v[64:67]
	v_mfma_f32_16x16x32_bf16 v[68:71], v[178:181], v[210:213], v[68:71]
	v_mfma_f32_16x16x32_bf16 v[112:115], v[174:177], v[190:193], v[112:115]
	v_mfma_f32_16x16x32_bf16 v[116:119], v[182:185], v[190:193], v[116:119]
	v_mfma_f32_16x16x32_bf16 v[96:99], v[174:177], v[198:201], v[96:99]
	v_mfma_f32_16x16x32_bf16 v[100:103], v[182:185], v[198:201], v[100:103]
	v_mfma_f32_16x16x32_bf16 v[80:83], v[174:177], v[206:209], v[80:83]
	v_mfma_f32_16x16x32_bf16 v[84:87], v[182:185], v[206:209], v[84:87]
	v_mfma_f32_16x16x32_bf16 v[64:67], v[174:177], v[214:217], v[64:67]
	v_mfma_f32_16x16x32_bf16 v[68:71], v[182:185], v[214:217], v[68:71]
	s_barrier
	s_setprio 0
	s_add_i32 s70, s62, s3
	v_lshl_add_u64 v[218:219], s[48:49], 0, v[130:131]
	s_mov_b32 m0, s70
	ds_read_b128 v[186:189], v159 offset:16384
	ds_read_b128 v[190:193], v159 offset:17408
	ds_read_b128 v[194:197], v159 offset:18432
	ds_read_b128 v[198:201], v159 offset:19456
	ds_read_b128 v[202:205], v159 offset:20480
	ds_read_b128 v[206:209], v159 offset:21504
	ds_read_b128 v[210:213], v159 offset:22528
	ds_read_b128 v[214:217], v159 offset:23552
	global_load_lds_dwordx4 v[218:219], off
	s_add_i32 m0, s70, 0x2000
	s_add_u32 s70, s48, 0x80000
	v_lshl_add_u64 v[220:221], s[48:49], 0, v[134:135]
	s_addc_u32 s71, s49, 0
	s_add_i32 s72, s63, s3
	global_load_lds_dwordx4 v[220:221], off
	v_lshl_add_u64 v[222:223], s[70:71], 0, v[130:131]
	s_mov_b32 m0, s72
	v_lshl_add_u64 v[224:225], s[50:51], 0, v[132:133]
	global_load_lds_dwordx4 v[222:223], off
	v_lshl_add_u64 v[222:223], s[70:71], 0, v[134:135]
	s_add_i32 m0, s72, 0x2000
	s_nop 0
	global_load_lds_dwordx4 v[222:223], off
	v_lshl_add_u64 v[222:223], s[50:51], 0, v[128:129]
	s_mov_b32 m0, s41
	s_nop 0
	global_load_lds_dwordx4 v[222:223], off
	s_mov_b32 m0, s52
	s_nop 0
	global_load_lds_dwordx4 v[224:225], off
	s_waitcnt vmcnt(8)
	s_waitcnt lgkmcnt(0)
	s_setprio 1
	s_barrier
; #define PG8_STAGE(bufoff, gbase, voff) do { _Pragma("unroll") for (int _i = 0; _i < 2; ++_i) \
;         __builtin_amdgcn_global_load_lds((const unsigned*)((const char*)(gbase) + (voff)[_i]), (PG8_LAS unsigned*)(lds + (bufoff) + ldsw + _i * 8192), 16, 0, 0); } while (0)
; #define PG8_LDA(dst, b, h) do { _Pragma("unroll") for (int m = 0; m < 4; ++m) _Pragma("unroll") for (int k = 0; k < 2; ++k) dst[m][k] = *(const PG8_LAS bf16x8*)(lds + PG8_SA(b, h) + aoff + m * 2048 + k * 1024); } while (0)
; #define PG8_LDB(dst, b, h) do { _Pragma("unroll") for (int n = 0; n < 2; ++n) _Pragma("unroll") for (int k = 0; k < 2; ++k) dst[n][k] = *(const PG8_LAS bf16x8*)(lds + PG8_SB(b, h) + boff + n * 2048 + k * 1024); } while (0)
; #define PG8_MMA(ai, bj, At, Bt) do { __builtin_amdgcn_s_setprio(1); _Pragma("unroll") for (int m = 0; m < 4; ++m) _Pragma("unroll") for (int n = 0; n < 2; ++n) _Pragma("unroll") for (int k = 0; k < 2; ++k) \
;         acc[ai][bj][m][n] = __builtin_amdgcn_mfma_f32_16x16x32_bf16(Bt[n][k], At[m][k], acc[ai][bj][m][n], 0, 0, 0); __builtin_amdgcn_s_setprio(0); } while (0)
; #define PG8_WAIT_V(n) asm volatile("s_waitcnt vmcnt(" #n ")" ::: "memory")
; #define PG8_WAIT_L(n) asm volatile("s_waitcnt lgkmcnt(" #n ")" ::: "memory")
; #define PG8_BAR __builtin_amdgcn_s_barrier()
; #define PG8_SCHED __builtin_amdgcn_sched_barrier(0)
; template <class Epi, class Sched, bool ALIGN_EPI = false, bool SP2 = false>
; __device__ __forceinline__ void gemm_phase(PG8_LAS unsigned char* lds, const Gemm g, const Sched& S, const Epi& E, const int wid) {
;     ...
;             PG8_WAIT_V(8); PG8_WAIT_L(0); PG8_BAR; PG8_MMA(1, 0, At, B0); PG8_MMA(1, 1, At, B1); PG8_BAR; PG8_SCHED;
;             PG8_LDB(B0, 1, 0); PG8_LDB(B1, 1, 1); PG8_SCHED; PG8_LDA(At, 1, 0); PG8_STAGE(PG8_SA(0, 1), a2 + hstep, voffA);
;             PG8_WAIT_V(8); PG8_WAIT_L(0); PG8_BAR; PG8_MMA(0, 0, At, B0); PG8_MMA(0, 1, At, B1); PG8_BAR; PG8_SCHED;
	v_mfma_f32_16x16x32_bf16 v[60:63], v[146:149], v[186:189], v[60:63]
	v_mfma_f32_16x16x32_bf16 v[56:59], v[162:165], v[186:189], v[56:59]
	v_mfma_f32_16x16x32_bf16 v[44:47], v[146:149], v[194:197], v[44:47]
	v_mfma_f32_16x16x32_bf16 v[40:43], v[162:165], v[194:197], v[40:43]
	v_mfma_f32_16x16x32_bf16 v[28:31], v[146:149], v[202:205], v[28:31]
	v_mfma_f32_16x16x32_bf16 v[24:27], v[162:165], v[202:205], v[24:27]
	v_mfma_f32_16x16x32_bf16 v[12:15], v[146:149], v[210:213], v[12:15]
	v_mfma_f32_16x16x32_bf16 v[8:11], v[162:165], v[210:213], v[8:11]
	v_mfma_f32_16x16x32_bf16 v[60:63], v[150:153], v[190:193], v[60:63]
	v_mfma_f32_16x16x32_bf16 v[56:59], v[166:169], v[190:193], v[56:59]
	v_mfma_f32_16x16x32_bf16 v[44:47], v[150:153], v[198:201], v[44:47]
	v_mfma_f32_16x16x32_bf16 v[40:43], v[166:169], v[198:201], v[40:43]
	v_mfma_f32_16x16x32_bf16 v[28:31], v[150:153], v[206:209], v[28:31]
	v_mfma_f32_16x16x32_bf16 v[24:27], v[166:169], v[206:209], v[24:27]
	v_mfma_f32_16x16x32_bf16 v[12:15], v[150:153], v[214:217], v[12:15]
	v_mfma_f32_16x16x32_bf16 v[8:11], v[166:169], v[214:217], v[8:11]
	s_setprio 0
	s_setprio 1
	v_mfma_f32_16x16x32_bf16 v[48:51], v[170:173], v[186:189], v[48:51]
	v_mfma_f32_16x16x32_bf16 v[52:55], v[178:181], v[186:189], v[52:55]
	v_mfma_f32_16x16x32_bf16 v[32:35], v[170:173], v[194:197], v[32:35]
	v_mfma_f32_16x16x32_bf16 v[36:39], v[178:181], v[194:197], v[36:39]
	v_mfma_f32_16x16x32_bf16 v[16:19], v[170:173], v[202:205], v[16:19]
	v_mfma_f32_16x16x32_bf16 v[20:23], v[178:181], v[202:205], v[20:23]
	v_mfma_f32_16x16x32_bf16 v[0:3], v[170:173], v[210:213], v[0:3]
	v_mfma_f32_16x16x32_bf16 v[4:7], v[178:181], v[210:213], v[4:7]
	v_mfma_f32_16x16x32_bf16 v[48:51], v[174:177], v[190:193], v[48:51]
	v_mfma_f32_16x16x32_bf16 v[52:55], v[182:185], v[190:193], v[52:55]
	v_mfma_f32_16x16x32_bf16 v[32:35], v[174:177], v[198:201], v[32:35]
	v_mfma_f32_16x16x32_bf16 v[36:39], v[182:185], v[198:201], v[36:39]
	v_mfma_f32_16x16x32_bf16 v[16:19], v[174:177], v[206:209], v[16:19]
	v_mfma_f32_16x16x32_bf16 v[20:23], v[182:185], v[206:209], v[20:23]
	v_mfma_f32_16x16x32_bf16 v[0:3], v[174:177], v[214:217], v[0:3]
	v_mfma_f32_16x16x32_bf16 v[4:7], v[182:185], v[214:217], v[4:7]
	s_barrier
	s_setprio 0
	s_add_i32 s70, 0, 0x18000
	v_add_u32_e32 v137, s70, v155
	s_add_i32 s71, 0, 0x1c000
	ds_read_b128 v[146:149], v137
	ds_read_b128 v[150:153], v137 offset:1024
	ds_read_b128 v[162:165], v137 offset:2048
	ds_read_b128 v[166:169], v137 offset:3072
	v_add_u32_e32 v137, s71, v155
	ds_read_b128 v[170:173], v137
	ds_read_b128 v[174:177], v137 offset:1024
	ds_read_b128 v[178:181], v137 offset:2048
	ds_read_b128 v[182:185], v137 offset:3072
	s_add_u32 s50, s50, 0x80000
	s_addc_u32 s51, s51, 0
	s_mov_b32 m0, s53
	v_lshl_add_u64 v[226:227], s[50:51], 0, v[128:129]
	ds_read_b128 v[186:189], v159 offset:32768
	ds_read_b128 v[190:193], v159 offset:33792
	ds_read_b128 v[194:197], v159 offset:34816
	ds_read_b128 v[198:201], v159 offset:35840
	ds_read_b128 v[202:205], v159 offset:36864
	ds_read_b128 v[206:209], v159 offset:37888
	ds_read_b128 v[210:213], v159 offset:38912
	ds_read_b128 v[214:217], v159 offset:39936
	global_load_lds_dwordx4 v[226:227], off
	v_lshl_add_u64 v[226:227], s[50:51], 0, v[132:133]
	s_mov_b32 m0, s54
	s_nop 0
	global_load_lds_dwordx4 v[226:227], off
	s_waitcnt vmcnt(8)
	s_waitcnt lgkmcnt(0)
	s_setprio 1
	s_barrier
	v_mfma_f32_16x16x32_bf16 v[124:127], v[146:149], v[186:189], v[124:127]
	v_mfma_f32_16x16x32_bf16 v[120:123], v[162:165], v[186:189], v[120:123]
	v_mfma_f32_16x16x32_bf16 v[108:111], v[146:149], v[194:197], v[108:111]
	v_mfma_f32_16x16x32_bf16 v[104:107], v[162:165], v[194:197], v[104:107]
	v_mfma_f32_16x16x32_bf16 v[92:95], v[146:149], v[202:205], v[92:95]
	v_mfma_f32_16x16x32_bf16 v[88:91], v[162:165], v[202:205], v[88:91]
	v_mfma_f32_16x16x32_bf16 v[76:79], v[146:149], v[210:213], v[76:79]
	v_mfma_f32_16x16x32_bf16 v[72:75], v[162:165], v[210:213], v[72:75]
	v_mfma_f32_16x16x32_bf16 v[124:127], v[150:153], v[190:193], v[124:127]
	v_mfma_f32_16x16x32_bf16 v[120:123], v[166:169], v[190:193], v[120:123]
	v_mfma_f32_16x16x32_bf16 v[108:111], v[150:153], v[198:201], v[108:111]
	v_mfma_f32_16x16x32_bf16 v[104:107], v[166:169], v[198:201], v[104:107]
	v_mfma_f32_16x16x32_bf16 v[92:95], v[150:153], v[206:209], v[92:95]
	v_mfma_f32_16x16x32_bf16 v[88:91], v[166:169], v[206:209], v[88:91]
	v_mfma_f32_16x16x32_bf16 v[76:79], v[150:153], v[214:217], v[76:79]
	v_mfma_f32_16x16x32_bf16 v[72:75], v[166:169], v[214:217], v[72:75]
	s_setprio 0
	s_setprio 1
	v_mfma_f32_16x16x32_bf16 v[112:115], v[170:173], v[186:189], v[112:115]
	v_mfma_f32_16x16x32_bf16 v[116:119], v[178:181], v[186:189], v[116:119]
	v_mfma_f32_16x16x32_bf16 v[96:99], v[170:173], v[194:197], v[96:99]
	v_mfma_f32_16x16x32_bf16 v[100:103], v[178:181], v[194:197], v[100:103]
	v_mfma_f32_16x16x32_bf16 v[80:83], v[170:173], v[202:205], v[80:83]
	v_mfma_f32_16x16x32_bf16 v[84:87], v[178:181], v[202:205], v[84:87]
	v_mfma_f32_16x16x32_bf16 v[64:67], v[170:173], v[210:213], v[64:67]
	v_mfma_f32_16x16x32_bf16 v[68:71], v[178:181], v[210:213], v[68:71]
	v_mfma_f32_16x16x32_bf16 v[112:115], v[174:177], v[190:193], v[112:115]
	v_mfma_f32_16x16x32_bf16 v[116:119], v[182:185], v[190:193], v[116:119]
	v_mfma_f32_16x16x32_bf16 v[96:99], v[174:177], v[198:201], v[96:99]
	v_mfma_f32_16x16x32_bf16 v[100:103], v[182:185], v[198:201], v[100:103]
	v_mfma_f32_16x16x32_bf16 v[80:83], v[174:177], v[206:209], v[80:83]
	v_mfma_f32_16x16x32_bf16 v[84:87], v[182:185], v[206:209], v[84:87]
	v_mfma_f32_16x16x32_bf16 v[64:67], v[174:177], v[214:217], v[64:67]
	v_mfma_f32_16x16x32_bf16 v[68:71], v[182:185], v[214:217], v[68:71]
	s_barrier
; #define PG8_STAGE(bufoff, gbase, voff) do { _Pragma("unroll") for (int _i = 0; _i < 2; ++_i) \
;         __builtin_amdgcn_global_load_lds((const unsigned*)((const char*)(gbase) + (voff)[_i]), (PG8_LAS unsigned*)(lds + (bufoff) + ldsw + _i * 8192), 16, 0, 0); } while (0)
; #define PG8_LDA(dst, b, h) do { _Pragma("unroll") for (int m = 0; m < 4; ++m) _Pragma("unroll") for (int k = 0; k < 2; ++k) dst[m][k] = *(const PG8_LAS bf16x8*)(lds + PG8_SA(b, h) + aoff + m * 2048 + k * 1024); } while (0)
; #define PG8_MMA(ai, bj, At, Bt) do { __builtin_amdgcn_s_setprio(1); _Pragma("unroll") for (int m = 0; m < 4; ++m) _Pragma("unroll") for (int n = 0; n < 2; ++n) _Pragma("unroll") for (int k = 0; k < 2; ++k) \
;         acc[ai][bj][m][n] = __builtin_amdgcn_mfma_f32_16x16x32_bf16(Bt[n][k], At[m][k], acc[ai][bj][m][n], 0, 0, 0); __builtin_amdgcn_s_setprio(0); } while (0)
; #define PG8_WAIT_V(n) asm volatile("s_waitcnt vmcnt(" #n ")" ::: "memory")
; #define PG8_WAIT_L(n) asm volatile("s_waitcnt lgkmcnt(" #n ")" ::: "memory")
; #define PG8_BAR __builtin_amdgcn_s_barrier()
; #define PG8_SCHED __builtin_amdgcn_sched_barrier(0)
; template <class Epi, class Sched, bool ALIGN_EPI = false, bool SP2 = false>
; __device__ __forceinline__ void gemm_phase(PG8_LAS unsigned char* lds, const Gemm g, const Sched& S, const Epi& E, const int wid) {
;     ...
;             PG8_LDA(At, 1, 1); PG8_STAGE(PG8_SB(1, 0), b3, voffB); PG8_STAGE(PG8_SB(1, 1), b3 + hstep, voffB); PG8_STAGE(PG8_SA(1, 0), a3, voffA);
;             PG8_WAIT_V(8); PG8_WAIT_L(0); PG8_BAR; PG8_MMA(1, 0, At, B0); PG8_MMA(1, 1, At, B1); PG8_BAR; PG8_SCHED;
;     ...
;         if constexpr (ALIGN_EPI) { if (wr == 0) PG8_BAR; }
	s_setprio 0
	s_add_i32 s50, s70, s3
	v_lshl_add_u64 v[218:219], v[218:219], 0, s[26:27]
	s_mov_b32 m0, s50
	ds_read_b128 v[186:189], v159 offset:49152
	ds_read_b128 v[190:193], v159 offset:50176
	ds_read_b128 v[194:197], v159 offset:51200
	ds_read_b128 v[198:201], v159 offset:52224
	ds_read_b128 v[202:205], v159 offset:53248
	ds_read_b128 v[206:209], v159 offset:54272
	ds_read_b128 v[210:213], v159 offset:55296
	ds_read_b128 v[214:217], v159 offset:56320
	global_load_lds_dwordx4 v[218:219], off
	s_add_i32 m0, s50, 0x2000
	s_add_u32 s48, s48, 0x80080
	v_lshl_add_u64 v[218:219], v[220:221], 0, s[26:27]
	s_addc_u32 s49, s49, 0
	s_add_i32 s50, s71, s3
	global_load_lds_dwordx4 v[218:219], off
	v_lshl_add_u64 v[218:219], s[48:49], 0, v[130:131]
	s_mov_b32 m0, s50
	s_nop 0
	global_load_lds_dwordx4 v[218:219], off
	v_lshl_add_u64 v[218:219], s[48:49], 0, v[134:135]
	s_add_i32 m0, s50, 0x2000
	s_nop 0
	global_load_lds_dwordx4 v[218:219], off
	v_lshl_add_u64 v[218:219], v[222:223], 0, s[26:27]
	s_mov_b32 m0, s56
	s_nop 0
	global_load_lds_dwordx4 v[218:219], off
	v_lshl_add_u64 v[218:219], v[224:225], 0, s[26:27]
	s_mov_b32 m0, s57
	s_nop 0
	global_load_lds_dwordx4 v[218:219], off
	s_waitcnt vmcnt(8)
	s_waitcnt lgkmcnt(0)
	s_setprio 1
	s_barrier
	v_mfma_f32_16x16x32_bf16 v[60:63], v[146:149], v[186:189], v[60:63]
	v_mfma_f32_16x16x32_bf16 v[56:59], v[162:165], v[186:189], v[56:59]
	v_mfma_f32_16x16x32_bf16 v[44:47], v[146:149], v[194:197], v[44:47]
	v_mfma_f32_16x16x32_bf16 v[40:43], v[162:165], v[194:197], v[40:43]
	v_mfma_f32_16x16x32_bf16 v[28:31], v[146:149], v[202:205], v[28:31]
	v_mfma_f32_16x16x32_bf16 v[24:27], v[162:165], v[202:205], v[24:27]
	v_mfma_f32_16x16x32_bf16 v[12:15], v[146:149], v[210:213], v[12:15]
	v_mfma_f32_16x16x32_bf16 v[8:11], v[162:165], v[210:213], v[8:11]
	v_mfma_f32_16x16x32_bf16 v[60:63], v[150:153], v[190:193], v[60:63]
	v_mfma_f32_16x16x32_bf16 v[56:59], v[166:169], v[190:193], v[56:59]
	v_mfma_f32_16x16x32_bf16 v[44:47], v[150:153], v[198:201], v[44:47]
	v_mfma_f32_16x16x32_bf16 v[40:43], v[166:169], v[198:201], v[40:43]
	v_mfma_f32_16x16x32_bf16 v[28:31], v[150:153], v[206:209], v[28:31]
	v_mfma_f32_16x16x32_bf16 v[24:27], v[166:169], v[206:209], v[24:27]
	v_mfma_f32_16x16x32_bf16 v[12:15], v[150:153], v[214:217], v[12:15]
	v_mfma_f32_16x16x32_bf16 v[8:11], v[166:169], v[214:217], v[8:11]
	s_setprio 0
	s_setprio 1
	v_mfma_f32_16x16x32_bf16 v[48:51], v[170:173], v[186:189], v[48:51]
	v_mfma_f32_16x16x32_bf16 v[52:55], v[178:181], v[186:189], v[52:55]
	v_mfma_f32_16x16x32_bf16 v[32:35], v[170:173], v[194:197], v[32:35]
	v_mfma_f32_16x16x32_bf16 v[36:39], v[178:181], v[194:197], v[36:39]
	v_mfma_f32_16x16x32_bf16 v[16:19], v[170:173], v[202:205], v[16:19]
	v_mfma_f32_16x16x32_bf16 v[20:23], v[178:181], v[202:205], v[20:23]
	v_mfma_f32_16x16x32_bf16 v[0:3], v[170:173], v[210:213], v[0:3]
	v_mfma_f32_16x16x32_bf16 v[4:7], v[178:181], v[210:213], v[4:7]
	v_mfma_f32_16x16x32_bf16 v[48:51], v[174:177], v[190:193], v[48:51]
	v_mfma_f32_16x16x32_bf16 v[52:55], v[182:185], v[190:193], v[52:55]
	v_mfma_f32_16x16x32_bf16 v[32:35], v[174:177], v[198:201], v[32:35]
	v_mfma_f32_16x16x32_bf16 v[36:39], v[182:185], v[198:201], v[36:39]
	v_mfma_f32_16x16x32_bf16 v[16:19], v[174:177], v[206:209], v[16:19]
	v_mfma_f32_16x16x32_bf16 v[20:23], v[182:185], v[206:209], v[20:23]
	v_mfma_f32_16x16x32_bf16 v[0:3], v[174:177], v[214:217], v[0:3]
	v_mfma_f32_16x16x32_bf16 v[4:7], v[182:185], v[214:217], v[4:7]
	s_barrier
	s_setprio 0
	s_add_i32 s69, s69, 2
	s_add_u32 s12, s12, 0x100
	s_addc_u32 s13, s13, 0
	s_add_u32 s67, s67, 0x100
	s_addc_u32 s68, s68, 0
	s_cmp_gt_u32 s69, 29
	s_cbranch_scc0 .LBB0_335
	s_and_b64 vcc, exec, s[28:29]
	s_cbranch_vccz .LBB0_338
	s_barrier

; #define PG8_STAGE(bufoff, gbase, voff) do { _Pragma("unroll") for (int _i = 0; _i < 2; ++_i) \
;         __builtin_amdgcn_global_load_lds((const unsigned*)((const char*)(gbase) + (voff)[_i]), (PG8_LAS unsigned*)(lds + (bufoff) + ldsw + _i * 8192), 16, 0, 0); } while (0)
; #define PG8_LDA(dst, b, h) do { _Pragma("unroll") for (int m = 0; m < 4; ++m) _Pragma("unroll") for (int k = 0; k < 2; ++k) dst[m][k] = *(const PG8_LAS bf16x8*)(lds + PG8_SA(b, h) + aoff + m * 2048 + k * 1024); } while (0)
; #define PG8_LDB(dst, b, h) do { _Pragma("unroll") for (int n = 0; n < 2; ++n) _Pragma("unroll") for (int k = 0; k < 2; ++k) dst[n][k] = *(const PG8_LAS bf16x8*)(lds + PG8_SB(b, h) + boff + n * 2048 + k * 1024); } while (0)
; #define PG8_MMA(ai, bj, At, Bt) do { __builtin_amdgcn_s_setprio(1); _Pragma("unroll") for (int m = 0; m < 4; ++m) _Pragma("unroll") for (int n = 0; n < 2; ++n) _Pragma("unroll") for (int k = 0; k < 2; ++k) \
;         acc[ai][bj][m][n] = __builtin_amdgcn_mfma_f32_16x16x32_bf16(Bt[n][k], At[m][k], acc[ai][bj][m][n], 0, 0, 0); __builtin_amdgcn_s_setprio(0); } while (0)
; #define PG8_WAIT_V(n) asm volatile("s_waitcnt vmcnt(" #n ")" ::: "memory")
; #define PG8_WAIT_L(n) asm volatile("s_waitcnt lgkmcnt(" #n ")" ::: "memory")
; #define PG8_BAR __builtin_amdgcn_s_barrier()
; #define PG8_SCHED __builtin_amdgcn_sched_barrier(0)
; template <class Epi, class Sched, bool ALIGN_EPI = false, bool SP2 = false>
; __device__ __forceinline__ void gemm_phase(PG8_LAS unsigned char* lds, const Gemm g, const Sched& S, const Epi& E, const int wid) {
;     ...
;             PG8_LDB(B0, 0, 0); PG8_LDB(B1, 0, 1); PG8_SCHED; PG8_LDA(At, 0, 0); PG8_STAGE(PG8_SA(1, 1), a1 + hstep, voffA);
;             PG8_WAIT_V(8); PG8_WAIT_L(0); PG8_BAR; PG8_MMA(0, 0, At, B0); PG8_MMA(0, 1, At, B1); PG8_BAR; PG8_SCHED;
;             PG8_LDA(At, 0, 1); PG8_STAGE(PG8_SB(0, 0), b2, voffB); PG8_STAGE(PG8_SB(0, 1), b2 + hstep, voffB); PG8_STAGE(PG8_SA(0, 0), a2, voffA);
.LBB0_564:
	ds_read_b128 v[146:149], v201
	ds_read_b128 v[150:153], v201 offset:1024
	ds_read_b128 v[154:157], v201 offset:2048
	ds_read_b128 v[158:161], v201 offset:3072
	ds_read_b128 v[162:165], v202
	ds_read_b128 v[166:169], v202 offset:1024
	ds_read_b128 v[170:173], v202 offset:2048
	ds_read_b128 v[174:177], v202 offset:3072
	s_add_u32 s16, s14, 0xfff80080
	s_addc_u32 s17, s15, -1
	s_cmp_eq_u32 s55, 28
	s_cselect_b32 s19, s9, s17
	s_cselect_b32 s18, s13, s16
	s_cselect_b32 s17, s20, s25
	s_cselect_b32 s16, s21, s24
	v_lshl_add_u64 v[218:219], s[14:15], 0, v[138:139]
	s_add_i32 m0, s41, 0xc000
	ds_read_b128 v[178:181], v203
	ds_read_b128 v[182:185], v203 offset:1024
	ds_read_b128 v[186:189], v203 offset:2048
	ds_read_b128 v[190:193], v203 offset:3072
	ds_read_b128 v[194:197], v203 offset:4096
	ds_read_b128 v[206:209], v203 offset:5120
	ds_read_b128 v[210:213], v203 offset:6144
	ds_read_b128 v[214:217], v203 offset:7168
	global_load_lds_dwordx4 v[218:219], off
	v_lshl_add_u64 v[218:219], s[14:15], 0, v[140:141]
	s_add_i32 m0, s41, 0xe000
	s_nop 0
	global_load_lds_dwordx4 v[218:219], off
	s_waitcnt vmcnt(8)
	s_waitcnt lgkmcnt(0)
	s_setprio 1
	s_barrier
	v_mfma_f32_16x16x32_bf16 v[124:127], v[146:149], v[178:181], v[124:127]
	v_mfma_f32_16x16x32_bf16 v[120:123], v[154:157], v[178:181], v[120:123]
	v_mfma_f32_16x16x32_bf16 v[116:119], v[146:149], v[186:189], v[116:119]
	v_mfma_f32_16x16x32_bf16 v[112:115], v[154:157], v[186:189], v[112:115]
	v_mfma_f32_16x16x32_bf16 v[108:111], v[146:149], v[194:197], v[108:111]
	v_mfma_f32_16x16x32_bf16 v[104:107], v[154:157], v[194:197], v[104:107]
	v_mfma_f32_16x16x32_bf16 v[100:103], v[146:149], v[210:213], v[100:103]
	v_mfma_f32_16x16x32_bf16 v[96:99], v[154:157], v[210:213], v[96:99]
	v_mfma_f32_16x16x32_bf16 v[124:127], v[150:153], v[182:185], v[124:127]
	v_mfma_f32_16x16x32_bf16 v[120:123], v[158:161], v[182:185], v[120:123]
	v_mfma_f32_16x16x32_bf16 v[116:119], v[150:153], v[190:193], v[116:119]
	v_mfma_f32_16x16x32_bf16 v[112:115], v[158:161], v[190:193], v[112:115]
	v_mfma_f32_16x16x32_bf16 v[108:111], v[150:153], v[206:209], v[108:111]
	v_mfma_f32_16x16x32_bf16 v[104:107], v[158:161], v[206:209], v[104:107]
	v_mfma_f32_16x16x32_bf16 v[100:103], v[150:153], v[214:217], v[100:103]
	v_mfma_f32_16x16x32_bf16 v[96:99], v[158:161], v[214:217], v[96:99]
	s_setprio 0
	s_setprio 1
	v_mfma_f32_16x16x32_bf16 v[60:63], v[162:165], v[178:181], v[60:63]
	v_mfma_f32_16x16x32_bf16 v[56:59], v[170:173], v[178:181], v[56:59]
	v_mfma_f32_16x16x32_bf16 v[52:55], v[162:165], v[186:189], v[52:55]
	v_mfma_f32_16x16x32_bf16 v[48:51], v[170:173], v[186:189], v[48:51]
	v_mfma_f32_16x16x32_bf16 v[44:47], v[162:165], v[194:197], v[44:47]
	v_mfma_f32_16x16x32_bf16 v[40:43], v[170:173], v[194:197], v[40:43]
	v_mfma_f32_16x16x32_bf16 v[36:39], v[162:165], v[210:213], v[36:39]
	v_mfma_f32_16x16x32_bf16 v[32:35], v[170:173], v[210:213], v[32:35]
	v_mfma_f32_16x16x32_bf16 v[60:63], v[166:169], v[182:185], v[60:63]
	v_mfma_f32_16x16x32_bf16 v[56:59], v[174:177], v[182:185], v[56:59]
	v_mfma_f32_16x16x32_bf16 v[52:55], v[166:169], v[190:193], v[52:55]
	v_mfma_f32_16x16x32_bf16 v[48:51], v[174:177], v[190:193], v[48:51]
	v_mfma_f32_16x16x32_bf16 v[44:47], v[166:169], v[206:209], v[44:47]
	v_mfma_f32_16x16x32_bf16 v[40:43], v[174:177], v[206:209], v[40:43]
	v_mfma_f32_16x16x32_bf16 v[36:39], v[166:169], v[214:217], v[36:39]
	v_mfma_f32_16x16x32_bf16 v[32:35], v[174:177], v[214:217], v[32:35]
	s_barrier
	s_setprio 0
	s_add_i32 s57, s68, s3
	v_lshl_add_u64 v[218:219], s[16:17], 0, v[130:131]
	s_mov_b32 m0, s57
	ds_read_b128 v[178:181], v203 offset:16384
	ds_read_b128 v[182:185], v203 offset:17408
	ds_read_b128 v[186:189], v203 offset:18432
	ds_read_b128 v[190:193], v203 offset:19456
	ds_read_b128 v[194:197], v203 offset:20480
	ds_read_b128 v[206:209], v203 offset:21504
	ds_read_b128 v[210:213], v203 offset:22528
	ds_read_b128 v[214:217], v203 offset:23552
	global_load_lds_dwordx4 v[218:219], off
	s_add_i32 m0, s57, 0x2000
	s_add_u32 s90, s16, 0x80000
	v_lshl_add_u64 v[220:221], s[16:17], 0, v[134:135]
	s_addc_u32 s91, s17, 0
	s_add_i32 s57, s69, s3
	global_load_lds_dwordx4 v[220:221], off
	v_lshl_add_u64 v[222:223], s[90:91], 0, v[130:131]
	s_mov_b32 m0, s57
	v_lshl_add_u64 v[224:225], s[18:19], 0, v[132:133]
	global_load_lds_dwordx4 v[222:223], off
	v_lshl_add_u64 v[222:223], s[90:91], 0, v[134:135]
	s_add_i32 m0, s57, 0x2000
	s_nop 0
	global_load_lds_dwordx4 v[222:223], off
	v_lshl_add_u64 v[222:223], s[18:19], 0, v[128:129]
	s_mov_b32 m0, s41
	s_nop 0
	global_load_lds_dwordx4 v[222:223], off
	s_mov_b32 m0, s44
	s_nop 0
	global_load_lds_dwordx4 v[224:225], off
	s_waitcnt vmcnt(8)
	s_waitcnt lgkmcnt(0)
	s_setprio 1
	s_barrier
; #define PG8_STAGE(bufoff, gbase, voff) do { _Pragma("unroll") for (int _i = 0; _i < 2; ++_i) \
;         __builtin_amdgcn_global_load_lds((const unsigned*)((const char*)(gbase) + (voff)[_i]), (PG8_LAS unsigned*)(lds + (bufoff) + ldsw + _i * 8192), 16, 0, 0); } while (0)
; #define PG8_LDA(dst, b, h) do { _Pragma("unroll") for (int m = 0; m < 4; ++m) _Pragma("unroll") for (int k = 0; k < 2; ++k) dst[m][k] = *(const PG8_LAS bf16x8*)(lds + PG8_SA(b, h) + aoff + m * 2048 + k * 1024); } while (0)
; #define PG8_LDB(dst, b, h) do { _Pragma("unroll") for (int n = 0; n < 2; ++n) _Pragma("unroll") for (int k = 0; k < 2; ++k) dst[n][k] = *(const PG8_LAS bf16x8*)(lds + PG8_SB(b, h) + boff + n * 2048 + k * 1024); } while (0)
; #define PG8_MMA(ai, bj, At, Bt) do { __builtin_amdgcn_s_setprio(1); _Pragma("unroll") for (int m = 0; m < 4; ++m) _Pragma("unroll") for (int n = 0; n < 2; ++n) _Pragma("unroll") for (int k = 0; k < 2; ++k) \
;         acc[ai][bj][m][n] = __builtin_amdgcn_mfma_f32_16x16x32_bf16(Bt[n][k], At[m][k], acc[ai][bj][m][n], 0, 0, 0); __builtin_amdgcn_s_setprio(0); } while (0)
; #define PG8_WAIT_V(n) asm volatile("s_waitcnt vmcnt(" #n ")" ::: "memory")
; #define PG8_WAIT_L(n) asm volatile("s_waitcnt lgkmcnt(" #n ")" ::: "memory")
; #define PG8_BAR __builtin_amdgcn_s_barrier()
; #define PG8_SCHED __builtin_amdgcn_sched_barrier(0)
; template <class Epi, class Sched, bool ALIGN_EPI = false, bool SP2 = false>
; __device__ __forceinline__ void gemm_phase(PG8_LAS unsigned char* lds, const Gemm g, const Sched& S, const Epi& E, const int wid) {
;     ...
;             PG8_WAIT_V(8); PG8_WAIT_L(0); PG8_BAR; PG8_MMA(1, 0, At, B0); PG8_MMA(1, 1, At, B1); PG8_BAR; PG8_SCHED;
;             PG8_LDB(B0, 1, 0); PG8_LDB(B1, 1, 1); PG8_SCHED; PG8_LDA(At, 1, 0); PG8_STAGE(PG8_SA(0, 1), a2 + hstep, voffA);
;             PG8_WAIT_V(8); PG8_WAIT_L(0); PG8_BAR; PG8_MMA(0, 0, At, B0); PG8_MMA(0, 1, At, B1); PG8_BAR; PG8_SCHED;
	v_mfma_f32_16x16x32_bf16 v[92:95], v[146:149], v[178:181], v[92:95]
	v_mfma_f32_16x16x32_bf16 v[88:91], v[154:157], v[178:181], v[88:91]
	v_mfma_f32_16x16x32_bf16 v[84:87], v[146:149], v[186:189], v[84:87]
	v_mfma_f32_16x16x32_bf16 v[80:83], v[154:157], v[186:189], v[80:83]
	v_mfma_f32_16x16x32_bf16 v[76:79], v[146:149], v[194:197], v[76:79]
	v_mfma_f32_16x16x32_bf16 v[72:75], v[154:157], v[194:197], v[72:75]
	v_mfma_f32_16x16x32_bf16 v[68:71], v[146:149], v[210:213], v[68:71]
	v_mfma_f32_16x16x32_bf16 v[64:67], v[154:157], v[210:213], v[64:67]
	v_mfma_f32_16x16x32_bf16 v[92:95], v[150:153], v[182:185], v[92:95]
	v_mfma_f32_16x16x32_bf16 v[88:91], v[158:161], v[182:185], v[88:91]
	v_mfma_f32_16x16x32_bf16 v[84:87], v[150:153], v[190:193], v[84:87]
	v_mfma_f32_16x16x32_bf16 v[80:83], v[158:161], v[190:193], v[80:83]
	v_mfma_f32_16x16x32_bf16 v[76:79], v[150:153], v[206:209], v[76:79]
	v_mfma_f32_16x16x32_bf16 v[72:75], v[158:161], v[206:209], v[72:75]
	v_mfma_f32_16x16x32_bf16 v[68:71], v[150:153], v[214:217], v[68:71]
	v_mfma_f32_16x16x32_bf16 v[64:67], v[158:161], v[214:217], v[64:67]
	s_setprio 0
	s_setprio 1
	v_mfma_f32_16x16x32_bf16 v[28:31], v[162:165], v[178:181], v[28:31]
	v_mfma_f32_16x16x32_bf16 v[24:27], v[170:173], v[178:181], v[24:27]
	v_mfma_f32_16x16x32_bf16 v[20:23], v[162:165], v[186:189], v[20:23]
	v_mfma_f32_16x16x32_bf16 v[16:19], v[170:173], v[186:189], v[16:19]
	v_mfma_f32_16x16x32_bf16 v[12:15], v[162:165], v[194:197], v[12:15]
	v_mfma_f32_16x16x32_bf16 v[8:11], v[170:173], v[194:197], v[8:11]
	v_mfma_f32_16x16x32_bf16 v[4:7], v[162:165], v[210:213], v[4:7]
	v_mfma_f32_16x16x32_bf16 v[0:3], v[170:173], v[210:213], v[0:3]
	v_mfma_f32_16x16x32_bf16 v[28:31], v[166:169], v[182:185], v[28:31]
	v_mfma_f32_16x16x32_bf16 v[24:27], v[174:177], v[182:185], v[24:27]
	v_mfma_f32_16x16x32_bf16 v[20:23], v[166:169], v[190:193], v[20:23]
	v_mfma_f32_16x16x32_bf16 v[16:19], v[174:177], v[190:193], v[16:19]
	v_mfma_f32_16x16x32_bf16 v[12:15], v[166:169], v[206:209], v[12:15]
	v_mfma_f32_16x16x32_bf16 v[8:11], v[174:177], v[206:209], v[8:11]
	v_mfma_f32_16x16x32_bf16 v[4:7], v[166:169], v[214:217], v[4:7]
	v_mfma_f32_16x16x32_bf16 v[0:3], v[174:177], v[214:217], v[0:3]
	s_barrier
	s_setprio 0
	s_add_i32 s57, 0, 0x18000
	v_add_u32_e32 v136, s57, v199
	s_add_i32 s90, 0, 0x1c000
	ds_read_b128 v[146:149], v136
	ds_read_b128 v[150:153], v136 offset:1024
	ds_read_b128 v[154:157], v136 offset:2048
	ds_read_b128 v[158:161], v136 offset:3072
	v_add_u32_e32 v136, s90, v199
	ds_read_b128 v[162:165], v136
	ds_read_b128 v[166:169], v136 offset:1024
	ds_read_b128 v[170:173], v136 offset:2048
	ds_read_b128 v[174:177], v136 offset:3072
	s_add_u32 s18, s18, 0x80000
	s_addc_u32 s19, s19, 0
	s_mov_b32 m0, s45
	v_lshl_add_u64 v[226:227], s[18:19], 0, v[128:129]
	ds_read_b128 v[178:181], v203 offset:32768
	ds_read_b128 v[182:185], v203 offset:33792
	ds_read_b128 v[186:189], v203 offset:34816
	ds_read_b128 v[190:193], v203 offset:35840
	ds_read_b128 v[194:197], v203 offset:36864
	ds_read_b128 v[206:209], v203 offset:37888
	ds_read_b128 v[210:213], v203 offset:38912
	ds_read_b128 v[214:217], v203 offset:39936
	global_load_lds_dwordx4 v[226:227], off
	v_lshl_add_u64 v[226:227], s[18:19], 0, v[132:133]
	s_mov_b32 m0, s53
	s_nop 0
	global_load_lds_dwordx4 v[226:227], off
	s_waitcnt vmcnt(8)
	s_waitcnt lgkmcnt(0)
	s_setprio 1
	s_barrier
	v_mfma_f32_16x16x32_bf16 v[124:127], v[146:149], v[178:181], v[124:127]
	v_mfma_f32_16x16x32_bf16 v[120:123], v[154:157], v[178:181], v[120:123]
	v_mfma_f32_16x16x32_bf16 v[116:119], v[146:149], v[186:189], v[116:119]
	v_mfma_f32_16x16x32_bf16 v[112:115], v[154:157], v[186:189], v[112:115]
	v_mfma_f32_16x16x32_bf16 v[108:111], v[146:149], v[194:197], v[108:111]
	v_mfma_f32_16x16x32_bf16 v[104:107], v[154:157], v[194:197], v[104:107]
	v_mfma_f32_16x16x32_bf16 v[100:103], v[146:149], v[210:213], v[100:103]
	v_mfma_f32_16x16x32_bf16 v[96:99], v[154:157], v[210:213], v[96:99]
	v_mfma_f32_16x16x32_bf16 v[124:127], v[150:153], v[182:185], v[124:127]
	v_mfma_f32_16x16x32_bf16 v[120:123], v[158:161], v[182:185], v[120:123]
	v_mfma_f32_16x16x32_bf16 v[116:119], v[150:153], v[190:193], v[116:119]
	v_mfma_f32_16x16x32_bf16 v[112:115], v[158:161], v[190:193], v[112:115]
	v_mfma_f32_16x16x32_bf16 v[108:111], v[150:153], v[206:209], v[108:111]
	v_mfma_f32_16x16x32_bf16 v[104:107], v[158:161], v[206:209], v[104:107]
	v_mfma_f32_16x16x32_bf16 v[100:103], v[150:153], v[214:217], v[100:103]
	v_mfma_f32_16x16x32_bf16 v[96:99], v[158:161], v[214:217], v[96:99]
	s_setprio 0
	s_setprio 1
	v_mfma_f32_16x16x32_bf16 v[60:63], v[162:165], v[178:181], v[60:63]
	v_mfma_f32_16x16x32_bf16 v[56:59], v[170:173], v[178:181], v[56:59]
	v_mfma_f32_16x16x32_bf16 v[52:55], v[162:165], v[186:189], v[52:55]
	v_mfma_f32_16x16x32_bf16 v[48:51], v[170:173], v[186:189], v[48:51]
	v_mfma_f32_16x16x32_bf16 v[44:47], v[162:165], v[194:197], v[44:47]
	v_mfma_f32_16x16x32_bf16 v[40:43], v[170:173], v[194:197], v[40:43]
	v_mfma_f32_16x16x32_bf16 v[36:39], v[162:165], v[210:213], v[36:39]
	v_mfma_f32_16x16x32_bf16 v[32:35], v[170:173], v[210:213], v[32:35]
	v_mfma_f32_16x16x32_bf16 v[60:63], v[166:169], v[182:185], v[60:63]
	v_mfma_f32_16x16x32_bf16 v[56:59], v[174:177], v[182:185], v[56:59]
	v_mfma_f32_16x16x32_bf16 v[52:55], v[166:169], v[190:193], v[52:55]
	v_mfma_f32_16x16x32_bf16 v[48:51], v[174:177], v[190:193], v[48:51]
	v_mfma_f32_16x16x32_bf16 v[44:47], v[166:169], v[206:209], v[44:47]
	v_mfma_f32_16x16x32_bf16 v[40:43], v[174:177], v[206:209], v[40:43]
	v_mfma_f32_16x16x32_bf16 v[36:39], v[166:169], v[214:217], v[36:39]
	v_mfma_f32_16x16x32_bf16 v[32:35], v[174:177], v[214:217], v[32:35]
	s_barrier
; #define PG8_STAGE(bufoff, gbase, voff) do { _Pragma("unroll") for (int _i = 0; _i < 2; ++_i) \
;         __builtin_amdgcn_global_load_lds((const unsigned*)((const char*)(gbase) + (voff)[_i]), (PG8_LAS unsigned*)(lds + (bufoff) + ldsw + _i * 8192), 16, 0, 0); } while (0)
; #define PG8_LDA(dst, b, h) do { _Pragma("unroll") for (int m = 0; m < 4; ++m) _Pragma("unroll") for (int k = 0; k < 2; ++k) dst[m][k] = *(const PG8_LAS bf16x8*)(lds + PG8_SA(b, h) + aoff + m * 2048 + k * 1024); } while (0)
; #define PG8_MMA(ai, bj, At, Bt) do { __builtin_amdgcn_s_setprio(1); _Pragma("unroll") for (int m = 0; m < 4; ++m) _Pragma("unroll") for (int n = 0; n < 2; ++n) _Pragma("unroll") for (int k = 0; k < 2; ++k) \
;         acc[ai][bj][m][n] = __builtin_amdgcn_mfma_f32_16x16x32_bf16(Bt[n][k], At[m][k], acc[ai][bj][m][n], 0, 0, 0); __builtin_amdgcn_s_setprio(0); } while (0)
; #define PG8_WAIT_V(n) asm volatile("s_waitcnt vmcnt(" #n ")" ::: "memory")
; #define PG8_WAIT_L(n) asm volatile("s_waitcnt lgkmcnt(" #n ")" ::: "memory")
; #define PG8_BAR __builtin_amdgcn_s_barrier()
; #define PG8_SCHED __builtin_amdgcn_sched_barrier(0)
; template <class Epi, class Sched, bool ALIGN_EPI = false, bool SP2 = false>
; __device__ __forceinline__ void gemm_phase(PG8_LAS unsigned char* lds, const Gemm g, const Sched& S, const Epi& E, const int wid) {
;     ...
;             PG8_LDA(At, 1, 1); PG8_STAGE(PG8_SB(1, 0), b3, voffB); PG8_STAGE(PG8_SB(1, 1), b3 + hstep, voffB); PG8_STAGE(PG8_SA(1, 0), a3, voffA);
;             PG8_WAIT_V(8); PG8_WAIT_L(0); PG8_BAR; PG8_MMA(1, 0, At, B0); PG8_MMA(1, 1, At, B1); PG8_BAR; PG8_SCHED;
;     ...
;         if constexpr (ALIGN_EPI) { if (wr == 0) PG8_BAR; }
	s_setprio 0
	s_add_i32 s18, s57, s3
	v_lshl_add_u64 v[218:219], v[218:219], 0, s[48:49]
	s_mov_b32 m0, s18
	ds_read_b128 v[178:181], v203 offset:49152
	ds_read_b128 v[182:185], v203 offset:50176
	ds_read_b128 v[186:189], v203 offset:51200
	ds_read_b128 v[190:193], v203 offset:52224
	ds_read_b128 v[194:197], v203 offset:53248
	ds_read_b128 v[206:209], v203 offset:54272
	ds_read_b128 v[210:213], v203 offset:55296
	ds_read_b128 v[214:217], v203 offset:56320
	global_load_lds_dwordx4 v[218:219], off
	s_add_i32 m0, s18, 0x2000
	s_add_u32 s16, s16, 0x80080
	v_lshl_add_u64 v[218:219], v[220:221], 0, s[48:49]
	s_addc_u32 s17, s17, 0
	s_add_i32 s18, s90, s3
	global_load_lds_dwordx4 v[218:219], off
	v_lshl_add_u64 v[218:219], s[16:17], 0, v[130:131]
	s_mov_b32 m0, s18
	s_nop 0
	global_load_lds_dwordx4 v[218:219], off
	v_lshl_add_u64 v[218:219], s[16:17], 0, v[134:135]
	s_add_i32 m0, s18, 0x2000
	s_nop 0
	global_load_lds_dwordx4 v[218:219], off
	v_lshl_add_u64 v[218:219], v[222:223], 0, s[48:49]
	s_mov_b32 m0, s63
	s_nop 0
	global_load_lds_dwordx4 v[218:219], off
	v_lshl_add_u64 v[218:219], v[224:225], 0, s[48:49]
	s_mov_b32 m0, s64
	s_nop 0
	global_load_lds_dwordx4 v[218:219], off
	s_waitcnt vmcnt(8)
	s_waitcnt lgkmcnt(0)
	s_setprio 1
	s_barrier
	v_mfma_f32_16x16x32_bf16 v[92:95], v[146:149], v[178:181], v[92:95]
	v_mfma_f32_16x16x32_bf16 v[88:91], v[154:157], v[178:181], v[88:91]
	v_mfma_f32_16x16x32_bf16 v[84:87], v[146:149], v[186:189], v[84:87]
	v_mfma_f32_16x16x32_bf16 v[80:83], v[154:157], v[186:189], v[80:83]
	v_mfma_f32_16x16x32_bf16 v[76:79], v[146:149], v[194:197], v[76:79]
	v_mfma_f32_16x16x32_bf16 v[72:75], v[154:157], v[194:197], v[72:75]
	v_mfma_f32_16x16x32_bf16 v[68:71], v[146:149], v[210:213], v[68:71]
	v_mfma_f32_16x16x32_bf16 v[64:67], v[154:157], v[210:213], v[64:67]
	v_mfma_f32_16x16x32_bf16 v[92:95], v[150:153], v[182:185], v[92:95]
	v_mfma_f32_16x16x32_bf16 v[88:91], v[158:161], v[182:185], v[88:91]
	v_mfma_f32_16x16x32_bf16 v[84:87], v[150:153], v[190:193], v[84:87]
	v_mfma_f32_16x16x32_bf16 v[80:83], v[158:161], v[190:193], v[80:83]
	v_mfma_f32_16x16x32_bf16 v[76:79], v[150:153], v[206:209], v[76:79]
	v_mfma_f32_16x16x32_bf16 v[72:75], v[158:161], v[206:209], v[72:75]
	v_mfma_f32_16x16x32_bf16 v[68:71], v[150:153], v[214:217], v[68:71]
	v_mfma_f32_16x16x32_bf16 v[64:67], v[158:161], v[214:217], v[64:67]
	s_setprio 0
	s_setprio 1
	v_mfma_f32_16x16x32_bf16 v[28:31], v[162:165], v[178:181], v[28:31]
	v_mfma_f32_16x16x32_bf16 v[24:27], v[170:173], v[178:181], v[24:27]
	v_mfma_f32_16x16x32_bf16 v[20:23], v[162:165], v[186:189], v[20:23]
	v_mfma_f32_16x16x32_bf16 v[16:19], v[170:173], v[186:189], v[16:19]
	v_mfma_f32_16x16x32_bf16 v[12:15], v[162:165], v[194:197], v[12:15]
	v_mfma_f32_16x16x32_bf16 v[8:11], v[170:173], v[194:197], v[8:11]
	v_mfma_f32_16x16x32_bf16 v[4:7], v[162:165], v[210:213], v[4:7]
	v_mfma_f32_16x16x32_bf16 v[0:3], v[170:173], v[210:213], v[0:3]
	v_mfma_f32_16x16x32_bf16 v[28:31], v[166:169], v[182:185], v[28:31]
	v_mfma_f32_16x16x32_bf16 v[24:27], v[174:177], v[182:185], v[24:27]
	v_mfma_f32_16x16x32_bf16 v[20:23], v[166:169], v[190:193], v[20:23]
	v_mfma_f32_16x16x32_bf16 v[16:19], v[174:177], v[190:193], v[16:19]
	v_mfma_f32_16x16x32_bf16 v[12:15], v[166:169], v[206:209], v[12:15]
	v_mfma_f32_16x16x32_bf16 v[8:11], v[174:177], v[206:209], v[8:11]
	v_mfma_f32_16x16x32_bf16 v[4:7], v[166:169], v[214:217], v[4:7]
	v_mfma_f32_16x16x32_bf16 v[0:3], v[174:177], v[214:217], v[0:3]
	s_barrier
	s_setprio 0
	s_add_i32 s55, s55, 2
	s_add_u32 s14, s14, 0x100
	s_addc_u32 s15, s15, 0
	s_add_u32 s24, s24, 0x100
	s_addc_u32 s25, s25, 0
	s_cmp_gt_u32 s55, 29
	s_cbranch_scc0 .LBB0_564
	s_and_b64 vcc, exec, s[50:51]
	s_cbranch_vccz .LBB0_567
	s_barrier

; #define PG8_STAGE(bufoff, gbase, voff) do { _Pragma("unroll") for (int _i = 0; _i < 2; ++_i) \
;         __builtin_amdgcn_global_load_lds((const unsigned*)((const char*)(gbase) + (voff)[_i]), (PG8_LAS unsigned*)(lds + (bufoff) + ldsw + _i * 8192), 16, 0, 0); } while (0)
; #define PG8_LDA(dst, b, h) do { _Pragma("unroll") for (int m = 0; m < 4; ++m) _Pragma("unroll") for (int k = 0; k < 2; ++k) dst[m][k] = *(const PG8_LAS bf16x8*)(lds + PG8_SA(b, h) + aoff + m * 2048 + k * 1024); } while (0)
; #define PG8_LDB(dst, b, h) do { _Pragma("unroll") for (int n = 0; n < 2; ++n) _Pragma("unroll") for (int k = 0; k < 2; ++k) dst[n][k] = *(const PG8_LAS bf16x8*)(lds + PG8_SB(b, h) + boff + n * 2048 + k * 1024); } while (0)
; #define PG8_MMA(ai, bj, At, Bt) do { __builtin_amdgcn_s_setprio(1); _Pragma("unroll") for (int m = 0; m < 4; ++m) _Pragma("unroll") for (int n = 0; n < 2; ++n) _Pragma("unroll") for (int k = 0; k < 2; ++k) \
;         acc[ai][bj][m][n] = __builtin_amdgcn_mfma_f32_16x16x32_bf16(Bt[n][k], At[m][k], acc[ai][bj][m][n], 0, 0, 0); __builtin_amdgcn_s_setprio(0); } while (0)
; #define PG8_WAIT_V(n) asm volatile("s_waitcnt vmcnt(" #n ")" ::: "memory")
; #define PG8_WAIT_L(n) asm volatile("s_waitcnt lgkmcnt(" #n ")" ::: "memory")
; #define PG8_BAR __builtin_amdgcn_s_barrier()
; #define PG8_SCHED __builtin_amdgcn_sched_barrier(0)
; template <class Epi, class Sched, bool ALIGN_EPI = false, bool SP2 = false>
; __device__ __forceinline__ void gemm_phase(PG8_LAS unsigned char* lds, const Gemm g, const Sched& S, const Epi& E, const int wid) {
;     ...
;             PG8_LDB(B0, 0, 0); PG8_LDB(B1, 0, 1); PG8_SCHED; PG8_LDA(At, 0, 0); PG8_STAGE(PG8_SA(1, 1), a1 + hstep, voffA);
;             PG8_WAIT_V(8); PG8_WAIT_L(0); PG8_BAR; PG8_MMA(0, 0, At, B0); PG8_MMA(0, 1, At, B1); PG8_BAR; PG8_SCHED;
;             PG8_LDA(At, 0, 1); PG8_STAGE(PG8_SB(0, 0), b2, voffB); PG8_STAGE(PG8_SB(0, 1), b2 + hstep, voffB); PG8_STAGE(PG8_SA(0, 0), a2, voffA);
.LBB0_682:
	ds_read_b128 v[128:131], v167
	ds_read_b128 v[132:135], v167 offset:1024
	ds_read_b128 v[136:139], v167 offset:2048
	ds_read_b128 v[140:143], v167 offset:3072
	ds_read_b128 v[174:177], v169
	ds_read_b128 v[178:181], v169 offset:1024
	ds_read_b128 v[182:185], v169 offset:2048
	ds_read_b128 v[186:189], v169 offset:3072
	s_add_u32 s54, s14, 0xfff80080
	s_addc_u32 s55, s15, -1
	s_cmp_eq_u32 s73, 28
	s_cselect_b32 s57, s13, s55
	s_cselect_b32 s56, s49, s54
	s_cselect_b32 s55, s31, s72
	s_cselect_b32 s54, s70, s71
	v_lshl_add_u64 v[222:223], s[14:15], 0, v[154:155]
	s_add_i32 m0, s44, 0xc000
	ds_read_b128 v[190:193], v171
	ds_read_b128 v[194:197], v171 offset:1024
	ds_read_b128 v[198:201], v171 offset:2048
	ds_read_b128 v[202:205], v171 offset:3072
	ds_read_b128 v[206:209], v171 offset:4096
	ds_read_b128 v[210:213], v171 offset:5120
	ds_read_b128 v[214:217], v171 offset:6144
	ds_read_b128 v[218:221], v171 offset:7168
	global_load_lds_dwordx4 v[222:223], off
	v_lshl_add_u64 v[222:223], s[14:15], 0, v[152:153]
	s_add_i32 m0, s44, 0xe000
	s_nop 0
	global_load_lds_dwordx4 v[222:223], off
	s_waitcnt vmcnt(8)
	s_waitcnt lgkmcnt(0)
	s_setprio 1
	s_barrier
	v_mfma_f32_16x16x32_bf16 v[124:127], v[128:131], v[190:193], v[124:127]
	v_mfma_f32_16x16x32_bf16 v[120:123], v[136:139], v[190:193], v[120:123]
	v_mfma_f32_16x16x32_bf16 v[116:119], v[128:131], v[198:201], v[116:119]
	v_mfma_f32_16x16x32_bf16 v[112:115], v[136:139], v[198:201], v[112:115]
	v_mfma_f32_16x16x32_bf16 v[108:111], v[128:131], v[206:209], v[108:111]
	v_mfma_f32_16x16x32_bf16 v[104:107], v[136:139], v[206:209], v[104:107]
	v_mfma_f32_16x16x32_bf16 v[100:103], v[128:131], v[214:217], v[100:103]
	v_mfma_f32_16x16x32_bf16 v[96:99], v[136:139], v[214:217], v[96:99]
	v_mfma_f32_16x16x32_bf16 v[124:127], v[132:135], v[194:197], v[124:127]
	v_mfma_f32_16x16x32_bf16 v[120:123], v[140:143], v[194:197], v[120:123]
	v_mfma_f32_16x16x32_bf16 v[116:119], v[132:135], v[202:205], v[116:119]
	v_mfma_f32_16x16x32_bf16 v[112:115], v[140:143], v[202:205], v[112:115]
	v_mfma_f32_16x16x32_bf16 v[108:111], v[132:135], v[210:213], v[108:111]
	v_mfma_f32_16x16x32_bf16 v[104:107], v[140:143], v[210:213], v[104:107]
	v_mfma_f32_16x16x32_bf16 v[100:103], v[132:135], v[218:221], v[100:103]
	v_mfma_f32_16x16x32_bf16 v[96:99], v[140:143], v[218:221], v[96:99]
	s_setprio 0
	s_setprio 1
	v_mfma_f32_16x16x32_bf16 v[68:71], v[174:177], v[190:193], v[68:71]
	v_mfma_f32_16x16x32_bf16 v[60:63], v[182:185], v[190:193], v[60:63]
	v_mfma_f32_16x16x32_bf16 v[52:55], v[174:177], v[198:201], v[52:55]
	v_mfma_f32_16x16x32_bf16 v[48:51], v[182:185], v[198:201], v[48:51]
	v_mfma_f32_16x16x32_bf16 v[44:47], v[174:177], v[206:209], v[44:47]
	v_mfma_f32_16x16x32_bf16 v[40:43], v[182:185], v[206:209], v[40:43]
	v_mfma_f32_16x16x32_bf16 v[36:39], v[174:177], v[214:217], v[36:39]
	v_mfma_f32_16x16x32_bf16 v[32:35], v[182:185], v[214:217], v[32:35]
	v_mfma_f32_16x16x32_bf16 v[68:71], v[178:181], v[194:197], v[68:71]
	v_mfma_f32_16x16x32_bf16 v[60:63], v[186:189], v[194:197], v[60:63]
	v_mfma_f32_16x16x32_bf16 v[52:55], v[178:181], v[202:205], v[52:55]
	v_mfma_f32_16x16x32_bf16 v[48:51], v[186:189], v[202:205], v[48:51]
	v_mfma_f32_16x16x32_bf16 v[44:47], v[178:181], v[210:213], v[44:47]
	v_mfma_f32_16x16x32_bf16 v[40:43], v[186:189], v[210:213], v[40:43]
	v_mfma_f32_16x16x32_bf16 v[36:39], v[178:181], v[218:221], v[36:39]
	v_mfma_f32_16x16x32_bf16 v[32:35], v[186:189], v[218:221], v[32:35]
	s_barrier
	s_setprio 0
	s_add_i32 s74, s64, s3
	v_lshl_add_u64 v[222:223], s[54:55], 0, v[148:149]
	s_mov_b32 m0, s74
	ds_read_b128 v[190:193], v171 offset:16384
	ds_read_b128 v[194:197], v171 offset:17408
	ds_read_b128 v[198:201], v171 offset:18432
	ds_read_b128 v[202:205], v171 offset:19456
	ds_read_b128 v[206:209], v171 offset:20480
	ds_read_b128 v[210:213], v171 offset:21504
	ds_read_b128 v[214:217], v171 offset:22528
	ds_read_b128 v[218:221], v171 offset:23552
	global_load_lds_dwordx4 v[222:223], off
	s_add_i32 m0, s74, 0x2000
	s_add_u32 s74, s54, 0x80000
	v_lshl_add_u64 v[224:225], s[54:55], 0, v[144:145]
	s_addc_u32 s75, s55, 0
	s_add_i32 s76, s65, s3
	global_load_lds_dwordx4 v[224:225], off
	v_lshl_add_u64 v[226:227], s[74:75], 0, v[148:149]
	s_mov_b32 m0, s76
	v_lshl_add_u64 v[228:229], s[56:57], 0, v[146:147]
	global_load_lds_dwordx4 v[226:227], off
	v_lshl_add_u64 v[226:227], s[74:75], 0, v[144:145]
	s_add_i32 m0, s76, 0x2000
	s_nop 0
	global_load_lds_dwordx4 v[226:227], off
	v_lshl_add_u64 v[226:227], s[56:57], 0, v[150:151]
	s_mov_b32 m0, s44
	s_nop 0
	global_load_lds_dwordx4 v[226:227], off
	s_mov_b32 m0, s45
	s_nop 0
	global_load_lds_dwordx4 v[228:229], off
	s_waitcnt vmcnt(8)
	s_waitcnt lgkmcnt(0)
	s_setprio 1
	s_barrier
; #define PG8_STAGE(bufoff, gbase, voff) do { _Pragma("unroll") for (int _i = 0; _i < 2; ++_i) \
;         __builtin_amdgcn_global_load_lds((const unsigned*)((const char*)(gbase) + (voff)[_i]), (PG8_LAS unsigned*)(lds + (bufoff) + ldsw + _i * 8192), 16, 0, 0); } while (0)
; #define PG8_LDA(dst, b, h) do { _Pragma("unroll") for (int m = 0; m < 4; ++m) _Pragma("unroll") for (int k = 0; k < 2; ++k) dst[m][k] = *(const PG8_LAS bf16x8*)(lds + PG8_SA(b, h) + aoff + m * 2048 + k * 1024); } while (0)
; #define PG8_LDB(dst, b, h) do { _Pragma("unroll") for (int n = 0; n < 2; ++n) _Pragma("unroll") for (int k = 0; k < 2; ++k) dst[n][k] = *(const PG8_LAS bf16x8*)(lds + PG8_SB(b, h) + boff + n * 2048 + k * 1024); } while (0)
; #define PG8_MMA(ai, bj, At, Bt) do { __builtin_amdgcn_s_setprio(1); _Pragma("unroll") for (int m = 0; m < 4; ++m) _Pragma("unroll") for (int n = 0; n < 2; ++n) _Pragma("unroll") for (int k = 0; k < 2; ++k) \
;         acc[ai][bj][m][n] = __builtin_amdgcn_mfma_f32_16x16x32_bf16(Bt[n][k], At[m][k], acc[ai][bj][m][n], 0, 0, 0); __builtin_amdgcn_s_setprio(0); } while (0)
; #define PG8_WAIT_V(n) asm volatile("s_waitcnt vmcnt(" #n ")" ::: "memory")
; #define PG8_WAIT_L(n) asm volatile("s_waitcnt lgkmcnt(" #n ")" ::: "memory")
; #define PG8_BAR __builtin_amdgcn_s_barrier()
; #define PG8_SCHED __builtin_amdgcn_sched_barrier(0)
; template <class Epi, class Sched, bool ALIGN_EPI = false, bool SP2 = false>
; __device__ __forceinline__ void gemm_phase(PG8_LAS unsigned char* lds, const Gemm g, const Sched& S, const Epi& E, const int wid) {
;     ...
;             PG8_WAIT_V(8); PG8_WAIT_L(0); PG8_BAR; PG8_MMA(1, 0, At, B0); PG8_MMA(1, 1, At, B1); PG8_BAR; PG8_SCHED;
;             PG8_LDB(B0, 1, 0); PG8_LDB(B1, 1, 1); PG8_SCHED; PG8_LDA(At, 1, 0); PG8_STAGE(PG8_SA(0, 1), a2 + hstep, voffA);
;             PG8_WAIT_V(8); PG8_WAIT_L(0); PG8_BAR; PG8_MMA(0, 0, At, B0); PG8_MMA(0, 1, At, B1); PG8_BAR; PG8_SCHED;
	v_mfma_f32_16x16x32_bf16 v[92:95], v[128:131], v[190:193], v[92:95]
	v_mfma_f32_16x16x32_bf16 v[88:91], v[136:139], v[190:193], v[88:91]
	v_mfma_f32_16x16x32_bf16 v[84:87], v[128:131], v[198:201], v[84:87]
	v_mfma_f32_16x16x32_bf16 v[80:83], v[136:139], v[198:201], v[80:83]
	v_mfma_f32_16x16x32_bf16 v[76:79], v[128:131], v[206:209], v[76:79]
	v_mfma_f32_16x16x32_bf16 v[72:75], v[136:139], v[206:209], v[72:75]
	v_mfma_f32_16x16x32_bf16 v[64:67], v[128:131], v[214:217], v[64:67]
	v_mfma_f32_16x16x32_bf16 v[56:59], v[136:139], v[214:217], v[56:59]
	v_mfma_f32_16x16x32_bf16 v[92:95], v[132:135], v[194:197], v[92:95]
	v_mfma_f32_16x16x32_bf16 v[88:91], v[140:143], v[194:197], v[88:91]
	v_mfma_f32_16x16x32_bf16 v[84:87], v[132:135], v[202:205], v[84:87]
	v_mfma_f32_16x16x32_bf16 v[80:83], v[140:143], v[202:205], v[80:83]
	v_mfma_f32_16x16x32_bf16 v[76:79], v[132:135], v[210:213], v[76:79]
	v_mfma_f32_16x16x32_bf16 v[72:75], v[140:143], v[210:213], v[72:75]
	v_mfma_f32_16x16x32_bf16 v[64:67], v[132:135], v[218:221], v[64:67]
	v_mfma_f32_16x16x32_bf16 v[56:59], v[140:143], v[218:221], v[56:59]
	s_setprio 0
	s_setprio 1
	v_mfma_f32_16x16x32_bf16 v[28:31], v[174:177], v[190:193], v[28:31]
	v_mfma_f32_16x16x32_bf16 v[24:27], v[182:185], v[190:193], v[24:27]
	v_mfma_f32_16x16x32_bf16 v[20:23], v[174:177], v[198:201], v[20:23]
	v_mfma_f32_16x16x32_bf16 v[16:19], v[182:185], v[198:201], v[16:19]
	v_mfma_f32_16x16x32_bf16 v[12:15], v[174:177], v[206:209], v[12:15]
	v_mfma_f32_16x16x32_bf16 v[8:11], v[182:185], v[206:209], v[8:11]
	v_mfma_f32_16x16x32_bf16 v[4:7], v[174:177], v[214:217], v[4:7]
	v_mfma_f32_16x16x32_bf16 v[0:3], v[182:185], v[214:217], v[0:3]
	v_mfma_f32_16x16x32_bf16 v[28:31], v[178:181], v[194:197], v[28:31]
	v_mfma_f32_16x16x32_bf16 v[24:27], v[186:189], v[194:197], v[24:27]
	v_mfma_f32_16x16x32_bf16 v[20:23], v[178:181], v[202:205], v[20:23]
	v_mfma_f32_16x16x32_bf16 v[16:19], v[186:189], v[202:205], v[16:19]
	v_mfma_f32_16x16x32_bf16 v[12:15], v[178:181], v[210:213], v[12:15]
	v_mfma_f32_16x16x32_bf16 v[8:11], v[186:189], v[210:213], v[8:11]
	v_mfma_f32_16x16x32_bf16 v[4:7], v[178:181], v[218:221], v[4:7]
	v_mfma_f32_16x16x32_bf16 v[0:3], v[186:189], v[218:221], v[0:3]
	s_barrier
	s_setprio 0
	s_add_i32 s74, 0, 0x18000
	s_add_i32 s75, 0, 0x1c000
	v_add_u32_e32 v140, s74, v163
	v_add_u32_e32 v160, s75, v163
	ds_read_b128 v[128:131], v140
	ds_read_b128 v[132:135], v140 offset:1024
	ds_read_b128 v[136:139], v140 offset:2048
	ds_read_b128 v[140:143], v140 offset:3072
	ds_read_b128 v[174:177], v160
	ds_read_b128 v[178:181], v160 offset:1024
	ds_read_b128 v[182:185], v160 offset:2048
	ds_read_b128 v[186:189], v160 offset:3072
	s_add_u32 s56, s56, 0x80000
	s_addc_u32 s57, s57, 0
	s_mov_b32 m0, s58
	v_lshl_add_u64 v[230:231], s[56:57], 0, v[150:151]
	ds_read_b128 v[190:193], v171 offset:32768
	ds_read_b128 v[194:197], v171 offset:33792
	ds_read_b128 v[198:201], v171 offset:34816
	ds_read_b128 v[202:205], v171 offset:35840
	ds_read_b128 v[206:209], v171 offset:36864
	ds_read_b128 v[210:213], v171 offset:37888
	ds_read_b128 v[214:217], v171 offset:38912
	ds_read_b128 v[218:221], v171 offset:39936
	global_load_lds_dwordx4 v[230:231], off
	v_lshl_add_u64 v[230:231], s[56:57], 0, v[146:147]
	s_mov_b32 m0, s59
	s_nop 0
	global_load_lds_dwordx4 v[230:231], off
	s_waitcnt vmcnt(8)
	s_waitcnt lgkmcnt(0)
	s_setprio 1
	s_barrier
	v_mfma_f32_16x16x32_bf16 v[124:127], v[128:131], v[190:193], v[124:127]
	v_mfma_f32_16x16x32_bf16 v[120:123], v[136:139], v[190:193], v[120:123]
	v_mfma_f32_16x16x32_bf16 v[116:119], v[128:131], v[198:201], v[116:119]
	v_mfma_f32_16x16x32_bf16 v[112:115], v[136:139], v[198:201], v[112:115]
	v_mfma_f32_16x16x32_bf16 v[108:111], v[128:131], v[206:209], v[108:111]
	v_mfma_f32_16x16x32_bf16 v[104:107], v[136:139], v[206:209], v[104:107]
	v_mfma_f32_16x16x32_bf16 v[100:103], v[128:131], v[214:217], v[100:103]
	v_mfma_f32_16x16x32_bf16 v[96:99], v[136:139], v[214:217], v[96:99]
	v_mfma_f32_16x16x32_bf16 v[124:127], v[132:135], v[194:197], v[124:127]
	v_mfma_f32_16x16x32_bf16 v[120:123], v[140:143], v[194:197], v[120:123]
	v_mfma_f32_16x16x32_bf16 v[116:119], v[132:135], v[202:205], v[116:119]
	v_mfma_f32_16x16x32_bf16 v[112:115], v[140:143], v[202:205], v[112:115]
	v_mfma_f32_16x16x32_bf16 v[108:111], v[132:135], v[210:213], v[108:111]
	v_mfma_f32_16x16x32_bf16 v[104:107], v[140:143], v[210:213], v[104:107]
	v_mfma_f32_16x16x32_bf16 v[100:103], v[132:135], v[218:221], v[100:103]
	v_mfma_f32_16x16x32_bf16 v[96:99], v[140:143], v[218:221], v[96:99]
	s_setprio 0
	s_setprio 1
	v_mfma_f32_16x16x32_bf16 v[68:71], v[174:177], v[190:193], v[68:71]
	v_mfma_f32_16x16x32_bf16 v[60:63], v[182:185], v[190:193], v[60:63]
	v_mfma_f32_16x16x32_bf16 v[52:55], v[174:177], v[198:201], v[52:55]
	v_mfma_f32_16x16x32_bf16 v[48:51], v[182:185], v[198:201], v[48:51]
	v_mfma_f32_16x16x32_bf16 v[44:47], v[174:177], v[206:209], v[44:47]
	v_mfma_f32_16x16x32_bf16 v[40:43], v[182:185], v[206:209], v[40:43]
	v_mfma_f32_16x16x32_bf16 v[36:39], v[174:177], v[214:217], v[36:39]
	v_mfma_f32_16x16x32_bf16 v[32:35], v[182:185], v[214:217], v[32:35]
	v_mfma_f32_16x16x32_bf16 v[68:71], v[178:181], v[194:197], v[68:71]
	v_mfma_f32_16x16x32_bf16 v[60:63], v[186:189], v[194:197], v[60:63]
	v_mfma_f32_16x16x32_bf16 v[52:55], v[178:181], v[202:205], v[52:55]
	v_mfma_f32_16x16x32_bf16 v[48:51], v[186:189], v[202:205], v[48:51]
	v_mfma_f32_16x16x32_bf16 v[44:47], v[178:181], v[210:213], v[44:47]
	v_mfma_f32_16x16x32_bf16 v[40:43], v[186:189], v[210:213], v[40:43]
	v_mfma_f32_16x16x32_bf16 v[36:39], v[178:181], v[218:221], v[36:39]
	v_mfma_f32_16x16x32_bf16 v[32:35], v[186:189], v[218:221], v[32:35]
	s_barrier
; #define PG8_STAGE(bufoff, gbase, voff) do { _Pragma("unroll") for (int _i = 0; _i < 2; ++_i) \
;         __builtin_amdgcn_global_load_lds((const unsigned*)((const char*)(gbase) + (voff)[_i]), (PG8_LAS unsigned*)(lds + (bufoff) + ldsw + _i * 8192), 16, 0, 0); } while (0)
; #define PG8_LDA(dst, b, h) do { _Pragma("unroll") for (int m = 0; m < 4; ++m) _Pragma("unroll") for (int k = 0; k < 2; ++k) dst[m][k] = *(const PG8_LAS bf16x8*)(lds + PG8_SA(b, h) + aoff + m * 2048 + k * 1024); } while (0)
; #define PG8_MMA(ai, bj, At, Bt) do { __builtin_amdgcn_s_setprio(1); _Pragma("unroll") for (int m = 0; m < 4; ++m) _Pragma("unroll") for (int n = 0; n < 2; ++n) _Pragma("unroll") for (int k = 0; k < 2; ++k) \
;         acc[ai][bj][m][n] = __builtin_amdgcn_mfma_f32_16x16x32_bf16(Bt[n][k], At[m][k], acc[ai][bj][m][n], 0, 0, 0); __builtin_amdgcn_s_setprio(0); } while (0)
; #define PG8_WAIT_V(n) asm volatile("s_waitcnt vmcnt(" #n ")" ::: "memory")
; #define PG8_WAIT_L(n) asm volatile("s_waitcnt lgkmcnt(" #n ")" ::: "memory")
; #define PG8_BAR __builtin_amdgcn_s_barrier()
; #define PG8_SCHED __builtin_amdgcn_sched_barrier(0)
; template <class Epi, class Sched, bool ALIGN_EPI = false, bool SP2 = false>
; __device__ __forceinline__ void gemm_phase(PG8_LAS unsigned char* lds, const Gemm g, const Sched& S, const Epi& E, const int wid) {
;     ...
;             PG8_LDA(At, 1, 1); PG8_STAGE(PG8_SB(1, 0), b3, voffB); PG8_STAGE(PG8_SB(1, 1), b3 + hstep, voffB); PG8_STAGE(PG8_SA(1, 0), a3, voffA);
;             PG8_WAIT_V(8); PG8_WAIT_L(0); PG8_BAR; PG8_MMA(1, 0, At, B0); PG8_MMA(1, 1, At, B1); PG8_BAR; PG8_SCHED;
;     ...
;         if constexpr (ALIGN_EPI) { if (wr == 0) PG8_BAR; }
	s_setprio 0
	s_add_i32 s56, s74, s3
	v_lshl_add_u64 v[222:223], v[222:223], 0, s[26:27]
	s_mov_b32 m0, s56
	ds_read_b128 v[190:193], v171 offset:49152
	ds_read_b128 v[194:197], v171 offset:50176
	ds_read_b128 v[198:201], v171 offset:51200
	ds_read_b128 v[202:205], v171 offset:52224
	ds_read_b128 v[206:209], v171 offset:53248
	ds_read_b128 v[210:213], v171 offset:54272
	ds_read_b128 v[214:217], v171 offset:55296
	ds_read_b128 v[218:221], v171 offset:56320
	global_load_lds_dwordx4 v[222:223], off
	s_add_i32 m0, s56, 0x2000
	s_add_u32 s54, s54, 0x80080
	v_lshl_add_u64 v[222:223], v[224:225], 0, s[26:27]
	s_addc_u32 s55, s55, 0
	s_add_i32 s56, s75, s3
	global_load_lds_dwordx4 v[222:223], off
	v_lshl_add_u64 v[222:223], s[54:55], 0, v[148:149]
	s_mov_b32 m0, s56
	s_nop 0
	global_load_lds_dwordx4 v[222:223], off
	v_lshl_add_u64 v[222:223], s[54:55], 0, v[144:145]
	s_add_i32 m0, s56, 0x2000
	s_nop 0
	global_load_lds_dwordx4 v[222:223], off
	v_lshl_add_u64 v[222:223], v[226:227], 0, s[26:27]
	s_mov_b32 m0, s60
	s_nop 0
	global_load_lds_dwordx4 v[222:223], off
	v_lshl_add_u64 v[222:223], v[228:229], 0, s[26:27]
	s_mov_b32 m0, s61
	s_nop 0
	global_load_lds_dwordx4 v[222:223], off
	s_waitcnt vmcnt(8)
	s_waitcnt lgkmcnt(0)
	s_setprio 1
	s_barrier
	v_mfma_f32_16x16x32_bf16 v[92:95], v[128:131], v[190:193], v[92:95]
	v_mfma_f32_16x16x32_bf16 v[88:91], v[136:139], v[190:193], v[88:91]
	v_mfma_f32_16x16x32_bf16 v[84:87], v[128:131], v[198:201], v[84:87]
	v_mfma_f32_16x16x32_bf16 v[80:83], v[136:139], v[198:201], v[80:83]
	v_mfma_f32_16x16x32_bf16 v[76:79], v[128:131], v[206:209], v[76:79]
	v_mfma_f32_16x16x32_bf16 v[72:75], v[136:139], v[206:209], v[72:75]
	v_mfma_f32_16x16x32_bf16 v[64:67], v[128:131], v[214:217], v[64:67]
	v_mfma_f32_16x16x32_bf16 v[56:59], v[136:139], v[214:217], v[56:59]
	v_mfma_f32_16x16x32_bf16 v[92:95], v[132:135], v[194:197], v[92:95]
	v_mfma_f32_16x16x32_bf16 v[88:91], v[140:143], v[194:197], v[88:91]
	v_mfma_f32_16x16x32_bf16 v[84:87], v[132:135], v[202:205], v[84:87]
	v_mfma_f32_16x16x32_bf16 v[80:83], v[140:143], v[202:205], v[80:83]
	v_mfma_f32_16x16x32_bf16 v[76:79], v[132:135], v[210:213], v[76:79]
	v_mfma_f32_16x16x32_bf16 v[72:75], v[140:143], v[210:213], v[72:75]
	v_mfma_f32_16x16x32_bf16 v[64:67], v[132:135], v[218:221], v[64:67]
	v_mfma_f32_16x16x32_bf16 v[56:59], v[140:143], v[218:221], v[56:59]
	s_setprio 0
	s_setprio 1
	v_mfma_f32_16x16x32_bf16 v[28:31], v[174:177], v[190:193], v[28:31]
	v_mfma_f32_16x16x32_bf16 v[24:27], v[182:185], v[190:193], v[24:27]
	v_mfma_f32_16x16x32_bf16 v[20:23], v[174:177], v[198:201], v[20:23]
	v_mfma_f32_16x16x32_bf16 v[16:19], v[182:185], v[198:201], v[16:19]
	v_mfma_f32_16x16x32_bf16 v[12:15], v[174:177], v[206:209], v[12:15]
	v_mfma_f32_16x16x32_bf16 v[8:11], v[182:185], v[206:209], v[8:11]
	v_mfma_f32_16x16x32_bf16 v[4:7], v[174:177], v[214:217], v[4:7]
	v_mfma_f32_16x16x32_bf16 v[0:3], v[182:185], v[214:217], v[0:3]
	v_mfma_f32_16x16x32_bf16 v[28:31], v[178:181], v[194:197], v[28:31]
	v_mfma_f32_16x16x32_bf16 v[24:27], v[186:189], v[194:197], v[24:27]
	v_mfma_f32_16x16x32_bf16 v[20:23], v[178:181], v[202:205], v[20:23]
	v_mfma_f32_16x16x32_bf16 v[16:19], v[186:189], v[202:205], v[16:19]
	v_mfma_f32_16x16x32_bf16 v[12:15], v[178:181], v[210:213], v[12:15]
	v_mfma_f32_16x16x32_bf16 v[8:11], v[186:189], v[210:213], v[8:11]
	v_mfma_f32_16x16x32_bf16 v[4:7], v[178:181], v[218:221], v[4:7]
	v_mfma_f32_16x16x32_bf16 v[0:3], v[186:189], v[218:221], v[0:3]
	s_barrier
	s_setprio 0
	s_add_i32 s73, s73, 2
	s_add_u32 s71, s71, 0x100
	s_addc_u32 s72, s72, 0
	s_add_u32 s14, s14, 0x100
	s_addc_u32 s15, s15, 0
	s_cmp_gt_u32 s73, 29
	s_cbranch_scc0 .LBB0_682
	s_and_b64 vcc, exec, s[20:21]
	s_cbranch_vccz .LBB0_685
	s_barrier

; #define PG8_STAGE(bufoff, gbase, voff) do { _Pragma("unroll") for (int _i = 0; _i < 2; ++_i) \
;         __builtin_amdgcn_global_load_lds((const unsigned*)((const char*)(gbase) + (voff)[_i]), (PG8_LAS unsigned*)(lds + (bufoff) + ldsw + _i * 8192), 16, 0, 0); } while (0)
; #define PG8_LDA(dst, b, h) do { _Pragma("unroll") for (int m = 0; m < 4; ++m) _Pragma("unroll") for (int k = 0; k < 2; ++k) dst[m][k] = *(const PG8_LAS bf16x8*)(lds + PG8_SA(b, h) + aoff + m * 2048 + k * 1024); } while (0)
; #define PG8_LDB(dst, b, h) do { _Pragma("unroll") for (int n = 0; n < 2; ++n) _Pragma("unroll") for (int k = 0; k < 2; ++k) dst[n][k] = *(const PG8_LAS bf16x8*)(lds + PG8_SB(b, h) + boff + n * 2048 + k * 1024); } while (0)
; #define PG8_MMA(ai, bj, At, Bt) do { __builtin_amdgcn_s_setprio(1); _Pragma("unroll") for (int m = 0; m < 4; ++m) _Pragma("unroll") for (int n = 0; n < 2; ++n) _Pragma("unroll") for (int k = 0; k < 2; ++k) \
;         acc[ai][bj][m][n] = __builtin_amdgcn_mfma_f32_16x16x32_bf16(Bt[n][k], At[m][k], acc[ai][bj][m][n], 0, 0, 0); __builtin_amdgcn_s_setprio(0); } while (0)
; #define PG8_WAIT_V(n) asm volatile("s_waitcnt vmcnt(" #n ")" ::: "memory")
; #define PG8_WAIT_L(n) asm volatile("s_waitcnt lgkmcnt(" #n ")" ::: "memory")
; #define PG8_BAR __builtin_amdgcn_s_barrier()
; #define PG8_SCHED __builtin_amdgcn_sched_barrier(0)
; template <class Epi, class Sched, bool ALIGN_EPI = false, bool SP2 = false>
; __device__ __forceinline__ void gemm_phase(PG8_LAS unsigned char* lds, const Gemm g, const Sched& S, const Epi& E, const int wid) {
;     ...
;             PG8_LDB(B0, 0, 0); PG8_LDB(B1, 0, 1); PG8_SCHED; PG8_LDA(At, 0, 0); PG8_STAGE(PG8_SA(1, 1), a1 + hstep, voffA);
;             PG8_WAIT_V(8); PG8_WAIT_L(0); PG8_BAR; PG8_MMA(0, 0, At, B0); PG8_MMA(0, 1, At, B1); PG8_BAR; PG8_SCHED;
;             PG8_LDA(At, 0, 1); PG8_STAGE(PG8_SB(0, 0), b2, voffB); PG8_STAGE(PG8_SB(0, 1), b2 + hstep, voffB); PG8_STAGE(PG8_SA(0, 0), a2, voffA);
.LBB0_754:
	ds_read_b128 v[128:131], v239
	ds_read_b128 v[132:135], v239 offset:1024
	ds_read_b128 v[136:139], v239 offset:2048
	ds_read_b128 v[140:143], v239 offset:3072
	ds_read_b128 v[144:147], v240
	ds_read_b128 v[148:151], v240 offset:1024
	ds_read_b128 v[152:155], v240 offset:2048
	ds_read_b128 v[156:159], v240 offset:3072
	s_add_u32 s8, s64, 0xffe00080
	s_addc_u32 s9, s65, -1
	s_cmpk_eq_i32 s93, 0x7c
	s_cselect_b32 s69, s17, s9
	s_cselect_b32 s68, s57, s8
	s_cselect_b32 s67, s55, s92
	s_cselect_b32 s66, s90, s91
	v_lshl_add_u64 v[208:209], s[64:65], 0, v[182:183]
	s_add_i32 m0, s41, 0xc000
	ds_read_b128 v[160:163], v241
	ds_read_b128 v[164:167], v241 offset:1024
	ds_read_b128 v[168:171], v241 offset:2048
	ds_read_b128 v[188:191], v241 offset:3072
	ds_read_b128 v[192:195], v241 offset:4096
	ds_read_b128 v[196:199], v241 offset:5120
	ds_read_b128 v[200:203], v241 offset:6144
	ds_read_b128 v[204:207], v241 offset:7168
	global_load_lds_dwordx4 v[208:209], off
	v_lshl_add_u64 v[208:209], s[64:65], 0, v[180:181]
	s_add_i32 m0, s41, 0xe000
	s_nop 0
	global_load_lds_dwordx4 v[208:209], off
	s_waitcnt vmcnt(8)
	s_waitcnt lgkmcnt(0)
	s_setprio 1
	s_barrier
	v_mfma_f32_16x16x32_bf16 v[124:127], v[128:131], v[160:163], v[124:127]
	v_mfma_f32_16x16x32_bf16 v[120:123], v[136:139], v[160:163], v[120:123]
	v_mfma_f32_16x16x32_bf16 v[116:119], v[128:131], v[168:171], v[116:119]
	v_mfma_f32_16x16x32_bf16 v[112:115], v[136:139], v[168:171], v[112:115]
	v_mfma_f32_16x16x32_bf16 v[108:111], v[128:131], v[192:195], v[108:111]
	v_mfma_f32_16x16x32_bf16 v[104:107], v[136:139], v[192:195], v[104:107]
	v_mfma_f32_16x16x32_bf16 v[100:103], v[128:131], v[200:203], v[100:103]
	v_mfma_f32_16x16x32_bf16 v[96:99], v[136:139], v[200:203], v[96:99]
	v_mfma_f32_16x16x32_bf16 v[124:127], v[132:135], v[164:167], v[124:127]
	v_mfma_f32_16x16x32_bf16 v[120:123], v[140:143], v[164:167], v[120:123]
	v_mfma_f32_16x16x32_bf16 v[116:119], v[132:135], v[188:191], v[116:119]
	v_mfma_f32_16x16x32_bf16 v[112:115], v[140:143], v[188:191], v[112:115]
	v_mfma_f32_16x16x32_bf16 v[108:111], v[132:135], v[196:199], v[108:111]
	v_mfma_f32_16x16x32_bf16 v[104:107], v[140:143], v[196:199], v[104:107]
	v_mfma_f32_16x16x32_bf16 v[100:103], v[132:135], v[204:207], v[100:103]
	v_mfma_f32_16x16x32_bf16 v[96:99], v[140:143], v[204:207], v[96:99]
	s_setprio 0
	s_setprio 1
	v_mfma_f32_16x16x32_bf16 v[60:63], v[144:147], v[160:163], v[60:63]
	v_mfma_f32_16x16x32_bf16 v[56:59], v[152:155], v[160:163], v[56:59]
	v_mfma_f32_16x16x32_bf16 v[52:55], v[144:147], v[168:171], v[52:55]
	v_mfma_f32_16x16x32_bf16 v[48:51], v[152:155], v[168:171], v[48:51]
	v_mfma_f32_16x16x32_bf16 v[44:47], v[144:147], v[192:195], v[44:47]
	v_mfma_f32_16x16x32_bf16 v[40:43], v[152:155], v[192:195], v[40:43]
	v_mfma_f32_16x16x32_bf16 v[36:39], v[144:147], v[200:203], v[36:39]
	v_mfma_f32_16x16x32_bf16 v[32:35], v[152:155], v[200:203], v[32:35]
	v_mfma_f32_16x16x32_bf16 v[60:63], v[148:151], v[164:167], v[60:63]
	v_mfma_f32_16x16x32_bf16 v[56:59], v[156:159], v[164:167], v[56:59]
	v_mfma_f32_16x16x32_bf16 v[52:55], v[148:151], v[188:191], v[52:55]
	v_mfma_f32_16x16x32_bf16 v[48:51], v[156:159], v[188:191], v[48:51]
	v_mfma_f32_16x16x32_bf16 v[44:47], v[148:151], v[196:199], v[44:47]
	v_mfma_f32_16x16x32_bf16 v[40:43], v[156:159], v[196:199], v[40:43]
	v_mfma_f32_16x16x32_bf16 v[36:39], v[148:151], v[204:207], v[36:39]
	v_mfma_f32_16x16x32_bf16 v[32:35], v[156:159], v[204:207], v[32:35]
	s_barrier
	s_setprio 0
	s_add_i32 s8, s73, s3
	v_lshl_add_u64 v[208:209], s[66:67], 0, v[174:175]
	s_mov_b32 m0, s8
	ds_read_b128 v[160:163], v241 offset:16384
	ds_read_b128 v[164:167], v241 offset:17408
	ds_read_b128 v[168:171], v241 offset:18432
	ds_read_b128 v[188:191], v241 offset:19456
	ds_read_b128 v[192:195], v241 offset:20480
	ds_read_b128 v[196:199], v241 offset:21504
	ds_read_b128 v[200:203], v241 offset:22528
	ds_read_b128 v[204:207], v241 offset:23552
	global_load_lds_dwordx4 v[208:209], off
	s_add_i32 m0, s8, 0x2000
	s_add_u32 s94, s66, 0x200000
	v_lshl_add_u64 v[210:211], s[66:67], 0, v[178:179]
	s_addc_u32 s95, s67, 0
	s_add_i32 s8, s74, s3
	global_load_lds_dwordx4 v[210:211], off
	v_lshl_add_u64 v[212:213], s[94:95], 0, v[174:175]
	s_mov_b32 m0, s8
	v_lshl_add_u64 v[216:217], s[68:69], 0, v[176:177]
	global_load_lds_dwordx4 v[212:213], off
	v_lshl_add_u64 v[212:213], s[94:95], 0, v[178:179]
	s_add_i32 m0, s8, 0x2000
	s_nop 0
	global_load_lds_dwordx4 v[212:213], off
	v_lshl_add_u64 v[212:213], s[68:69], 0, v[172:173]
	s_mov_b32 m0, s41
	s_nop 0
	global_load_lds_dwordx4 v[212:213], off
	s_mov_b32 m0, s44
	s_nop 0
	global_load_lds_dwordx4 v[216:217], off
	s_waitcnt vmcnt(8)
	s_waitcnt lgkmcnt(0)
	s_setprio 1
	s_barrier
; #define PG8_STAGE(bufoff, gbase, voff) do { _Pragma("unroll") for (int _i = 0; _i < 2; ++_i) \
;         __builtin_amdgcn_global_load_lds((const unsigned*)((const char*)(gbase) + (voff)[_i]), (PG8_LAS unsigned*)(lds + (bufoff) + ldsw + _i * 8192), 16, 0, 0); } while (0)
; #define PG8_LDA(dst, b, h) do { _Pragma("unroll") for (int m = 0; m < 4; ++m) _Pragma("unroll") for (int k = 0; k < 2; ++k) dst[m][k] = *(const PG8_LAS bf16x8*)(lds + PG8_SA(b, h) + aoff + m * 2048 + k * 1024); } while (0)
; #define PG8_LDB(dst, b, h) do { _Pragma("unroll") for (int n = 0; n < 2; ++n) _Pragma("unroll") for (int k = 0; k < 2; ++k) dst[n][k] = *(const PG8_LAS bf16x8*)(lds + PG8_SB(b, h) + boff + n * 2048 + k * 1024); } while (0)
; #define PG8_MMA(ai, bj, At, Bt) do { __builtin_amdgcn_s_setprio(1); _Pragma("unroll") for (int m = 0; m < 4; ++m) _Pragma("unroll") for (int n = 0; n < 2; ++n) _Pragma("unroll") for (int k = 0; k < 2; ++k) \
;         acc[ai][bj][m][n] = __builtin_amdgcn_mfma_f32_16x16x32_bf16(Bt[n][k], At[m][k], acc[ai][bj][m][n], 0, 0, 0); __builtin_amdgcn_s_setprio(0); } while (0)
; #define PG8_WAIT_V(n) asm volatile("s_waitcnt vmcnt(" #n ")" ::: "memory")
; #define PG8_WAIT_L(n) asm volatile("s_waitcnt lgkmcnt(" #n ")" ::: "memory")
; #define PG8_BAR __builtin_amdgcn_s_barrier()
; #define PG8_SCHED __builtin_amdgcn_sched_barrier(0)
; template <class Epi, class Sched, bool ALIGN_EPI = false, bool SP2 = false>
; __device__ __forceinline__ void gemm_phase(PG8_LAS unsigned char* lds, const Gemm g, const Sched& S, const Epi& E, const int wid) {
;     ...
;             PG8_WAIT_V(8); PG8_WAIT_L(0); PG8_BAR; PG8_MMA(1, 0, At, B0); PG8_MMA(1, 1, At, B1); PG8_BAR; PG8_SCHED;
;             PG8_LDB(B0, 1, 0); PG8_LDB(B1, 1, 1); PG8_SCHED; PG8_LDA(At, 1, 0); PG8_STAGE(PG8_SA(0, 1), a2 + hstep, voffA);
;             PG8_WAIT_V(8); PG8_WAIT_L(0); PG8_BAR; PG8_MMA(0, 0, At, B0); PG8_MMA(0, 1, At, B1); PG8_BAR; PG8_SCHED;
	v_mfma_f32_16x16x32_bf16 v[92:95], v[128:131], v[160:163], v[92:95]
	v_mfma_f32_16x16x32_bf16 v[88:91], v[136:139], v[160:163], v[88:91]
	v_mfma_f32_16x16x32_bf16 v[84:87], v[128:131], v[168:171], v[84:87]
	v_mfma_f32_16x16x32_bf16 v[80:83], v[136:139], v[168:171], v[80:83]
	v_mfma_f32_16x16x32_bf16 v[76:79], v[128:131], v[192:195], v[76:79]
	v_mfma_f32_16x16x32_bf16 v[72:75], v[136:139], v[192:195], v[72:75]
	v_mfma_f32_16x16x32_bf16 v[68:71], v[128:131], v[200:203], v[68:71]
	v_mfma_f32_16x16x32_bf16 v[64:67], v[136:139], v[200:203], v[64:67]
	v_mfma_f32_16x16x32_bf16 v[92:95], v[132:135], v[164:167], v[92:95]
	v_mfma_f32_16x16x32_bf16 v[88:91], v[140:143], v[164:167], v[88:91]
	v_mfma_f32_16x16x32_bf16 v[84:87], v[132:135], v[188:191], v[84:87]
	v_mfma_f32_16x16x32_bf16 v[80:83], v[140:143], v[188:191], v[80:83]
	v_mfma_f32_16x16x32_bf16 v[76:79], v[132:135], v[196:199], v[76:79]
	v_mfma_f32_16x16x32_bf16 v[72:75], v[140:143], v[196:199], v[72:75]
	v_mfma_f32_16x16x32_bf16 v[68:71], v[132:135], v[204:207], v[68:71]
	v_mfma_f32_16x16x32_bf16 v[64:67], v[140:143], v[204:207], v[64:67]
	s_setprio 0
	s_setprio 1
	v_mfma_f32_16x16x32_bf16 v[28:31], v[144:147], v[160:163], v[28:31]
	v_mfma_f32_16x16x32_bf16 v[24:27], v[152:155], v[160:163], v[24:27]
	v_mfma_f32_16x16x32_bf16 v[20:23], v[144:147], v[168:171], v[20:23]
	v_mfma_f32_16x16x32_bf16 v[16:19], v[152:155], v[168:171], v[16:19]
	v_mfma_f32_16x16x32_bf16 v[12:15], v[144:147], v[192:195], v[12:15]
	v_mfma_f32_16x16x32_bf16 v[8:11], v[152:155], v[192:195], v[8:11]
	v_mfma_f32_16x16x32_bf16 v[4:7], v[144:147], v[200:203], v[4:7]
	v_mfma_f32_16x16x32_bf16 v[0:3], v[152:155], v[200:203], v[0:3]
	v_mfma_f32_16x16x32_bf16 v[28:31], v[148:151], v[164:167], v[28:31]
	v_mfma_f32_16x16x32_bf16 v[24:27], v[156:159], v[164:167], v[24:27]
	v_mfma_f32_16x16x32_bf16 v[20:23], v[148:151], v[188:191], v[20:23]
	v_mfma_f32_16x16x32_bf16 v[16:19], v[156:159], v[188:191], v[16:19]
	v_mfma_f32_16x16x32_bf16 v[12:15], v[148:151], v[196:199], v[12:15]
	v_mfma_f32_16x16x32_bf16 v[8:11], v[156:159], v[196:199], v[8:11]
	v_mfma_f32_16x16x32_bf16 v[4:7], v[148:151], v[204:207], v[4:7]
	v_mfma_f32_16x16x32_bf16 v[0:3], v[156:159], v[204:207], v[0:3]
	s_barrier
	s_setprio 0
	s_add_i32 s8, 0, 0x18000
	s_add_i32 s9, 0, 0x1c000
	v_add_u32_e32 v140, s8, v231
	v_add_u32_e32 v156, s9, v231
	ds_read_b128 v[128:131], v140
	ds_read_b128 v[132:135], v140 offset:1024
	ds_read_b128 v[136:139], v140 offset:2048
	ds_read_b128 v[140:143], v140 offset:3072
	ds_read_b128 v[144:147], v156
	ds_read_b128 v[148:151], v156 offset:1024
	ds_read_b128 v[152:155], v156 offset:2048
	ds_read_b128 v[156:159], v156 offset:3072
	s_add_u32 s68, s68, 0x200000
	s_addc_u32 s69, s69, 0
	s_mov_b32 m0, s45
	v_lshl_add_u64 v[218:219], s[68:69], 0, v[172:173]
	ds_read_b128 v[160:163], v241 offset:32768
	ds_read_b128 v[164:167], v241 offset:33792
	ds_read_b128 v[168:171], v241 offset:34816
	ds_read_b128 v[188:191], v241 offset:35840
	ds_read_b128 v[192:195], v241 offset:36864
	ds_read_b128 v[196:199], v241 offset:37888
	ds_read_b128 v[200:203], v241 offset:38912
	ds_read_b128 v[204:207], v241 offset:39936
	global_load_lds_dwordx4 v[218:219], off
	v_lshl_add_u64 v[218:219], s[68:69], 0, v[176:177]
	s_mov_b32 m0, s53
	s_nop 0
	global_load_lds_dwordx4 v[218:219], off
	s_waitcnt vmcnt(8)
	s_waitcnt lgkmcnt(0)
	s_setprio 1
	s_barrier
	v_mfma_f32_16x16x32_bf16 v[124:127], v[128:131], v[160:163], v[124:127]
	v_mfma_f32_16x16x32_bf16 v[120:123], v[136:139], v[160:163], v[120:123]
	v_mfma_f32_16x16x32_bf16 v[116:119], v[128:131], v[168:171], v[116:119]
	v_mfma_f32_16x16x32_bf16 v[112:115], v[136:139], v[168:171], v[112:115]
	v_mfma_f32_16x16x32_bf16 v[108:111], v[128:131], v[192:195], v[108:111]
	v_mfma_f32_16x16x32_bf16 v[104:107], v[136:139], v[192:195], v[104:107]
	v_mfma_f32_16x16x32_bf16 v[100:103], v[128:131], v[200:203], v[100:103]
	v_mfma_f32_16x16x32_bf16 v[96:99], v[136:139], v[200:203], v[96:99]
	v_mfma_f32_16x16x32_bf16 v[124:127], v[132:135], v[164:167], v[124:127]
	v_mfma_f32_16x16x32_bf16 v[120:123], v[140:143], v[164:167], v[120:123]
	v_mfma_f32_16x16x32_bf16 v[116:119], v[132:135], v[188:191], v[116:119]
	v_mfma_f32_16x16x32_bf16 v[112:115], v[140:143], v[188:191], v[112:115]
	v_mfma_f32_16x16x32_bf16 v[108:111], v[132:135], v[196:199], v[108:111]
	v_mfma_f32_16x16x32_bf16 v[104:107], v[140:143], v[196:199], v[104:107]
	v_mfma_f32_16x16x32_bf16 v[100:103], v[132:135], v[204:207], v[100:103]
	v_mfma_f32_16x16x32_bf16 v[96:99], v[140:143], v[204:207], v[96:99]
	s_setprio 0
	s_setprio 1
	v_mfma_f32_16x16x32_bf16 v[60:63], v[144:147], v[160:163], v[60:63]
	v_mfma_f32_16x16x32_bf16 v[56:59], v[152:155], v[160:163], v[56:59]
	v_mfma_f32_16x16x32_bf16 v[52:55], v[144:147], v[168:171], v[52:55]
	v_mfma_f32_16x16x32_bf16 v[48:51], v[152:155], v[168:171], v[48:51]
	v_mfma_f32_16x16x32_bf16 v[44:47], v[144:147], v[192:195], v[44:47]
	v_mfma_f32_16x16x32_bf16 v[40:43], v[152:155], v[192:195], v[40:43]
	v_mfma_f32_16x16x32_bf16 v[36:39], v[144:147], v[200:203], v[36:39]
	v_mfma_f32_16x16x32_bf16 v[32:35], v[152:155], v[200:203], v[32:35]
	v_mfma_f32_16x16x32_bf16 v[60:63], v[148:151], v[164:167], v[60:63]
	v_mfma_f32_16x16x32_bf16 v[56:59], v[156:159], v[164:167], v[56:59]
	v_mfma_f32_16x16x32_bf16 v[52:55], v[148:151], v[188:191], v[52:55]
	v_mfma_f32_16x16x32_bf16 v[48:51], v[156:159], v[188:191], v[48:51]
	v_mfma_f32_16x16x32_bf16 v[44:47], v[148:151], v[196:199], v[44:47]
	v_mfma_f32_16x16x32_bf16 v[40:43], v[156:159], v[196:199], v[40:43]
	v_mfma_f32_16x16x32_bf16 v[36:39], v[148:151], v[204:207], v[36:39]
	v_mfma_f32_16x16x32_bf16 v[32:35], v[156:159], v[204:207], v[32:35]
	s_barrier
; #define PG8_STAGE(bufoff, gbase, voff) do { _Pragma("unroll") for (int _i = 0; _i < 2; ++_i) \
;         __builtin_amdgcn_global_load_lds((const unsigned*)((const char*)(gbase) + (voff)[_i]), (PG8_LAS unsigned*)(lds + (bufoff) + ldsw + _i * 8192), 16, 0, 0); } while (0)
; #define PG8_LDA(dst, b, h) do { _Pragma("unroll") for (int m = 0; m < 4; ++m) _Pragma("unroll") for (int k = 0; k < 2; ++k) dst[m][k] = *(const PG8_LAS bf16x8*)(lds + PG8_SA(b, h) + aoff + m * 2048 + k * 1024); } while (0)
; #define PG8_MMA(ai, bj, At, Bt) do { __builtin_amdgcn_s_setprio(1); _Pragma("unroll") for (int m = 0; m < 4; ++m) _Pragma("unroll") for (int n = 0; n < 2; ++n) _Pragma("unroll") for (int k = 0; k < 2; ++k) \
;         acc[ai][bj][m][n] = __builtin_amdgcn_mfma_f32_16x16x32_bf16(Bt[n][k], At[m][k], acc[ai][bj][m][n], 0, 0, 0); __builtin_amdgcn_s_setprio(0); } while (0)
; #define PG8_WAIT_V(n) asm volatile("s_waitcnt vmcnt(" #n ")" ::: "memory")
; #define PG8_WAIT_L(n) asm volatile("s_waitcnt lgkmcnt(" #n ")" ::: "memory")
; #define PG8_BAR __builtin_amdgcn_s_barrier()
; #define PG8_SCHED __builtin_amdgcn_sched_barrier(0)
; template <class Epi, class Sched, bool ALIGN_EPI = false, bool SP2 = false>
; __device__ __forceinline__ void gemm_phase(PG8_LAS unsigned char* lds, const Gemm g, const Sched& S, const Epi& E, const int wid) {
;     ...
;             PG8_LDA(At, 1, 1); PG8_STAGE(PG8_SB(1, 0), b3, voffB); PG8_STAGE(PG8_SB(1, 1), b3 + hstep, voffB); PG8_STAGE(PG8_SA(1, 0), a3, voffA);
;             PG8_WAIT_V(8); PG8_WAIT_L(0); PG8_BAR; PG8_MMA(1, 0, At, B0); PG8_MMA(1, 1, At, B1); PG8_BAR; PG8_SCHED;
;     ...
;         if constexpr (ALIGN_EPI) { if (wr == 0) PG8_BAR; }
	s_setprio 0
	s_add_i32 s8, s8, s3
	v_lshl_add_u64 v[208:209], v[208:209], 0, s[50:51]
	s_mov_b32 m0, s8
	ds_read_b128 v[160:163], v241 offset:49152
	ds_read_b128 v[164:167], v241 offset:50176
	ds_read_b128 v[168:171], v241 offset:51200
	ds_read_b128 v[188:191], v241 offset:52224
	ds_read_b128 v[192:195], v241 offset:53248
	ds_read_b128 v[196:199], v241 offset:54272
	ds_read_b128 v[200:203], v241 offset:55296
	ds_read_b128 v[204:207], v241 offset:56320
	global_load_lds_dwordx4 v[208:209], off
	s_add_i32 m0, s8, 0x2000
	s_add_u32 s66, s66, 0x200080
	v_lshl_add_u64 v[208:209], v[210:211], 0, s[50:51]
	s_addc_u32 s67, s67, 0
	s_add_i32 s8, s9, s3
	global_load_lds_dwordx4 v[208:209], off
	v_lshl_add_u64 v[208:209], s[66:67], 0, v[174:175]
	s_mov_b32 m0, s8
	s_nop 0
	global_load_lds_dwordx4 v[208:209], off
	v_lshl_add_u64 v[208:209], s[66:67], 0, v[178:179]
	s_add_i32 m0, s8, 0x2000
	s_nop 0
	global_load_lds_dwordx4 v[208:209], off
	v_lshl_add_u64 v[208:209], v[212:213], 0, s[50:51]
	s_mov_b32 m0, s70
	s_nop 0
	global_load_lds_dwordx4 v[208:209], off
	v_lshl_add_u64 v[208:209], v[216:217], 0, s[50:51]
	s_mov_b32 m0, s71
	s_nop 0
	global_load_lds_dwordx4 v[208:209], off
	s_waitcnt vmcnt(8)
	s_waitcnt lgkmcnt(0)
	s_setprio 1
	s_barrier
	v_mfma_f32_16x16x32_bf16 v[92:95], v[128:131], v[160:163], v[92:95]
	v_mfma_f32_16x16x32_bf16 v[88:91], v[136:139], v[160:163], v[88:91]
	v_mfma_f32_16x16x32_bf16 v[84:87], v[128:131], v[168:171], v[84:87]
	v_mfma_f32_16x16x32_bf16 v[80:83], v[136:139], v[168:171], v[80:83]
	v_mfma_f32_16x16x32_bf16 v[76:79], v[128:131], v[192:195], v[76:79]
	v_mfma_f32_16x16x32_bf16 v[72:75], v[136:139], v[192:195], v[72:75]
	v_mfma_f32_16x16x32_bf16 v[68:71], v[128:131], v[200:203], v[68:71]
	v_mfma_f32_16x16x32_bf16 v[64:67], v[136:139], v[200:203], v[64:67]
	v_mfma_f32_16x16x32_bf16 v[92:95], v[132:135], v[164:167], v[92:95]
	v_mfma_f32_16x16x32_bf16 v[88:91], v[140:143], v[164:167], v[88:91]
	v_mfma_f32_16x16x32_bf16 v[84:87], v[132:135], v[188:191], v[84:87]
	v_mfma_f32_16x16x32_bf16 v[80:83], v[140:143], v[188:191], v[80:83]
	v_mfma_f32_16x16x32_bf16 v[76:79], v[132:135], v[196:199], v[76:79]
	v_mfma_f32_16x16x32_bf16 v[72:75], v[140:143], v[196:199], v[72:75]
	v_mfma_f32_16x16x32_bf16 v[68:71], v[132:135], v[204:207], v[68:71]
	v_mfma_f32_16x16x32_bf16 v[64:67], v[140:143], v[204:207], v[64:67]
	s_setprio 0
	s_setprio 1
	v_mfma_f32_16x16x32_bf16 v[28:31], v[144:147], v[160:163], v[28:31]
	v_mfma_f32_16x16x32_bf16 v[24:27], v[152:155], v[160:163], v[24:27]
	v_mfma_f32_16x16x32_bf16 v[20:23], v[144:147], v[168:171], v[20:23]
	v_mfma_f32_16x16x32_bf16 v[16:19], v[152:155], v[168:171], v[16:19]
	v_mfma_f32_16x16x32_bf16 v[12:15], v[144:147], v[192:195], v[12:15]
	v_mfma_f32_16x16x32_bf16 v[8:11], v[152:155], v[192:195], v[8:11]
	v_mfma_f32_16x16x32_bf16 v[4:7], v[144:147], v[200:203], v[4:7]
	v_mfma_f32_16x16x32_bf16 v[0:3], v[152:155], v[200:203], v[0:3]
	v_mfma_f32_16x16x32_bf16 v[28:31], v[148:151], v[164:167], v[28:31]
	v_mfma_f32_16x16x32_bf16 v[24:27], v[156:159], v[164:167], v[24:27]
	v_mfma_f32_16x16x32_bf16 v[20:23], v[148:151], v[188:191], v[20:23]
	v_mfma_f32_16x16x32_bf16 v[16:19], v[156:159], v[188:191], v[16:19]
	v_mfma_f32_16x16x32_bf16 v[12:15], v[148:151], v[196:199], v[12:15]
	v_mfma_f32_16x16x32_bf16 v[8:11], v[156:159], v[196:199], v[8:11]
	v_mfma_f32_16x16x32_bf16 v[4:7], v[148:151], v[204:207], v[4:7]
	v_mfma_f32_16x16x32_bf16 v[0:3], v[156:159], v[204:207], v[0:3]
	s_barrier
	s_setprio 0
	s_add_i32 s93, s93, 2
	s_add_u32 s91, s91, 0x100
	s_addc_u32 s92, s92, 0
	s_add_u32 s64, s64, 0x100
	s_addc_u32 s65, s65, 0
	s_cmpk_gt_u32 s93, 0x7d
	s_cbranch_scc0 .LBB0_754
	s_and_b64 vcc, exec, s[20:21]
	s_cbranch_vccz .LBB0_757
	s_barrier

; #define PG8_STAGE(bufoff, gbase, voff) do { _Pragma("unroll") for (int _i = 0; _i < 2; ++_i) \
;         __builtin_amdgcn_global_load_lds((const unsigned*)((const char*)(gbase) + (voff)[_i]), (PG8_LAS unsigned*)(lds + (bufoff) + ldsw + _i * 8192), 16, 0, 0); } while (0)
; #define PG8_LDA(dst, b, h) do { _Pragma("unroll") for (int m = 0; m < 4; ++m) _Pragma("unroll") for (int k = 0; k < 2; ++k) dst[m][k] = *(const PG8_LAS bf16x8*)(lds + PG8_SA(b, h) + aoff + m * 2048 + k * 1024); } while (0)
; #define PG8_LDB(dst, b, h) do { _Pragma("unroll") for (int n = 0; n < 2; ++n) _Pragma("unroll") for (int k = 0; k < 2; ++k) dst[n][k] = *(const PG8_LAS bf16x8*)(lds + PG8_SB(b, h) + boff + n * 2048 + k * 1024); } while (0)
; #define PG8_MMA(ai, bj, At, Bt) do { __builtin_amdgcn_s_setprio(1); _Pragma("unroll") for (int m = 0; m < 4; ++m) _Pragma("unroll") for (int n = 0; n < 2; ++n) _Pragma("unroll") for (int k = 0; k < 2; ++k) \
;         acc[ai][bj][m][n] = __builtin_amdgcn_mfma_f32_16x16x32_bf16(Bt[n][k], At[m][k], acc[ai][bj][m][n], 0, 0, 0); __builtin_amdgcn_s_setprio(0); } while (0)
; #define PG8_WAIT_V(n) asm volatile("s_waitcnt vmcnt(" #n ")" ::: "memory")
; #define PG8_WAIT_L(n) asm volatile("s_waitcnt lgkmcnt(" #n ")" ::: "memory")
; #define PG8_BAR __builtin_amdgcn_s_barrier()
; #define PG8_SCHED __builtin_amdgcn_sched_barrier(0)
; template <class Epi, class Sched, bool ALIGN_EPI = false, bool SP2 = false>
; __device__ __forceinline__ void gemm_phase(PG8_LAS unsigned char* lds, const Gemm g, const Sched& S, const Epi& E, const int wid) {
;     ...
;             PG8_LDB(B0, 0, 0); PG8_LDB(B1, 0, 1); PG8_SCHED; PG8_LDA(At, 0, 0); PG8_STAGE(PG8_SA(1, 1), a1 + hstep, voffA);
;             PG8_WAIT_V(8); PG8_WAIT_L(0); PG8_BAR; PG8_MMA(0, 0, At, B0); PG8_MMA(0, 1, At, B1); PG8_BAR; PG8_SCHED;
;             PG8_LDA(At, 0, 1); PG8_STAGE(PG8_SB(0, 0), b2, voffB); PG8_STAGE(PG8_SB(0, 1), b2 + hstep, voffB); PG8_STAGE(PG8_SA(0, 0), a2, voffA);
.LBB0_840:
	ds_read_b128 v[128:131], v167
	ds_read_b128 v[132:135], v167 offset:1024
	ds_read_b128 v[136:139], v167 offset:2048
	ds_read_b128 v[140:143], v167 offset:3072
	ds_read_b128 v[174:177], v169
	ds_read_b128 v[178:181], v169 offset:1024
	ds_read_b128 v[182:185], v169 offset:2048
	ds_read_b128 v[186:189], v169 offset:3072
	s_add_u32 s8, s16, 0xfff80080
	s_addc_u32 s9, s17, -1
	s_cmp_eq_u32 s75, 28
	s_cselect_b32 s59, s15, s9
	s_cselect_b32 s58, s51, s8
	s_cselect_b32 s57, s49, s74
	s_cselect_b32 s56, s72, s73
	v_lshl_add_u64 v[222:223], s[16:17], 0, v[154:155]
	s_add_i32 m0, s44, 0xc000
	ds_read_b128 v[190:193], v171
	ds_read_b128 v[194:197], v171 offset:1024
	ds_read_b128 v[198:201], v171 offset:2048
	ds_read_b128 v[202:205], v171 offset:3072
	ds_read_b128 v[206:209], v171 offset:4096
	ds_read_b128 v[210:213], v171 offset:5120
	ds_read_b128 v[214:217], v171 offset:6144
	ds_read_b128 v[218:221], v171 offset:7168
	global_load_lds_dwordx4 v[222:223], off
	v_lshl_add_u64 v[222:223], s[16:17], 0, v[152:153]
	s_add_i32 m0, s44, 0xe000
	s_nop 0
	global_load_lds_dwordx4 v[222:223], off
	s_waitcnt vmcnt(8)
	s_waitcnt lgkmcnt(0)
	s_setprio 1
	s_barrier
	v_mfma_f32_16x16x32_bf16 v[124:127], v[128:131], v[190:193], v[124:127]
	v_mfma_f32_16x16x32_bf16 v[120:123], v[136:139], v[190:193], v[120:123]
	v_mfma_f32_16x16x32_bf16 v[116:119], v[128:131], v[198:201], v[116:119]
	v_mfma_f32_16x16x32_bf16 v[112:115], v[136:139], v[198:201], v[112:115]
	v_mfma_f32_16x16x32_bf16 v[108:111], v[128:131], v[206:209], v[108:111]
	v_mfma_f32_16x16x32_bf16 v[104:107], v[136:139], v[206:209], v[104:107]
	v_mfma_f32_16x16x32_bf16 v[100:103], v[128:131], v[214:217], v[100:103]
	v_mfma_f32_16x16x32_bf16 v[96:99], v[136:139], v[214:217], v[96:99]
	v_mfma_f32_16x16x32_bf16 v[124:127], v[132:135], v[194:197], v[124:127]
	v_mfma_f32_16x16x32_bf16 v[120:123], v[140:143], v[194:197], v[120:123]
	v_mfma_f32_16x16x32_bf16 v[116:119], v[132:135], v[202:205], v[116:119]
	v_mfma_f32_16x16x32_bf16 v[112:115], v[140:143], v[202:205], v[112:115]
	v_mfma_f32_16x16x32_bf16 v[108:111], v[132:135], v[210:213], v[108:111]
	v_mfma_f32_16x16x32_bf16 v[104:107], v[140:143], v[210:213], v[104:107]
	v_mfma_f32_16x16x32_bf16 v[100:103], v[132:135], v[218:221], v[100:103]
	v_mfma_f32_16x16x32_bf16 v[96:99], v[140:143], v[218:221], v[96:99]
	s_setprio 0
	s_setprio 1
	v_mfma_f32_16x16x32_bf16 v[68:71], v[174:177], v[190:193], v[68:71]
	v_mfma_f32_16x16x32_bf16 v[60:63], v[182:185], v[190:193], v[60:63]
	v_mfma_f32_16x16x32_bf16 v[52:55], v[174:177], v[198:201], v[52:55]
	v_mfma_f32_16x16x32_bf16 v[48:51], v[182:185], v[198:201], v[48:51]
	v_mfma_f32_16x16x32_bf16 v[44:47], v[174:177], v[206:209], v[44:47]
	v_mfma_f32_16x16x32_bf16 v[40:43], v[182:185], v[206:209], v[40:43]
	v_mfma_f32_16x16x32_bf16 v[36:39], v[174:177], v[214:217], v[36:39]
	v_mfma_f32_16x16x32_bf16 v[32:35], v[182:185], v[214:217], v[32:35]
	v_mfma_f32_16x16x32_bf16 v[68:71], v[178:181], v[194:197], v[68:71]
	v_mfma_f32_16x16x32_bf16 v[60:63], v[186:189], v[194:197], v[60:63]
	v_mfma_f32_16x16x32_bf16 v[52:55], v[178:181], v[202:205], v[52:55]
	v_mfma_f32_16x16x32_bf16 v[48:51], v[186:189], v[202:205], v[48:51]
	v_mfma_f32_16x16x32_bf16 v[44:47], v[178:181], v[210:213], v[44:47]
	v_mfma_f32_16x16x32_bf16 v[40:43], v[186:189], v[210:213], v[40:43]
	v_mfma_f32_16x16x32_bf16 v[36:39], v[178:181], v[218:221], v[36:39]
	v_mfma_f32_16x16x32_bf16 v[32:35], v[186:189], v[218:221], v[32:35]
	s_barrier
	s_setprio 0
	s_add_i32 s8, s66, s3
	v_lshl_add_u64 v[222:223], s[56:57], 0, v[148:149]
	s_mov_b32 m0, s8
	ds_read_b128 v[190:193], v171 offset:16384
	ds_read_b128 v[194:197], v171 offset:17408
	ds_read_b128 v[198:201], v171 offset:18432
	ds_read_b128 v[202:205], v171 offset:19456
	ds_read_b128 v[206:209], v171 offset:20480
	ds_read_b128 v[210:213], v171 offset:21504
	ds_read_b128 v[214:217], v171 offset:22528
	ds_read_b128 v[218:221], v171 offset:23552
	global_load_lds_dwordx4 v[222:223], off
	s_add_i32 m0, s8, 0x2000
	s_add_u32 s76, s56, 0x80000
	v_lshl_add_u64 v[224:225], s[56:57], 0, v[144:145]
	s_addc_u32 s77, s57, 0
	s_add_i32 s8, s67, s3
	global_load_lds_dwordx4 v[224:225], off
	v_lshl_add_u64 v[226:227], s[76:77], 0, v[148:149]
	s_mov_b32 m0, s8
	v_lshl_add_u64 v[228:229], s[58:59], 0, v[146:147]
	global_load_lds_dwordx4 v[226:227], off
	v_lshl_add_u64 v[226:227], s[76:77], 0, v[144:145]
	s_add_i32 m0, s8, 0x2000
	s_nop 0
	global_load_lds_dwordx4 v[226:227], off
	v_lshl_add_u64 v[226:227], s[58:59], 0, v[150:151]
	s_mov_b32 m0, s44
	s_nop 0
	global_load_lds_dwordx4 v[226:227], off
	s_mov_b32 m0, s45
	s_nop 0
	global_load_lds_dwordx4 v[228:229], off
	s_waitcnt vmcnt(8)
	s_waitcnt lgkmcnt(0)
	s_setprio 1
	s_barrier
; #define PG8_STAGE(bufoff, gbase, voff) do { _Pragma("unroll") for (int _i = 0; _i < 2; ++_i) \
;         __builtin_amdgcn_global_load_lds((const unsigned*)((const char*)(gbase) + (voff)[_i]), (PG8_LAS unsigned*)(lds + (bufoff) + ldsw + _i * 8192), 16, 0, 0); } while (0)
; #define PG8_LDA(dst, b, h) do { _Pragma("unroll") for (int m = 0; m < 4; ++m) _Pragma("unroll") for (int k = 0; k < 2; ++k) dst[m][k] = *(const PG8_LAS bf16x8*)(lds + PG8_SA(b, h) + aoff + m * 2048 + k * 1024); } while (0)
; #define PG8_LDB(dst, b, h) do { _Pragma("unroll") for (int n = 0; n < 2; ++n) _Pragma("unroll") for (int k = 0; k < 2; ++k) dst[n][k] = *(const PG8_LAS bf16x8*)(lds + PG8_SB(b, h) + boff + n * 2048 + k * 1024); } while (0)
; #define PG8_MMA(ai, bj, At, Bt) do { __builtin_amdgcn_s_setprio(1); _Pragma("unroll") for (int m = 0; m < 4; ++m) _Pragma("unroll") for (int n = 0; n < 2; ++n) _Pragma("unroll") for (int k = 0; k < 2; ++k) \
;         acc[ai][bj][m][n] = __builtin_amdgcn_mfma_f32_16x16x32_bf16(Bt[n][k], At[m][k], acc[ai][bj][m][n], 0, 0, 0); __builtin_amdgcn_s_setprio(0); } while (0)
; #define PG8_WAIT_V(n) asm volatile("s_waitcnt vmcnt(" #n ")" ::: "memory")
; #define PG8_WAIT_L(n) asm volatile("s_waitcnt lgkmcnt(" #n ")" ::: "memory")
; #define PG8_BAR __builtin_amdgcn_s_barrier()
; #define PG8_SCHED __builtin_amdgcn_sched_barrier(0)
; template <class Epi, class Sched, bool ALIGN_EPI = false, bool SP2 = false>
; __device__ __forceinline__ void gemm_phase(PG8_LAS unsigned char* lds, const Gemm g, const Sched& S, const Epi& E, const int wid) {
;     ...
;             PG8_WAIT_V(8); PG8_WAIT_L(0); PG8_BAR; PG8_MMA(1, 0, At, B0); PG8_MMA(1, 1, At, B1); PG8_BAR; PG8_SCHED;
;             PG8_LDB(B0, 1, 0); PG8_LDB(B1, 1, 1); PG8_SCHED; PG8_LDA(At, 1, 0); PG8_STAGE(PG8_SA(0, 1), a2 + hstep, voffA);
;             PG8_WAIT_V(8); PG8_WAIT_L(0); PG8_BAR; PG8_MMA(0, 0, At, B0); PG8_MMA(0, 1, At, B1); PG8_BAR; PG8_SCHED;
	v_mfma_f32_16x16x32_bf16 v[92:95], v[128:131], v[190:193], v[92:95]
	v_mfma_f32_16x16x32_bf16 v[88:91], v[136:139], v[190:193], v[88:91]
	v_mfma_f32_16x16x32_bf16 v[84:87], v[128:131], v[198:201], v[84:87]
	v_mfma_f32_16x16x32_bf16 v[80:83], v[136:139], v[198:201], v[80:83]
	v_mfma_f32_16x16x32_bf16 v[76:79], v[128:131], v[206:209], v[76:79]
	v_mfma_f32_16x16x32_bf16 v[72:75], v[136:139], v[206:209], v[72:75]
	v_mfma_f32_16x16x32_bf16 v[64:67], v[128:131], v[214:217], v[64:67]
	v_mfma_f32_16x16x32_bf16 v[56:59], v[136:139], v[214:217], v[56:59]
	v_mfma_f32_16x16x32_bf16 v[92:95], v[132:135], v[194:197], v[92:95]
	v_mfma_f32_16x16x32_bf16 v[88:91], v[140:143], v[194:197], v[88:91]
	v_mfma_f32_16x16x32_bf16 v[84:87], v[132:135], v[202:205], v[84:87]
	v_mfma_f32_16x16x32_bf16 v[80:83], v[140:143], v[202:205], v[80:83]
	v_mfma_f32_16x16x32_bf16 v[76:79], v[132:135], v[210:213], v[76:79]
	v_mfma_f32_16x16x32_bf16 v[72:75], v[140:143], v[210:213], v[72:75]
	v_mfma_f32_16x16x32_bf16 v[64:67], v[132:135], v[218:221], v[64:67]
	v_mfma_f32_16x16x32_bf16 v[56:59], v[140:143], v[218:221], v[56:59]
	s_setprio 0
	s_setprio 1
	v_mfma_f32_16x16x32_bf16 v[28:31], v[174:177], v[190:193], v[28:31]
	v_mfma_f32_16x16x32_bf16 v[24:27], v[182:185], v[190:193], v[24:27]
	v_mfma_f32_16x16x32_bf16 v[20:23], v[174:177], v[198:201], v[20:23]
	v_mfma_f32_16x16x32_bf16 v[16:19], v[182:185], v[198:201], v[16:19]
	v_mfma_f32_16x16x32_bf16 v[12:15], v[174:177], v[206:209], v[12:15]
	v_mfma_f32_16x16x32_bf16 v[8:11], v[182:185], v[206:209], v[8:11]
	v_mfma_f32_16x16x32_bf16 v[4:7], v[174:177], v[214:217], v[4:7]
	v_mfma_f32_16x16x32_bf16 v[0:3], v[182:185], v[214:217], v[0:3]
	v_mfma_f32_16x16x32_bf16 v[28:31], v[178:181], v[194:197], v[28:31]
	v_mfma_f32_16x16x32_bf16 v[24:27], v[186:189], v[194:197], v[24:27]
	v_mfma_f32_16x16x32_bf16 v[20:23], v[178:181], v[202:205], v[20:23]
	v_mfma_f32_16x16x32_bf16 v[16:19], v[186:189], v[202:205], v[16:19]
	v_mfma_f32_16x16x32_bf16 v[12:15], v[178:181], v[210:213], v[12:15]
	v_mfma_f32_16x16x32_bf16 v[8:11], v[186:189], v[210:213], v[8:11]
	v_mfma_f32_16x16x32_bf16 v[4:7], v[178:181], v[218:221], v[4:7]
	v_mfma_f32_16x16x32_bf16 v[0:3], v[186:189], v[218:221], v[0:3]
	s_barrier
	s_setprio 0
	s_add_i32 s8, 0, 0x18000
	s_add_i32 s9, 0, 0x1c000
	v_add_u32_e32 v140, s8, v163
	v_add_u32_e32 v160, s9, v163
	ds_read_b128 v[128:131], v140
	ds_read_b128 v[132:135], v140 offset:1024
	ds_read_b128 v[136:139], v140 offset:2048
	ds_read_b128 v[140:143], v140 offset:3072
	ds_read_b128 v[174:177], v160
	ds_read_b128 v[178:181], v160 offset:1024
	ds_read_b128 v[182:185], v160 offset:2048
	ds_read_b128 v[186:189], v160 offset:3072
	s_add_u32 s58, s58, 0x80000
	s_addc_u32 s59, s59, 0
	s_mov_b32 m0, s60
	v_lshl_add_u64 v[230:231], s[58:59], 0, v[150:151]
	ds_read_b128 v[190:193], v171 offset:32768
	ds_read_b128 v[194:197], v171 offset:33792
	ds_read_b128 v[198:201], v171 offset:34816
	ds_read_b128 v[202:205], v171 offset:35840
	ds_read_b128 v[206:209], v171 offset:36864
	ds_read_b128 v[210:213], v171 offset:37888
	ds_read_b128 v[214:217], v171 offset:38912
	ds_read_b128 v[218:221], v171 offset:39936
	global_load_lds_dwordx4 v[230:231], off
	v_lshl_add_u64 v[230:231], s[58:59], 0, v[146:147]
	s_mov_b32 m0, s61
	s_nop 0
	global_load_lds_dwordx4 v[230:231], off
	s_waitcnt vmcnt(8)
	s_waitcnt lgkmcnt(0)
	s_setprio 1
	s_barrier
	v_mfma_f32_16x16x32_bf16 v[124:127], v[128:131], v[190:193], v[124:127]
	v_mfma_f32_16x16x32_bf16 v[120:123], v[136:139], v[190:193], v[120:123]
	v_mfma_f32_16x16x32_bf16 v[116:119], v[128:131], v[198:201], v[116:119]
	v_mfma_f32_16x16x32_bf16 v[112:115], v[136:139], v[198:201], v[112:115]
	v_mfma_f32_16x16x32_bf16 v[108:111], v[128:131], v[206:209], v[108:111]
	v_mfma_f32_16x16x32_bf16 v[104:107], v[136:139], v[206:209], v[104:107]
	v_mfma_f32_16x16x32_bf16 v[100:103], v[128:131], v[214:217], v[100:103]
	v_mfma_f32_16x16x32_bf16 v[96:99], v[136:139], v[214:217], v[96:99]
	v_mfma_f32_16x16x32_bf16 v[124:127], v[132:135], v[194:197], v[124:127]
	v_mfma_f32_16x16x32_bf16 v[120:123], v[140:143], v[194:197], v[120:123]
	v_mfma_f32_16x16x32_bf16 v[116:119], v[132:135], v[202:205], v[116:119]
	v_mfma_f32_16x16x32_bf16 v[112:115], v[140:143], v[202:205], v[112:115]
	v_mfma_f32_16x16x32_bf16 v[108:111], v[132:135], v[210:213], v[108:111]
	v_mfma_f32_16x16x32_bf16 v[104:107], v[140:143], v[210:213], v[104:107]
	v_mfma_f32_16x16x32_bf16 v[100:103], v[132:135], v[218:221], v[100:103]
	v_mfma_f32_16x16x32_bf16 v[96:99], v[140:143], v[218:221], v[96:99]
	s_setprio 0
	s_setprio 1
	v_mfma_f32_16x16x32_bf16 v[68:71], v[174:177], v[190:193], v[68:71]
	v_mfma_f32_16x16x32_bf16 v[60:63], v[182:185], v[190:193], v[60:63]
	v_mfma_f32_16x16x32_bf16 v[52:55], v[174:177], v[198:201], v[52:55]
	v_mfma_f32_16x16x32_bf16 v[48:51], v[182:185], v[198:201], v[48:51]
	v_mfma_f32_16x16x32_bf16 v[44:47], v[174:177], v[206:209], v[44:47]
	v_mfma_f32_16x16x32_bf16 v[40:43], v[182:185], v[206:209], v[40:43]
	v_mfma_f32_16x16x32_bf16 v[36:39], v[174:177], v[214:217], v[36:39]
	v_mfma_f32_16x16x32_bf16 v[32:35], v[182:185], v[214:217], v[32:35]
	v_mfma_f32_16x16x32_bf16 v[68:71], v[178:181], v[194:197], v[68:71]
	v_mfma_f32_16x16x32_bf16 v[60:63], v[186:189], v[194:197], v[60:63]
	v_mfma_f32_16x16x32_bf16 v[52:55], v[178:181], v[202:205], v[52:55]
	v_mfma_f32_16x16x32_bf16 v[48:51], v[186:189], v[202:205], v[48:51]
	v_mfma_f32_16x16x32_bf16 v[44:47], v[178:181], v[210:213], v[44:47]
	v_mfma_f32_16x16x32_bf16 v[40:43], v[186:189], v[210:213], v[40:43]
	v_mfma_f32_16x16x32_bf16 v[36:39], v[178:181], v[218:221], v[36:39]
	v_mfma_f32_16x16x32_bf16 v[32:35], v[186:189], v[218:221], v[32:35]
	s_barrier
; #define PG8_STAGE(bufoff, gbase, voff) do { _Pragma("unroll") for (int _i = 0; _i < 2; ++_i) \
;         __builtin_amdgcn_global_load_lds((const unsigned*)((const char*)(gbase) + (voff)[_i]), (PG8_LAS unsigned*)(lds + (bufoff) + ldsw + _i * 8192), 16, 0, 0); } while (0)
; #define PG8_LDA(dst, b, h) do { _Pragma("unroll") for (int m = 0; m < 4; ++m) _Pragma("unroll") for (int k = 0; k < 2; ++k) dst[m][k] = *(const PG8_LAS bf16x8*)(lds + PG8_SA(b, h) + aoff + m * 2048 + k * 1024); } while (0)
; #define PG8_MMA(ai, bj, At, Bt) do { __builtin_amdgcn_s_setprio(1); _Pragma("unroll") for (int m = 0; m < 4; ++m) _Pragma("unroll") for (int n = 0; n < 2; ++n) _Pragma("unroll") for (int k = 0; k < 2; ++k) \
;         acc[ai][bj][m][n] = __builtin_amdgcn_mfma_f32_16x16x32_bf16(Bt[n][k], At[m][k], acc[ai][bj][m][n], 0, 0, 0); __builtin_amdgcn_s_setprio(0); } while (0)
; #define PG8_WAIT_V(n) asm volatile("s_waitcnt vmcnt(" #n ")" ::: "memory")
; #define PG8_WAIT_L(n) asm volatile("s_waitcnt lgkmcnt(" #n ")" ::: "memory")
; #define PG8_BAR __builtin_amdgcn_s_barrier()
; #define PG8_SCHED __builtin_amdgcn_sched_barrier(0)
; template <class Epi, class Sched, bool ALIGN_EPI = false, bool SP2 = false>
; __device__ __forceinline__ void gemm_phase(PG8_LAS unsigned char* lds, const Gemm g, const Sched& S, const Epi& E, const int wid) {
;     ...
;             PG8_LDA(At, 1, 1); PG8_STAGE(PG8_SB(1, 0), b3, voffB); PG8_STAGE(PG8_SB(1, 1), b3 + hstep, voffB); PG8_STAGE(PG8_SA(1, 0), a3, voffA);
;             PG8_WAIT_V(8); PG8_WAIT_L(0); PG8_BAR; PG8_MMA(1, 0, At, B0); PG8_MMA(1, 1, At, B1); PG8_BAR; PG8_SCHED;
;     ...
;         if constexpr (ALIGN_EPI) { if (wr == 0) PG8_BAR; }
	s_setprio 0
	s_add_i32 s8, s8, s3
	v_lshl_add_u64 v[222:223], v[222:223], 0, s[28:29]
	s_mov_b32 m0, s8
	ds_read_b128 v[190:193], v171 offset:49152
	ds_read_b128 v[194:197], v171 offset:50176
	ds_read_b128 v[198:201], v171 offset:51200
	ds_read_b128 v[202:205], v171 offset:52224
	ds_read_b128 v[206:209], v171 offset:53248
	ds_read_b128 v[210:213], v171 offset:54272
	ds_read_b128 v[214:217], v171 offset:55296
	ds_read_b128 v[218:221], v171 offset:56320
	global_load_lds_dwordx4 v[222:223], off
	s_add_i32 m0, s8, 0x2000
	s_add_u32 s56, s56, 0x80080
	v_lshl_add_u64 v[222:223], v[224:225], 0, s[28:29]
	s_addc_u32 s57, s57, 0
	s_add_i32 s8, s9, s3
	global_load_lds_dwordx4 v[222:223], off
	v_lshl_add_u64 v[222:223], s[56:57], 0, v[148:149]
	s_mov_b32 m0, s8
	s_nop 0
	global_load_lds_dwordx4 v[222:223], off
	v_lshl_add_u64 v[222:223], s[56:57], 0, v[144:145]
	s_add_i32 m0, s8, 0x2000
	s_nop 0
	global_load_lds_dwordx4 v[222:223], off
	v_lshl_add_u64 v[222:223], v[226:227], 0, s[28:29]
	s_mov_b32 m0, s63
	s_nop 0
	global_load_lds_dwordx4 v[222:223], off
	v_lshl_add_u64 v[222:223], v[228:229], 0, s[28:29]
	s_mov_b32 m0, s64
	s_nop 0
	global_load_lds_dwordx4 v[222:223], off
	s_waitcnt vmcnt(8)
	s_waitcnt lgkmcnt(0)
	s_setprio 1
	s_barrier
	v_mfma_f32_16x16x32_bf16 v[92:95], v[128:131], v[190:193], v[92:95]
	v_mfma_f32_16x16x32_bf16 v[88:91], v[136:139], v[190:193], v[88:91]
	v_mfma_f32_16x16x32_bf16 v[84:87], v[128:131], v[198:201], v[84:87]
	v_mfma_f32_16x16x32_bf16 v[80:83], v[136:139], v[198:201], v[80:83]
	v_mfma_f32_16x16x32_bf16 v[76:79], v[128:131], v[206:209], v[76:79]
	v_mfma_f32_16x16x32_bf16 v[72:75], v[136:139], v[206:209], v[72:75]
	v_mfma_f32_16x16x32_bf16 v[64:67], v[128:131], v[214:217], v[64:67]
	v_mfma_f32_16x16x32_bf16 v[56:59], v[136:139], v[214:217], v[56:59]
	v_mfma_f32_16x16x32_bf16 v[92:95], v[132:135], v[194:197], v[92:95]
	v_mfma_f32_16x16x32_bf16 v[88:91], v[140:143], v[194:197], v[88:91]
	v_mfma_f32_16x16x32_bf16 v[84:87], v[132:135], v[202:205], v[84:87]
	v_mfma_f32_16x16x32_bf16 v[80:83], v[140:143], v[202:205], v[80:83]
	v_mfma_f32_16x16x32_bf16 v[76:79], v[132:135], v[210:213], v[76:79]
	v_mfma_f32_16x16x32_bf16 v[72:75], v[140:143], v[210:213], v[72:75]
	v_mfma_f32_16x16x32_bf16 v[64:67], v[132:135], v[218:221], v[64:67]
	v_mfma_f32_16x16x32_bf16 v[56:59], v[140:143], v[218:221], v[56:59]
	s_setprio 0
	s_setprio 1
	v_mfma_f32_16x16x32_bf16 v[28:31], v[174:177], v[190:193], v[28:31]
	v_mfma_f32_16x16x32_bf16 v[24:27], v[182:185], v[190:193], v[24:27]
	v_mfma_f32_16x16x32_bf16 v[20:23], v[174:177], v[198:201], v[20:23]
	v_mfma_f32_16x16x32_bf16 v[16:19], v[182:185], v[198:201], v[16:19]
	v_mfma_f32_16x16x32_bf16 v[12:15], v[174:177], v[206:209], v[12:15]
	v_mfma_f32_16x16x32_bf16 v[8:11], v[182:185], v[206:209], v[8:11]
	v_mfma_f32_16x16x32_bf16 v[4:7], v[174:177], v[214:217], v[4:7]
	v_mfma_f32_16x16x32_bf16 v[0:3], v[182:185], v[214:217], v[0:3]
	v_mfma_f32_16x16x32_bf16 v[28:31], v[178:181], v[194:197], v[28:31]
	v_mfma_f32_16x16x32_bf16 v[24:27], v[186:189], v[194:197], v[24:27]
	v_mfma_f32_16x16x32_bf16 v[20:23], v[178:181], v[202:205], v[20:23]
	v_mfma_f32_16x16x32_bf16 v[16:19], v[186:189], v[202:205], v[16:19]
	v_mfma_f32_16x16x32_bf16 v[12:15], v[178:181], v[210:213], v[12:15]
	v_mfma_f32_16x16x32_bf16 v[8:11], v[186:189], v[210:213], v[8:11]
	v_mfma_f32_16x16x32_bf16 v[4:7], v[178:181], v[218:221], v[4:7]
	v_mfma_f32_16x16x32_bf16 v[0:3], v[186:189], v[218:221], v[0:3]
	s_barrier
	s_setprio 0
	s_add_i32 s75, s75, 2
	s_add_u32 s73, s73, 0x100
	s_addc_u32 s74, s74, 0
	s_add_u32 s16, s16, 0x100
	s_addc_u32 s17, s17, 0
	s_cmp_lt_u32 s75, 30
	s_cbranch_scc1 .LBB0_840
	s_andn2_b64 vcc, exec, s[20:21]
	s_cbranch_vccnz .LBB0_843
	s_barrier

; #define PG8_STAGE(bufoff, gbase, voff) do { _Pragma("unroll") for (int _i = 0; _i < 2; ++_i) \
;         __builtin_amdgcn_global_load_lds((const unsigned*)((const char*)(gbase) + (voff)[_i]), (PG8_LAS unsigned*)(lds + (bufoff) + ldsw + _i * 8192), 16, 0, 0); } while (0)
; #define PG8_LDA(dst, b, h) do { _Pragma("unroll") for (int m = 0; m < 4; ++m) _Pragma("unroll") for (int k = 0; k < 2; ++k) dst[m][k] = *(const PG8_LAS bf16x8*)(lds + PG8_SA(b, h) + aoff + m * 2048 + k * 1024); } while (0)
; #define PG8_LDB(dst, b, h) do { _Pragma("unroll") for (int n = 0; n < 2; ++n) _Pragma("unroll") for (int k = 0; k < 2; ++k) dst[n][k] = *(const PG8_LAS bf16x8*)(lds + PG8_SB(b, h) + boff + n * 2048 + k * 1024); } while (0)
; #define PG8_MMA(ai, bj, At, Bt) do { __builtin_amdgcn_s_setprio(1); _Pragma("unroll") for (int m = 0; m < 4; ++m) _Pragma("unroll") for (int n = 0; n < 2; ++n) _Pragma("unroll") for (int k = 0; k < 2; ++k) \
;         acc[ai][bj][m][n] = __builtin_amdgcn_mfma_f32_16x16x32_bf16(Bt[n][k], At[m][k], acc[ai][bj][m][n], 0, 0, 0); __builtin_amdgcn_s_setprio(0); } while (0)
; #define PG8_WAIT_V(n) asm volatile("s_waitcnt vmcnt(" #n ")" ::: "memory")
; #define PG8_WAIT_L(n) asm volatile("s_waitcnt lgkmcnt(" #n ")" ::: "memory")
; #define PG8_BAR __builtin_amdgcn_s_barrier()
; #define PG8_SCHED __builtin_amdgcn_sched_barrier(0)
; template <class Epi, class Sched, bool ALIGN_EPI = false, bool SP2 = false>
; __device__ __forceinline__ void gemm_phase(PG8_LAS unsigned char* lds, const Gemm g, const Sched& S, const Epi& E, const int wid) {
;     ...
;             PG8_LDB(B0, 0, 0); PG8_LDB(B1, 0, 1); PG8_SCHED; PG8_LDA(At, 0, 0); PG8_STAGE(PG8_SA(1, 1), a1 + hstep, voffA);
;             PG8_WAIT_V(8); PG8_WAIT_L(0); PG8_BAR; PG8_MMA(0, 0, At, B0); PG8_MMA(0, 1, At, B1); PG8_BAR; PG8_SCHED;
;             PG8_LDA(At, 0, 1); PG8_STAGE(PG8_SB(0, 0), b2, voffB); PG8_STAGE(PG8_SB(0, 1), b2 + hstep, voffB); PG8_STAGE(PG8_SA(0, 0), a2, voffA);
.LBB0_912:
	ds_read_b128 v[128:131], v239
	ds_read_b128 v[132:135], v239 offset:1024
	ds_read_b128 v[136:139], v239 offset:2048
	ds_read_b128 v[140:143], v239 offset:3072
	ds_read_b128 v[144:147], v240
	ds_read_b128 v[148:151], v240 offset:1024
	ds_read_b128 v[152:155], v240 offset:2048
	ds_read_b128 v[156:159], v240 offset:3072
	s_add_u32 s8, s64, 0xffe00080
	s_addc_u32 s9, s65, -1
	s_cmpk_eq_i32 s93, 0x7c
	s_cselect_b32 s69, s17, s9
	s_cselect_b32 s68, s57, s8
	s_cselect_b32 s67, s55, s92
	s_cselect_b32 s66, s90, s91
	v_lshl_add_u64 v[208:209], s[64:65], 0, v[182:183]
	s_add_i32 m0, s41, 0xc000
	ds_read_b128 v[160:163], v241
	ds_read_b128 v[164:167], v241 offset:1024
	ds_read_b128 v[168:171], v241 offset:2048
	ds_read_b128 v[188:191], v241 offset:3072
	ds_read_b128 v[192:195], v241 offset:4096
	ds_read_b128 v[196:199], v241 offset:5120
	ds_read_b128 v[200:203], v241 offset:6144
	ds_read_b128 v[204:207], v241 offset:7168
	global_load_lds_dwordx4 v[208:209], off
	v_lshl_add_u64 v[208:209], s[64:65], 0, v[180:181]
	s_add_i32 m0, s41, 0xe000
	s_nop 0
	global_load_lds_dwordx4 v[208:209], off
	s_waitcnt vmcnt(8)
	s_waitcnt lgkmcnt(0)
	s_setprio 1
	s_barrier
	v_mfma_f32_16x16x32_bf16 v[124:127], v[128:131], v[160:163], v[124:127]
	v_mfma_f32_16x16x32_bf16 v[120:123], v[136:139], v[160:163], v[120:123]
	v_mfma_f32_16x16x32_bf16 v[116:119], v[128:131], v[168:171], v[116:119]
	v_mfma_f32_16x16x32_bf16 v[112:115], v[136:139], v[168:171], v[112:115]
	v_mfma_f32_16x16x32_bf16 v[108:111], v[128:131], v[192:195], v[108:111]
	v_mfma_f32_16x16x32_bf16 v[104:107], v[136:139], v[192:195], v[104:107]
	v_mfma_f32_16x16x32_bf16 v[100:103], v[128:131], v[200:203], v[100:103]
	v_mfma_f32_16x16x32_bf16 v[96:99], v[136:139], v[200:203], v[96:99]
	v_mfma_f32_16x16x32_bf16 v[124:127], v[132:135], v[164:167], v[124:127]
	v_mfma_f32_16x16x32_bf16 v[120:123], v[140:143], v[164:167], v[120:123]
	v_mfma_f32_16x16x32_bf16 v[116:119], v[132:135], v[188:191], v[116:119]
	v_mfma_f32_16x16x32_bf16 v[112:115], v[140:143], v[188:191], v[112:115]
	v_mfma_f32_16x16x32_bf16 v[108:111], v[132:135], v[196:199], v[108:111]
	v_mfma_f32_16x16x32_bf16 v[104:107], v[140:143], v[196:199], v[104:107]
	v_mfma_f32_16x16x32_bf16 v[100:103], v[132:135], v[204:207], v[100:103]
	v_mfma_f32_16x16x32_bf16 v[96:99], v[140:143], v[204:207], v[96:99]
	s_setprio 0
	s_setprio 1
	v_mfma_f32_16x16x32_bf16 v[60:63], v[144:147], v[160:163], v[60:63]
	v_mfma_f32_16x16x32_bf16 v[56:59], v[152:155], v[160:163], v[56:59]
	v_mfma_f32_16x16x32_bf16 v[52:55], v[144:147], v[168:171], v[52:55]
	v_mfma_f32_16x16x32_bf16 v[48:51], v[152:155], v[168:171], v[48:51]
	v_mfma_f32_16x16x32_bf16 v[44:47], v[144:147], v[192:195], v[44:47]
	v_mfma_f32_16x16x32_bf16 v[40:43], v[152:155], v[192:195], v[40:43]
	v_mfma_f32_16x16x32_bf16 v[36:39], v[144:147], v[200:203], v[36:39]
	v_mfma_f32_16x16x32_bf16 v[32:35], v[152:155], v[200:203], v[32:35]
	v_mfma_f32_16x16x32_bf16 v[60:63], v[148:151], v[164:167], v[60:63]
	v_mfma_f32_16x16x32_bf16 v[56:59], v[156:159], v[164:167], v[56:59]
	v_mfma_f32_16x16x32_bf16 v[52:55], v[148:151], v[188:191], v[52:55]
	v_mfma_f32_16x16x32_bf16 v[48:51], v[156:159], v[188:191], v[48:51]
	v_mfma_f32_16x16x32_bf16 v[44:47], v[148:151], v[196:199], v[44:47]
	v_mfma_f32_16x16x32_bf16 v[40:43], v[156:159], v[196:199], v[40:43]
	v_mfma_f32_16x16x32_bf16 v[36:39], v[148:151], v[204:207], v[36:39]
	v_mfma_f32_16x16x32_bf16 v[32:35], v[156:159], v[204:207], v[32:35]
	s_barrier
	s_setprio 0
	s_add_i32 s8, s73, s3
	v_lshl_add_u64 v[208:209], s[66:67], 0, v[174:175]
	s_mov_b32 m0, s8
	ds_read_b128 v[160:163], v241 offset:16384
	ds_read_b128 v[164:167], v241 offset:17408
	ds_read_b128 v[168:171], v241 offset:18432
	ds_read_b128 v[188:191], v241 offset:19456
	ds_read_b128 v[192:195], v241 offset:20480
	ds_read_b128 v[196:199], v241 offset:21504
	ds_read_b128 v[200:203], v241 offset:22528
	ds_read_b128 v[204:207], v241 offset:23552
	global_load_lds_dwordx4 v[208:209], off
	s_add_i32 m0, s8, 0x2000
	s_add_u32 s94, s66, 0x200000
	v_lshl_add_u64 v[210:211], s[66:67], 0, v[178:179]
	s_addc_u32 s95, s67, 0
	s_add_i32 s8, s74, s3
	global_load_lds_dwordx4 v[210:211], off
	v_lshl_add_u64 v[212:213], s[94:95], 0, v[174:175]
	s_mov_b32 m0, s8
	v_lshl_add_u64 v[216:217], s[68:69], 0, v[176:177]
	global_load_lds_dwordx4 v[212:213], off
	v_lshl_add_u64 v[212:213], s[94:95], 0, v[178:179]
	s_add_i32 m0, s8, 0x2000
	s_nop 0
	global_load_lds_dwordx4 v[212:213], off
	v_lshl_add_u64 v[212:213], s[68:69], 0, v[172:173]
	s_mov_b32 m0, s41
	s_nop 0
	global_load_lds_dwordx4 v[212:213], off
	s_mov_b32 m0, s44
	s_nop 0
	global_load_lds_dwordx4 v[216:217], off
	s_waitcnt vmcnt(8)
	s_waitcnt lgkmcnt(0)
	s_setprio 1
	s_barrier
; #define PG8_STAGE(bufoff, gbase, voff) do { _Pragma("unroll") for (int _i = 0; _i < 2; ++_i) \
;         __builtin_amdgcn_global_load_lds((const unsigned*)((const char*)(gbase) + (voff)[_i]), (PG8_LAS unsigned*)(lds + (bufoff) + ldsw + _i * 8192), 16, 0, 0); } while (0)
; #define PG8_LDA(dst, b, h) do { _Pragma("unroll") for (int m = 0; m < 4; ++m) _Pragma("unroll") for (int k = 0; k < 2; ++k) dst[m][k] = *(const PG8_LAS bf16x8*)(lds + PG8_SA(b, h) + aoff + m * 2048 + k * 1024); } while (0)
; #define PG8_LDB(dst, b, h) do { _Pragma("unroll") for (int n = 0; n < 2; ++n) _Pragma("unroll") for (int k = 0; k < 2; ++k) dst[n][k] = *(const PG8_LAS bf16x8*)(lds + PG8_SB(b, h) + boff + n * 2048 + k * 1024); } while (0)
; #define PG8_MMA(ai, bj, At, Bt) do { __builtin_amdgcn_s_setprio(1); _Pragma("unroll") for (int m = 0; m < 4; ++m) _Pragma("unroll") for (int n = 0; n < 2; ++n) _Pragma("unroll") for (int k = 0; k < 2; ++k) \
;         acc[ai][bj][m][n] = __builtin_amdgcn_mfma_f32_16x16x32_bf16(Bt[n][k], At[m][k], acc[ai][bj][m][n], 0, 0, 0); __builtin_amdgcn_s_setprio(0); } while (0)
; #define PG8_WAIT_V(n) asm volatile("s_waitcnt vmcnt(" #n ")" ::: "memory")
; #define PG8_WAIT_L(n) asm volatile("s_waitcnt lgkmcnt(" #n ")" ::: "memory")
; #define PG8_BAR __builtin_amdgcn_s_barrier()
; #define PG8_SCHED __builtin_amdgcn_sched_barrier(0)
; template <class Epi, class Sched, bool ALIGN_EPI = false, bool SP2 = false>
; __device__ __forceinline__ void gemm_phase(PG8_LAS unsigned char* lds, const Gemm g, const Sched& S, const Epi& E, const int wid) {
;     ...
;             PG8_WAIT_V(8); PG8_WAIT_L(0); PG8_BAR; PG8_MMA(1, 0, At, B0); PG8_MMA(1, 1, At, B1); PG8_BAR; PG8_SCHED;
;             PG8_LDB(B0, 1, 0); PG8_LDB(B1, 1, 1); PG8_SCHED; PG8_LDA(At, 1, 0); PG8_STAGE(PG8_SA(0, 1), a2 + hstep, voffA);
;             PG8_WAIT_V(8); PG8_WAIT_L(0); PG8_BAR; PG8_MMA(0, 0, At, B0); PG8_MMA(0, 1, At, B1); PG8_BAR; PG8_SCHED;
	v_mfma_f32_16x16x32_bf16 v[92:95], v[128:131], v[160:163], v[92:95]
	v_mfma_f32_16x16x32_bf16 v[88:91], v[136:139], v[160:163], v[88:91]
	v_mfma_f32_16x16x32_bf16 v[84:87], v[128:131], v[168:171], v[84:87]
	v_mfma_f32_16x16x32_bf16 v[80:83], v[136:139], v[168:171], v[80:83]
	v_mfma_f32_16x16x32_bf16 v[76:79], v[128:131], v[192:195], v[76:79]
	v_mfma_f32_16x16x32_bf16 v[72:75], v[136:139], v[192:195], v[72:75]
	v_mfma_f32_16x16x32_bf16 v[68:71], v[128:131], v[200:203], v[68:71]
	v_mfma_f32_16x16x32_bf16 v[64:67], v[136:139], v[200:203], v[64:67]
	v_mfma_f32_16x16x32_bf16 v[92:95], v[132:135], v[164:167], v[92:95]
	v_mfma_f32_16x16x32_bf16 v[88:91], v[140:143], v[164:167], v[88:91]
	v_mfma_f32_16x16x32_bf16 v[84:87], v[132:135], v[188:191], v[84:87]
	v_mfma_f32_16x16x32_bf16 v[80:83], v[140:143], v[188:191], v[80:83]
	v_mfma_f32_16x16x32_bf16 v[76:79], v[132:135], v[196:199], v[76:79]
	v_mfma_f32_16x16x32_bf16 v[72:75], v[140:143], v[196:199], v[72:75]
	v_mfma_f32_16x16x32_bf16 v[68:71], v[132:135], v[204:207], v[68:71]
	v_mfma_f32_16x16x32_bf16 v[64:67], v[140:143], v[204:207], v[64:67]
	s_setprio 0
	s_setprio 1
	v_mfma_f32_16x16x32_bf16 v[28:31], v[144:147], v[160:163], v[28:31]
	v_mfma_f32_16x16x32_bf16 v[24:27], v[152:155], v[160:163], v[24:27]
	v_mfma_f32_16x16x32_bf16 v[20:23], v[144:147], v[168:171], v[20:23]
	v_mfma_f32_16x16x32_bf16 v[16:19], v[152:155], v[168:171], v[16:19]
	v_mfma_f32_16x16x32_bf16 v[12:15], v[144:147], v[192:195], v[12:15]
	v_mfma_f32_16x16x32_bf16 v[8:11], v[152:155], v[192:195], v[8:11]
	v_mfma_f32_16x16x32_bf16 v[4:7], v[144:147], v[200:203], v[4:7]
	v_mfma_f32_16x16x32_bf16 v[0:3], v[152:155], v[200:203], v[0:3]
	v_mfma_f32_16x16x32_bf16 v[28:31], v[148:151], v[164:167], v[28:31]
	v_mfma_f32_16x16x32_bf16 v[24:27], v[156:159], v[164:167], v[24:27]
	v_mfma_f32_16x16x32_bf16 v[20:23], v[148:151], v[188:191], v[20:23]
	v_mfma_f32_16x16x32_bf16 v[16:19], v[156:159], v[188:191], v[16:19]
	v_mfma_f32_16x16x32_bf16 v[12:15], v[148:151], v[196:199], v[12:15]
	v_mfma_f32_16x16x32_bf16 v[8:11], v[156:159], v[196:199], v[8:11]
	v_mfma_f32_16x16x32_bf16 v[4:7], v[148:151], v[204:207], v[4:7]
	v_mfma_f32_16x16x32_bf16 v[0:3], v[156:159], v[204:207], v[0:3]
	s_barrier
	s_setprio 0
	s_add_i32 s8, 0, 0x18000
	s_add_i32 s9, 0, 0x1c000
	v_add_u32_e32 v140, s8, v215
	v_add_u32_e32 v156, s9, v215
	ds_read_b128 v[128:131], v140
	ds_read_b128 v[132:135], v140 offset:1024
	ds_read_b128 v[136:139], v140 offset:2048
	ds_read_b128 v[140:143], v140 offset:3072
	ds_read_b128 v[144:147], v156
	ds_read_b128 v[148:151], v156 offset:1024
	ds_read_b128 v[152:155], v156 offset:2048
	ds_read_b128 v[156:159], v156 offset:3072
	s_add_u32 s68, s68, 0x200000
	s_addc_u32 s69, s69, 0
	s_mov_b32 m0, s45
	v_lshl_add_u64 v[218:219], s[68:69], 0, v[172:173]
	ds_read_b128 v[160:163], v241 offset:32768
	ds_read_b128 v[164:167], v241 offset:33792
	ds_read_b128 v[168:171], v241 offset:34816
	ds_read_b128 v[188:191], v241 offset:35840
	ds_read_b128 v[192:195], v241 offset:36864
	ds_read_b128 v[196:199], v241 offset:37888
	ds_read_b128 v[200:203], v241 offset:38912
	ds_read_b128 v[204:207], v241 offset:39936
	global_load_lds_dwordx4 v[218:219], off
	v_lshl_add_u64 v[218:219], s[68:69], 0, v[176:177]
	s_mov_b32 m0, s53
	s_nop 0
	global_load_lds_dwordx4 v[218:219], off
	s_waitcnt vmcnt(8)
	s_waitcnt lgkmcnt(0)
	s_setprio 1
	s_barrier
	v_mfma_f32_16x16x32_bf16 v[124:127], v[128:131], v[160:163], v[124:127]
	v_mfma_f32_16x16x32_bf16 v[120:123], v[136:139], v[160:163], v[120:123]
	v_mfma_f32_16x16x32_bf16 v[116:119], v[128:131], v[168:171], v[116:119]
	v_mfma_f32_16x16x32_bf16 v[112:115], v[136:139], v[168:171], v[112:115]
	v_mfma_f32_16x16x32_bf16 v[108:111], v[128:131], v[192:195], v[108:111]
	v_mfma_f32_16x16x32_bf16 v[104:107], v[136:139], v[192:195], v[104:107]
	v_mfma_f32_16x16x32_bf16 v[100:103], v[128:131], v[200:203], v[100:103]
	v_mfma_f32_16x16x32_bf16 v[96:99], v[136:139], v[200:203], v[96:99]
	v_mfma_f32_16x16x32_bf16 v[124:127], v[132:135], v[164:167], v[124:127]
	v_mfma_f32_16x16x32_bf16 v[120:123], v[140:143], v[164:167], v[120:123]
	v_mfma_f32_16x16x32_bf16 v[116:119], v[132:135], v[188:191], v[116:119]
	v_mfma_f32_16x16x32_bf16 v[112:115], v[140:143], v[188:191], v[112:115]
	v_mfma_f32_16x16x32_bf16 v[108:111], v[132:135], v[196:199], v[108:111]
	v_mfma_f32_16x16x32_bf16 v[104:107], v[140:143], v[196:199], v[104:107]
	v_mfma_f32_16x16x32_bf16 v[100:103], v[132:135], v[204:207], v[100:103]
	v_mfma_f32_16x16x32_bf16 v[96:99], v[140:143], v[204:207], v[96:99]
	s_setprio 0
	s_setprio 1
	v_mfma_f32_16x16x32_bf16 v[60:63], v[144:147], v[160:163], v[60:63]
	v_mfma_f32_16x16x32_bf16 v[56:59], v[152:155], v[160:163], v[56:59]
	v_mfma_f32_16x16x32_bf16 v[52:55], v[144:147], v[168:171], v[52:55]
	v_mfma_f32_16x16x32_bf16 v[48:51], v[152:155], v[168:171], v[48:51]
	v_mfma_f32_16x16x32_bf16 v[44:47], v[144:147], v[192:195], v[44:47]
	v_mfma_f32_16x16x32_bf16 v[40:43], v[152:155], v[192:195], v[40:43]
	v_mfma_f32_16x16x32_bf16 v[36:39], v[144:147], v[200:203], v[36:39]
	v_mfma_f32_16x16x32_bf16 v[32:35], v[152:155], v[200:203], v[32:35]
	v_mfma_f32_16x16x32_bf16 v[60:63], v[148:151], v[164:167], v[60:63]
	v_mfma_f32_16x16x32_bf16 v[56:59], v[156:159], v[164:167], v[56:59]
	v_mfma_f32_16x16x32_bf16 v[52:55], v[148:151], v[188:191], v[52:55]
	v_mfma_f32_16x16x32_bf16 v[48:51], v[156:159], v[188:191], v[48:51]
	v_mfma_f32_16x16x32_bf16 v[44:47], v[148:151], v[196:199], v[44:47]
	v_mfma_f32_16x16x32_bf16 v[40:43], v[156:159], v[196:199], v[40:43]
	v_mfma_f32_16x16x32_bf16 v[36:39], v[148:151], v[204:207], v[36:39]
	v_mfma_f32_16x16x32_bf16 v[32:35], v[156:159], v[204:207], v[32:35]
	s_barrier
; #define PG8_STAGE(bufoff, gbase, voff) do { _Pragma("unroll") for (int _i = 0; _i < 2; ++_i) \
;         __builtin_amdgcn_global_load_lds((const unsigned*)((const char*)(gbase) + (voff)[_i]), (PG8_LAS unsigned*)(lds + (bufoff) + ldsw + _i * 8192), 16, 0, 0); } while (0)
; #define PG8_LDA(dst, b, h) do { _Pragma("unroll") for (int m = 0; m < 4; ++m) _Pragma("unroll") for (int k = 0; k < 2; ++k) dst[m][k] = *(const PG8_LAS bf16x8*)(lds + PG8_SA(b, h) + aoff + m * 2048 + k * 1024); } while (0)
; #define PG8_MMA(ai, bj, At, Bt) do { __builtin_amdgcn_s_setprio(1); _Pragma("unroll") for (int m = 0; m < 4; ++m) _Pragma("unroll") for (int n = 0; n < 2; ++n) _Pragma("unroll") for (int k = 0; k < 2; ++k) \
;         acc[ai][bj][m][n] = __builtin_amdgcn_mfma_f32_16x16x32_bf16(Bt[n][k], At[m][k], acc[ai][bj][m][n], 0, 0, 0); __builtin_amdgcn_s_setprio(0); } while (0)
; #define PG8_WAIT_V(n) asm volatile("s_waitcnt vmcnt(" #n ")" ::: "memory")
; #define PG8_WAIT_L(n) asm volatile("s_waitcnt lgkmcnt(" #n ")" ::: "memory")
; #define PG8_BAR __builtin_amdgcn_s_barrier()
; #define PG8_SCHED __builtin_amdgcn_sched_barrier(0)
; template <class Epi, class Sched, bool ALIGN_EPI = false, bool SP2 = false>
; __device__ __forceinline__ void gemm_phase(PG8_LAS unsigned char* lds, const Gemm g, const Sched& S, const Epi& E, const int wid) {
;     ...
;             PG8_LDA(At, 1, 1); PG8_STAGE(PG8_SB(1, 0), b3, voffB); PG8_STAGE(PG8_SB(1, 1), b3 + hstep, voffB); PG8_STAGE(PG8_SA(1, 0), a3, voffA);
;             PG8_WAIT_V(8); PG8_WAIT_L(0); PG8_BAR; PG8_MMA(1, 0, At, B0); PG8_MMA(1, 1, At, B1); PG8_BAR; PG8_SCHED;
;     ...
;         if constexpr (ALIGN_EPI) { if (wr == 0) PG8_BAR; }
	s_setprio 0
	s_add_i32 s8, s8, s3
	v_lshl_add_u64 v[208:209], v[208:209], 0, s[50:51]
	s_mov_b32 m0, s8
	ds_read_b128 v[160:163], v241 offset:49152
	ds_read_b128 v[164:167], v241 offset:50176
	ds_read_b128 v[168:171], v241 offset:51200
	ds_read_b128 v[188:191], v241 offset:52224
	ds_read_b128 v[192:195], v241 offset:53248
	ds_read_b128 v[196:199], v241 offset:54272
	ds_read_b128 v[200:203], v241 offset:55296
	ds_read_b128 v[204:207], v241 offset:56320
	global_load_lds_dwordx4 v[208:209], off
	s_add_i32 m0, s8, 0x2000
	s_add_u32 s66, s66, 0x200080
	v_lshl_add_u64 v[208:209], v[210:211], 0, s[50:51]
	s_addc_u32 s67, s67, 0
	s_add_i32 s8, s9, s3
	global_load_lds_dwordx4 v[208:209], off
	v_lshl_add_u64 v[208:209], s[66:67], 0, v[174:175]
	s_mov_b32 m0, s8
	s_nop 0
	global_load_lds_dwordx4 v[208:209], off
	v_lshl_add_u64 v[208:209], s[66:67], 0, v[178:179]
	s_add_i32 m0, s8, 0x2000
	s_nop 0
	global_load_lds_dwordx4 v[208:209], off
	v_lshl_add_u64 v[208:209], v[212:213], 0, s[50:51]
	s_mov_b32 m0, s70
	s_nop 0
	global_load_lds_dwordx4 v[208:209], off
	v_lshl_add_u64 v[208:209], v[216:217], 0, s[50:51]
	s_mov_b32 m0, s71
	s_nop 0
	global_load_lds_dwordx4 v[208:209], off
	s_waitcnt vmcnt(8)
	s_waitcnt lgkmcnt(0)
	s_setprio 1
	s_barrier
	v_mfma_f32_16x16x32_bf16 v[92:95], v[128:131], v[160:163], v[92:95]
	v_mfma_f32_16x16x32_bf16 v[88:91], v[136:139], v[160:163], v[88:91]
	v_mfma_f32_16x16x32_bf16 v[84:87], v[128:131], v[168:171], v[84:87]
	v_mfma_f32_16x16x32_bf16 v[80:83], v[136:139], v[168:171], v[80:83]
	v_mfma_f32_16x16x32_bf16 v[76:79], v[128:131], v[192:195], v[76:79]
	v_mfma_f32_16x16x32_bf16 v[72:75], v[136:139], v[192:195], v[72:75]
	v_mfma_f32_16x16x32_bf16 v[68:71], v[128:131], v[200:203], v[68:71]
	v_mfma_f32_16x16x32_bf16 v[64:67], v[136:139], v[200:203], v[64:67]
	v_mfma_f32_16x16x32_bf16 v[92:95], v[132:135], v[164:167], v[92:95]
	v_mfma_f32_16x16x32_bf16 v[88:91], v[140:143], v[164:167], v[88:91]
	v_mfma_f32_16x16x32_bf16 v[84:87], v[132:135], v[188:191], v[84:87]
	v_mfma_f32_16x16x32_bf16 v[80:83], v[140:143], v[188:191], v[80:83]
	v_mfma_f32_16x16x32_bf16 v[76:79], v[132:135], v[196:199], v[76:79]
	v_mfma_f32_16x16x32_bf16 v[72:75], v[140:143], v[196:199], v[72:75]
	v_mfma_f32_16x16x32_bf16 v[68:71], v[132:135], v[204:207], v[68:71]
	v_mfma_f32_16x16x32_bf16 v[64:67], v[140:143], v[204:207], v[64:67]
	s_setprio 0
	s_setprio 1
	v_mfma_f32_16x16x32_bf16 v[28:31], v[144:147], v[160:163], v[28:31]
	v_mfma_f32_16x16x32_bf16 v[24:27], v[152:155], v[160:163], v[24:27]
	v_mfma_f32_16x16x32_bf16 v[20:23], v[144:147], v[168:171], v[20:23]
	v_mfma_f32_16x16x32_bf16 v[16:19], v[152:155], v[168:171], v[16:19]
	v_mfma_f32_16x16x32_bf16 v[12:15], v[144:147], v[192:195], v[12:15]
	v_mfma_f32_16x16x32_bf16 v[8:11], v[152:155], v[192:195], v[8:11]
	v_mfma_f32_16x16x32_bf16 v[4:7], v[144:147], v[200:203], v[4:7]
	v_mfma_f32_16x16x32_bf16 v[0:3], v[152:155], v[200:203], v[0:3]
	v_mfma_f32_16x16x32_bf16 v[28:31], v[148:151], v[164:167], v[28:31]
	v_mfma_f32_16x16x32_bf16 v[24:27], v[156:159], v[164:167], v[24:27]
	v_mfma_f32_16x16x32_bf16 v[20:23], v[148:151], v[188:191], v[20:23]
	v_mfma_f32_16x16x32_bf16 v[16:19], v[156:159], v[188:191], v[16:19]
	v_mfma_f32_16x16x32_bf16 v[12:15], v[148:151], v[196:199], v[12:15]
	v_mfma_f32_16x16x32_bf16 v[8:11], v[156:159], v[196:199], v[8:11]
	v_mfma_f32_16x16x32_bf16 v[4:7], v[148:151], v[204:207], v[4:7]
	v_mfma_f32_16x16x32_bf16 v[0:3], v[156:159], v[204:207], v[0:3]
	s_barrier
	s_setprio 0
	s_add_i32 s93, s93, 2
	s_add_u32 s91, s91, 0x100
	s_addc_u32 s92, s92, 0
	s_add_u32 s64, s64, 0x100
	s_addc_u32 s65, s65, 0
	s_cmpk_lt_u32 s93, 0x7e
	s_cbranch_scc1 .LBB0_912
	s_andn2_b64 vcc, exec, s[20:21]
	s_cbranch_vccnz .LBB0_915
	s_barrier

; #define PG8_STAGE(bufoff, gbase, voff) do { _Pragma("unroll") for (int _i = 0; _i < 2; ++_i) \
;         __builtin_amdgcn_global_load_lds((const unsigned*)((const char*)(gbase) + (voff)[_i]), (PG8_LAS unsigned*)(lds + (bufoff) + ldsw + _i * 8192), 16, 0, 0); } while (0)
; #define PG8_LDA(dst, b, h) do { _Pragma("unroll") for (int m = 0; m < 4; ++m) _Pragma("unroll") for (int k = 0; k < 2; ++k) dst[m][k] = *(const PG8_LAS bf16x8*)(lds + PG8_SA(b, h) + aoff + m * 2048 + k * 1024); } while (0)
; #define PG8_LDB(dst, b, h) do { _Pragma("unroll") for (int n = 0; n < 2; ++n) _Pragma("unroll") for (int k = 0; k < 2; ++k) dst[n][k] = *(const PG8_LAS bf16x8*)(lds + PG8_SB(b, h) + boff + n * 2048 + k * 1024); } while (0)
; #define PG8_MMA(ai, bj, At, Bt) do { __builtin_amdgcn_s_setprio(1); _Pragma("unroll") for (int m = 0; m < 4; ++m) _Pragma("unroll") for (int n = 0; n < 2; ++n) _Pragma("unroll") for (int k = 0; k < 2; ++k) \
;         acc[ai][bj][m][n] = __builtin_amdgcn_mfma_f32_16x16x32_bf16(Bt[n][k], At[m][k], acc[ai][bj][m][n], 0, 0, 0); __builtin_amdgcn_s_setprio(0); } while (0)
; #define PG8_WAIT_V(n) asm volatile("s_waitcnt vmcnt(" #n ")" ::: "memory")
; #define PG8_WAIT_L(n) asm volatile("s_waitcnt lgkmcnt(" #n ")" ::: "memory")
; template <class Epi, class Sched, bool ALIGN_EPI = false, bool SP2 = false>
; __device__ __forceinline__ void gemm_phase(PG8_LAS unsigned char* lds, const Gemm g, const Sched& S, const Epi& E, const int wid) {
;     ...
;             const bool last = (t == nt - 2);
;             const char* a1 = cA + (size_t)(t + 1) * kstep;
;             const char* a2 = last ? nA : cA + (size_t)(t + 2) * kstep; const char* b2 = last ? nB : cB + (size_t)(t + 2) * kstep;
;             const char* a3 = a2 + kstep; const char* b3 = b2 + kstep;
;             if (last && has_next) S.a_ready(nxt);
;             if constexpr (SP2) {
;             PG8_LDB(B0, 0, 0); PG8_LDB(B1, 0, 1); PG8_SCHED; PG8_LDA(At, 0, 0); PG8_STAGE(PG8_SA(1, 1), a1 + hstep, voffA);
;             PG8_WAIT_V(8); PG8_WAIT_L(0); PG8_BAR; PG8_MMA(0, 0, At, B0); PG8_MMA(0, 1, At, B1); PG8_BAR; PG8_SCHED;
;             PG8_LDA(At, 0, 1); PG8_STAGE(PG8_SB(0, 0), b2, voffB); PG8_STAGE(PG8_SB(0, 1), b2 + hstep, voffB); PG8_STAGE(PG8_SA(0, 0), a2, voffA);
;             PG8_WAIT_V(8); PG8_WAIT_L(0); PG8_BAR; PG8_MMA(1, 0, At, B0); PG8_MMA(1, 1, At, B1); PG8_BAR; PG8_SCHED;
.LBB0_1000:
	ds_read_b128 v[88:91], v211
	ds_read_b128 v[100:103], v211 offset:1024
	ds_read_b128 v[104:107], v211 offset:2048
	ds_read_b128 v[108:111], v211 offset:3072
	ds_read_b128 v[112:115], v212
	ds_read_b128 v[116:119], v212 offset:1024
	ds_read_b128 v[128:131], v212 offset:2048
	ds_read_b128 v[140:143], v212 offset:3072
	s_add_u32 s8, s18, 0xfff80080
	s_addc_u32 s9, s19, -1
	s_cmp_eq_u32 vcc_hi, 28
	s_cselect_b32 s67, s15, s9
	s_cselect_b32 s66, s17, s8
	s_cselect_b32 s65, s28, vcc_lo
	s_cselect_b32 s64, s57, s59
	v_lshl_add_u64 v[206:207], s[18:19], 0, v[182:183]
	s_add_i32 m0, s70, 0xc000
	ds_read_b128 v[152:155], v213
	ds_read_b128 v[156:159], v213 offset:1024
	ds_read_b128 v[168:171], v213 offset:2048
	ds_read_b128 v[190:193], v213 offset:3072
	ds_read_b128 v[194:197], v213 offset:4096
	ds_read_b128 v[198:201], v213 offset:5120
	ds_read_b128 v[202:205], v213 offset:6144
	ds_read_b128 v[216:219], v213 offset:7168
	global_load_lds_dwordx4 v[206:207], off
	v_lshl_add_u64 v[206:207], s[18:19], 0, v[184:185]
	s_add_i32 m0, s70, 0xe000
	s_nop 0
	global_load_lds_dwordx4 v[206:207], off
	s_waitcnt vmcnt(8)
	s_waitcnt lgkmcnt(0)
	s_setprio 1
	s_barrier
	v_mfma_f32_16x16x32_bf16 v[164:167], v[88:91], v[152:155], v[164:167]
	v_mfma_f32_16x16x32_bf16 v[160:163], v[104:107], v[152:155], v[160:163]
	v_mfma_f32_16x16x32_bf16 v[148:151], v[88:91], v[168:171], v[148:151]
	v_mfma_f32_16x16x32_bf16 v[144:147], v[104:107], v[168:171], v[144:147]
	v_mfma_f32_16x16x32_bf16 v[136:139], v[88:91], v[194:197], v[136:139]
	v_mfma_f32_16x16x32_bf16 v[132:135], v[104:107], v[194:197], v[132:135]
	v_mfma_f32_16x16x32_bf16 v[124:127], v[88:91], v[202:205], v[124:127]
	v_mfma_f32_16x16x32_bf16 v[120:123], v[104:107], v[202:205], v[120:123]
	v_mfma_f32_16x16x32_bf16 v[164:167], v[100:103], v[156:159], v[164:167]
	v_mfma_f32_16x16x32_bf16 v[160:163], v[108:111], v[156:159], v[160:163]
	v_mfma_f32_16x16x32_bf16 v[148:151], v[100:103], v[190:193], v[148:151]
	v_mfma_f32_16x16x32_bf16 v[144:147], v[108:111], v[190:193], v[144:147]
	v_mfma_f32_16x16x32_bf16 v[136:139], v[100:103], v[198:201], v[136:139]
	v_mfma_f32_16x16x32_bf16 v[132:135], v[108:111], v[198:201], v[132:135]
	v_mfma_f32_16x16x32_bf16 v[124:127], v[100:103], v[216:219], v[124:127]
	v_mfma_f32_16x16x32_bf16 v[120:123], v[108:111], v[216:219], v[120:123]
	s_setprio 0
	s_setprio 1
	v_mfma_f32_16x16x32_bf16 v[60:63], v[112:115], v[152:155], v[60:63]
	v_mfma_f32_16x16x32_bf16 v[56:59], v[128:131], v[152:155], v[56:59]
	v_mfma_f32_16x16x32_bf16 v[52:55], v[112:115], v[168:171], v[52:55]
	v_mfma_f32_16x16x32_bf16 v[48:51], v[128:131], v[168:171], v[48:51]
	v_mfma_f32_16x16x32_bf16 v[44:47], v[112:115], v[194:197], v[44:47]
	v_mfma_f32_16x16x32_bf16 v[40:43], v[128:131], v[194:197], v[40:43]
	v_mfma_f32_16x16x32_bf16 v[36:39], v[112:115], v[202:205], v[36:39]
	v_mfma_f32_16x16x32_bf16 v[32:35], v[128:131], v[202:205], v[32:35]
	v_mfma_f32_16x16x32_bf16 v[60:63], v[116:119], v[156:159], v[60:63]
	v_mfma_f32_16x16x32_bf16 v[56:59], v[140:143], v[156:159], v[56:59]
	v_mfma_f32_16x16x32_bf16 v[52:55], v[116:119], v[190:193], v[52:55]
	v_mfma_f32_16x16x32_bf16 v[48:51], v[140:143], v[190:193], v[48:51]
	v_mfma_f32_16x16x32_bf16 v[44:47], v[116:119], v[198:201], v[44:47]
	v_mfma_f32_16x16x32_bf16 v[40:43], v[140:143], v[198:201], v[40:43]
	v_mfma_f32_16x16x32_bf16 v[36:39], v[116:119], v[216:219], v[36:39]
	v_mfma_f32_16x16x32_bf16 v[32:35], v[140:143], v[216:219], v[32:35]
	s_barrier
	s_setprio 0
	s_add_i32 s8, s95, s3
	v_lshl_add_u64 v[206:207], s[64:65], 0, v[172:173]
	s_mov_b32 m0, s8
	ds_read_b128 v[152:155], v213 offset:16384
	ds_read_b128 v[156:159], v213 offset:17408
	ds_read_b128 v[168:171], v213 offset:18432
	ds_read_b128 v[190:193], v213 offset:19456
	ds_read_b128 v[194:197], v213 offset:20480
	ds_read_b128 v[198:201], v213 offset:21504
	ds_read_b128 v[202:205], v213 offset:22528
	ds_read_b128 v[216:219], v213 offset:23552
	global_load_lds_dwordx4 v[206:207], off
	s_add_i32 m0, s8, 0x2000
	s_add_u32 s8, s64, 0x80000
	v_lshl_add_u64 v[220:221], s[64:65], 0, v[174:175]
	s_addc_u32 s9, s65, 0
	s_add_i32 s37, s96, s3
	global_load_lds_dwordx4 v[220:221], off
	v_lshl_add_u64 v[222:223], s[8:9], 0, v[172:173]
	s_mov_b32 m0, s37
	v_lshl_add_u64 v[224:225], s[66:67], 0, v[174:175]
	global_load_lds_dwordx4 v[222:223], off
	v_lshl_add_u64 v[222:223], s[8:9], 0, v[174:175]
	s_add_i32 m0, s37, 0x2000
	s_nop 0
	global_load_lds_dwordx4 v[222:223], off
	v_lshl_add_u64 v[222:223], s[66:67], 0, v[172:173]
	s_mov_b32 m0, s70
	s_nop 0
	global_load_lds_dwordx4 v[222:223], off
	s_mov_b32 m0, s71
	s_nop 0
	global_load_lds_dwordx4 v[224:225], off
	s_waitcnt vmcnt(8)
	s_waitcnt lgkmcnt(0)
	s_setprio 1
	s_barrier
; #define PG8_STAGE(bufoff, gbase, voff) do { _Pragma("unroll") for (int _i = 0; _i < 2; ++_i) \
;         __builtin_amdgcn_global_load_lds((const unsigned*)((const char*)(gbase) + (voff)[_i]), (PG8_LAS unsigned*)(lds + (bufoff) + ldsw + _i * 8192), 16, 0, 0); } while (0)
; #define PG8_LDA(dst, b, h) do { _Pragma("unroll") for (int m = 0; m < 4; ++m) _Pragma("unroll") for (int k = 0; k < 2; ++k) dst[m][k] = *(const PG8_LAS bf16x8*)(lds + PG8_SA(b, h) + aoff + m * 2048 + k * 1024); } while (0)
; #define PG8_LDB(dst, b, h) do { _Pragma("unroll") for (int n = 0; n < 2; ++n) _Pragma("unroll") for (int k = 0; k < 2; ++k) dst[n][k] = *(const PG8_LAS bf16x8*)(lds + PG8_SB(b, h) + boff + n * 2048 + k * 1024); } while (0)
; #define PG8_MMA(ai, bj, At, Bt) do { __builtin_amdgcn_s_setprio(1); _Pragma("unroll") for (int m = 0; m < 4; ++m) _Pragma("unroll") for (int n = 0; n < 2; ++n) _Pragma("unroll") for (int k = 0; k < 2; ++k) \
;         acc[ai][bj][m][n] = __builtin_amdgcn_mfma_f32_16x16x32_bf16(Bt[n][k], At[m][k], acc[ai][bj][m][n], 0, 0, 0); __builtin_amdgcn_s_setprio(0); } while (0)
; #define PG8_WAIT_V(n) asm volatile("s_waitcnt vmcnt(" #n ")" ::: "memory")
; #define PG8_WAIT_L(n) asm volatile("s_waitcnt lgkmcnt(" #n ")" ::: "memory")
; #define PG8_BAR __builtin_amdgcn_s_barrier()
; #define PG8_SCHED __builtin_amdgcn_sched_barrier(0)
; template <class Epi, class Sched, bool ALIGN_EPI = false, bool SP2 = false>
; __device__ __forceinline__ void gemm_phase(PG8_LAS unsigned char* lds, const Gemm g, const Sched& S, const Epi& E, const int wid) {
;     ...
;             PG8_WAIT_V(8); PG8_WAIT_L(0); PG8_BAR; PG8_MMA(1, 0, At, B0); PG8_MMA(1, 1, At, B1); PG8_BAR; PG8_SCHED;
;             PG8_LDB(B0, 1, 0); PG8_LDB(B1, 1, 1); PG8_SCHED; PG8_LDA(At, 1, 0); PG8_STAGE(PG8_SA(0, 1), a2 + hstep, voffA);
;             PG8_WAIT_V(8); PG8_WAIT_L(0); PG8_BAR; PG8_MMA(0, 0, At, B0); PG8_MMA(0, 1, At, B1); PG8_BAR; PG8_SCHED;
	v_mfma_f32_16x16x32_bf16 v[96:99], v[88:91], v[152:155], v[96:99]
	v_mfma_f32_16x16x32_bf16 v[92:95], v[104:107], v[152:155], v[92:95]
	v_mfma_f32_16x16x32_bf16 v[84:87], v[88:91], v[168:171], v[84:87]
	v_mfma_f32_16x16x32_bf16 v[80:83], v[104:107], v[168:171], v[80:83]
	v_mfma_f32_16x16x32_bf16 v[76:79], v[88:91], v[194:197], v[76:79]
	v_mfma_f32_16x16x32_bf16 v[72:75], v[104:107], v[194:197], v[72:75]
	v_mfma_f32_16x16x32_bf16 v[68:71], v[88:91], v[202:205], v[68:71]
	v_mfma_f32_16x16x32_bf16 v[64:67], v[104:107], v[202:205], v[64:67]
	v_mfma_f32_16x16x32_bf16 v[96:99], v[100:103], v[156:159], v[96:99]
	v_mfma_f32_16x16x32_bf16 v[92:95], v[108:111], v[156:159], v[92:95]
	v_mfma_f32_16x16x32_bf16 v[84:87], v[100:103], v[190:193], v[84:87]
	v_mfma_f32_16x16x32_bf16 v[80:83], v[108:111], v[190:193], v[80:83]
	v_mfma_f32_16x16x32_bf16 v[76:79], v[100:103], v[198:201], v[76:79]
	v_mfma_f32_16x16x32_bf16 v[72:75], v[108:111], v[198:201], v[72:75]
	v_mfma_f32_16x16x32_bf16 v[68:71], v[100:103], v[216:219], v[68:71]
	v_mfma_f32_16x16x32_bf16 v[64:67], v[108:111], v[216:219], v[64:67]
	s_setprio 0
	s_setprio 1
	v_mfma_f32_16x16x32_bf16 v[28:31], v[112:115], v[152:155], v[28:31]
	v_mfma_f32_16x16x32_bf16 v[24:27], v[128:131], v[152:155], v[24:27]
	v_mfma_f32_16x16x32_bf16 v[20:23], v[112:115], v[168:171], v[20:23]
	v_mfma_f32_16x16x32_bf16 v[16:19], v[128:131], v[168:171], v[16:19]
	v_mfma_f32_16x16x32_bf16 v[12:15], v[112:115], v[194:197], v[12:15]
	v_mfma_f32_16x16x32_bf16 v[8:11], v[128:131], v[194:197], v[8:11]
	v_mfma_f32_16x16x32_bf16 v[4:7], v[112:115], v[202:205], v[4:7]
	v_mfma_f32_16x16x32_bf16 v[0:3], v[128:131], v[202:205], v[0:3]
	v_mfma_f32_16x16x32_bf16 v[28:31], v[116:119], v[156:159], v[28:31]
	v_mfma_f32_16x16x32_bf16 v[24:27], v[140:143], v[156:159], v[24:27]
	v_mfma_f32_16x16x32_bf16 v[20:23], v[116:119], v[190:193], v[20:23]
	v_mfma_f32_16x16x32_bf16 v[16:19], v[140:143], v[190:193], v[16:19]
	v_mfma_f32_16x16x32_bf16 v[12:15], v[116:119], v[198:201], v[12:15]
	v_mfma_f32_16x16x32_bf16 v[8:11], v[140:143], v[198:201], v[8:11]
	v_mfma_f32_16x16x32_bf16 v[4:7], v[116:119], v[216:219], v[4:7]
	v_mfma_f32_16x16x32_bf16 v[0:3], v[140:143], v[216:219], v[0:3]
	s_barrier
	s_setprio 0
	s_add_i32 s37, 0, 0x18000
	s_add_i32 s79, 0, 0x1c000
	v_add_u32_e32 v108, s37, v209
	v_add_u32_e32 v140, s79, v209
	ds_read_b128 v[88:91], v108
	ds_read_b128 v[100:103], v108 offset:1024
	ds_read_b128 v[104:107], v108 offset:2048
	ds_read_b128 v[108:111], v108 offset:3072
	ds_read_b128 v[112:115], v140
	ds_read_b128 v[116:119], v140 offset:1024
	ds_read_b128 v[128:131], v140 offset:2048
	ds_read_b128 v[140:143], v140 offset:3072
	s_add_u32 s8, s66, 0x80000
	s_addc_u32 s9, s67, 0
	s_mov_b32 m0, s72
	v_lshl_add_u64 v[226:227], s[8:9], 0, v[172:173]
	ds_read_b128 v[152:155], v213 offset:32768
	ds_read_b128 v[156:159], v213 offset:33792
	ds_read_b128 v[168:171], v213 offset:34816
	ds_read_b128 v[190:193], v213 offset:35840
	ds_read_b128 v[194:197], v213 offset:36864
	ds_read_b128 v[198:201], v213 offset:37888
	ds_read_b128 v[202:205], v213 offset:38912
	ds_read_b128 v[216:219], v213 offset:39936
	global_load_lds_dwordx4 v[226:227], off
	v_lshl_add_u64 v[226:227], s[8:9], 0, v[174:175]
	s_mov_b32 m0, s73
	s_nop 0
	global_load_lds_dwordx4 v[226:227], off
	s_waitcnt vmcnt(8)
	s_waitcnt lgkmcnt(0)
	s_setprio 1
	s_barrier
	v_mfma_f32_16x16x32_bf16 v[164:167], v[88:91], v[152:155], v[164:167]
	v_mfma_f32_16x16x32_bf16 v[160:163], v[104:107], v[152:155], v[160:163]
	v_mfma_f32_16x16x32_bf16 v[148:151], v[88:91], v[168:171], v[148:151]
	v_mfma_f32_16x16x32_bf16 v[144:147], v[104:107], v[168:171], v[144:147]
	v_mfma_f32_16x16x32_bf16 v[136:139], v[88:91], v[194:197], v[136:139]
	v_mfma_f32_16x16x32_bf16 v[132:135], v[104:107], v[194:197], v[132:135]
	v_mfma_f32_16x16x32_bf16 v[124:127], v[88:91], v[202:205], v[124:127]
	v_mfma_f32_16x16x32_bf16 v[120:123], v[104:107], v[202:205], v[120:123]
	v_mfma_f32_16x16x32_bf16 v[164:167], v[100:103], v[156:159], v[164:167]
	v_mfma_f32_16x16x32_bf16 v[160:163], v[108:111], v[156:159], v[160:163]
	v_mfma_f32_16x16x32_bf16 v[148:151], v[100:103], v[190:193], v[148:151]
	v_mfma_f32_16x16x32_bf16 v[144:147], v[108:111], v[190:193], v[144:147]
	v_mfma_f32_16x16x32_bf16 v[136:139], v[100:103], v[198:201], v[136:139]
	v_mfma_f32_16x16x32_bf16 v[132:135], v[108:111], v[198:201], v[132:135]
	v_mfma_f32_16x16x32_bf16 v[124:127], v[100:103], v[216:219], v[124:127]
	v_mfma_f32_16x16x32_bf16 v[120:123], v[108:111], v[216:219], v[120:123]
	s_setprio 0
	s_setprio 1
	v_mfma_f32_16x16x32_bf16 v[60:63], v[112:115], v[152:155], v[60:63]
	v_mfma_f32_16x16x32_bf16 v[56:59], v[128:131], v[152:155], v[56:59]
	v_mfma_f32_16x16x32_bf16 v[52:55], v[112:115], v[168:171], v[52:55]
	v_mfma_f32_16x16x32_bf16 v[48:51], v[128:131], v[168:171], v[48:51]
	v_mfma_f32_16x16x32_bf16 v[44:47], v[112:115], v[194:197], v[44:47]
	v_mfma_f32_16x16x32_bf16 v[40:43], v[128:131], v[194:197], v[40:43]
	v_mfma_f32_16x16x32_bf16 v[36:39], v[112:115], v[202:205], v[36:39]
	v_mfma_f32_16x16x32_bf16 v[32:35], v[128:131], v[202:205], v[32:35]
	v_mfma_f32_16x16x32_bf16 v[60:63], v[116:119], v[156:159], v[60:63]
	v_mfma_f32_16x16x32_bf16 v[56:59], v[140:143], v[156:159], v[56:59]
	v_mfma_f32_16x16x32_bf16 v[52:55], v[116:119], v[190:193], v[52:55]
	v_mfma_f32_16x16x32_bf16 v[48:51], v[140:143], v[190:193], v[48:51]
	v_mfma_f32_16x16x32_bf16 v[44:47], v[116:119], v[198:201], v[44:47]
	v_mfma_f32_16x16x32_bf16 v[40:43], v[140:143], v[198:201], v[40:43]
	v_mfma_f32_16x16x32_bf16 v[36:39], v[116:119], v[216:219], v[36:39]
	v_mfma_f32_16x16x32_bf16 v[32:35], v[140:143], v[216:219], v[32:35]
	s_barrier
; #define PG8_STAGE(bufoff, gbase, voff) do { _Pragma("unroll") for (int _i = 0; _i < 2; ++_i) \
;         __builtin_amdgcn_global_load_lds((const unsigned*)((const char*)(gbase) + (voff)[_i]), (PG8_LAS unsigned*)(lds + (bufoff) + ldsw + _i * 8192), 16, 0, 0); } while (0)
; #define PG8_LDA(dst, b, h) do { _Pragma("unroll") for (int m = 0; m < 4; ++m) _Pragma("unroll") for (int k = 0; k < 2; ++k) dst[m][k] = *(const PG8_LAS bf16x8*)(lds + PG8_SA(b, h) + aoff + m * 2048 + k * 1024); } while (0)
; #define PG8_MMA(ai, bj, At, Bt) do { __builtin_amdgcn_s_setprio(1); _Pragma("unroll") for (int m = 0; m < 4; ++m) _Pragma("unroll") for (int n = 0; n < 2; ++n) _Pragma("unroll") for (int k = 0; k < 2; ++k) \
;         acc[ai][bj][m][n] = __builtin_amdgcn_mfma_f32_16x16x32_bf16(Bt[n][k], At[m][k], acc[ai][bj][m][n], 0, 0, 0); __builtin_amdgcn_s_setprio(0); } while (0)
; #define PG8_WAIT_V(n) asm volatile("s_waitcnt vmcnt(" #n ")" ::: "memory")
; #define PG8_WAIT_L(n) asm volatile("s_waitcnt lgkmcnt(" #n ")" ::: "memory")
; #define PG8_BAR __builtin_amdgcn_s_barrier()
; #define PG8_SCHED __builtin_amdgcn_sched_barrier(0)
; template <class Epi, class Sched, bool ALIGN_EPI = false, bool SP2 = false>
; __device__ __forceinline__ void gemm_phase(PG8_LAS unsigned char* lds, const Gemm g, const Sched& S, const Epi& E, const int wid) {
;     ...
;             PG8_LDA(At, 1, 1); PG8_STAGE(PG8_SB(1, 0), b3, voffB); PG8_STAGE(PG8_SB(1, 1), b3 + hstep, voffB); PG8_STAGE(PG8_SA(1, 0), a3, voffA);
;             PG8_WAIT_V(8); PG8_WAIT_L(0); PG8_BAR; PG8_MMA(1, 0, At, B0); PG8_MMA(1, 1, At, B1); PG8_BAR; PG8_SCHED;
;     ...
;         if constexpr (ALIGN_EPI) { if (wr == 0) PG8_BAR; }
	s_setprio 0
	s_add_i32 s8, s37, s3
	v_lshl_add_u64 v[206:207], v[206:207], 0, s[54:55]
	s_mov_b32 m0, s8
	ds_read_b128 v[152:155], v213 offset:49152
	ds_read_b128 v[156:159], v213 offset:50176
	ds_read_b128 v[168:171], v213 offset:51200
	ds_read_b128 v[190:193], v213 offset:52224
	ds_read_b128 v[194:197], v213 offset:53248
	ds_read_b128 v[198:201], v213 offset:54272
	ds_read_b128 v[202:205], v213 offset:55296
	ds_read_b128 v[216:219], v213 offset:56320
	global_load_lds_dwordx4 v[206:207], off
	s_add_i32 m0, s8, 0x2000
	s_add_u32 s8, s64, 0x80080
	v_lshl_add_u64 v[206:207], v[220:221], 0, s[54:55]
	s_addc_u32 s9, s65, 0
	s_add_i32 s37, s79, s3
	global_load_lds_dwordx4 v[206:207], off
	v_lshl_add_u64 v[206:207], s[8:9], 0, v[172:173]
	s_mov_b32 m0, s37
	s_nop 0
	global_load_lds_dwordx4 v[206:207], off
	v_lshl_add_u64 v[206:207], s[8:9], 0, v[174:175]
	s_add_i32 m0, s37, 0x2000
	s_nop 0
	global_load_lds_dwordx4 v[206:207], off
	v_lshl_add_u64 v[206:207], v[222:223], 0, s[54:55]
	s_mov_b32 m0, s75
	s_nop 0
	global_load_lds_dwordx4 v[206:207], off
	v_lshl_add_u64 v[206:207], v[224:225], 0, s[54:55]
	s_mov_b32 m0, s77
	s_nop 0
	global_load_lds_dwordx4 v[206:207], off
	s_waitcnt vmcnt(8)
	s_waitcnt lgkmcnt(0)
	s_setprio 1
	s_barrier
	v_mfma_f32_16x16x32_bf16 v[96:99], v[88:91], v[152:155], v[96:99]
	v_mfma_f32_16x16x32_bf16 v[92:95], v[104:107], v[152:155], v[92:95]
	v_mfma_f32_16x16x32_bf16 v[84:87], v[88:91], v[168:171], v[84:87]
	v_mfma_f32_16x16x32_bf16 v[80:83], v[104:107], v[168:171], v[80:83]
	v_mfma_f32_16x16x32_bf16 v[76:79], v[88:91], v[194:197], v[76:79]
	v_mfma_f32_16x16x32_bf16 v[72:75], v[104:107], v[194:197], v[72:75]
	v_mfma_f32_16x16x32_bf16 v[68:71], v[88:91], v[202:205], v[68:71]
	v_mfma_f32_16x16x32_bf16 v[64:67], v[104:107], v[202:205], v[64:67]
	v_mfma_f32_16x16x32_bf16 v[96:99], v[100:103], v[156:159], v[96:99]
	v_mfma_f32_16x16x32_bf16 v[92:95], v[108:111], v[156:159], v[92:95]
	v_mfma_f32_16x16x32_bf16 v[84:87], v[100:103], v[190:193], v[84:87]
	v_mfma_f32_16x16x32_bf16 v[80:83], v[108:111], v[190:193], v[80:83]
	v_mfma_f32_16x16x32_bf16 v[76:79], v[100:103], v[198:201], v[76:79]
	v_mfma_f32_16x16x32_bf16 v[72:75], v[108:111], v[198:201], v[72:75]
	v_mfma_f32_16x16x32_bf16 v[68:71], v[100:103], v[216:219], v[68:71]
	v_mfma_f32_16x16x32_bf16 v[64:67], v[108:111], v[216:219], v[64:67]
	s_setprio 0
	s_setprio 1
	v_mfma_f32_16x16x32_bf16 v[28:31], v[112:115], v[152:155], v[28:31]
	v_mfma_f32_16x16x32_bf16 v[24:27], v[128:131], v[152:155], v[24:27]
	v_mfma_f32_16x16x32_bf16 v[20:23], v[112:115], v[168:171], v[20:23]
	v_mfma_f32_16x16x32_bf16 v[16:19], v[128:131], v[168:171], v[16:19]
	v_mfma_f32_16x16x32_bf16 v[12:15], v[112:115], v[194:197], v[12:15]
	v_mfma_f32_16x16x32_bf16 v[8:11], v[128:131], v[194:197], v[8:11]
	v_mfma_f32_16x16x32_bf16 v[4:7], v[112:115], v[202:205], v[4:7]
	v_mfma_f32_16x16x32_bf16 v[0:3], v[128:131], v[202:205], v[0:3]
	v_mfma_f32_16x16x32_bf16 v[28:31], v[116:119], v[156:159], v[28:31]
	v_mfma_f32_16x16x32_bf16 v[24:27], v[140:143], v[156:159], v[24:27]
	v_mfma_f32_16x16x32_bf16 v[20:23], v[116:119], v[190:193], v[20:23]
	v_mfma_f32_16x16x32_bf16 v[16:19], v[140:143], v[190:193], v[16:19]
	v_mfma_f32_16x16x32_bf16 v[12:15], v[116:119], v[198:201], v[12:15]
	v_mfma_f32_16x16x32_bf16 v[8:11], v[140:143], v[198:201], v[8:11]
	v_mfma_f32_16x16x32_bf16 v[4:7], v[116:119], v[216:219], v[4:7]
	v_mfma_f32_16x16x32_bf16 v[0:3], v[140:143], v[216:219], v[0:3]
	s_barrier
	s_setprio 0
	s_add_i32 vcc_hi, vcc_hi, 2
	s_add_u32 s18, s18, 0x100
	s_addc_u32 s19, s19, 0
	s_add_u32 s59, s59, 0x100
	s_addc_u32 vcc_lo, vcc_lo, 0
	s_cmp_gt_u32 vcc_hi, 29
	s_cbranch_scc0 .LBB0_1000
	s_and_b64 vcc, exec, s[20:21]
	s_cbranch_vccz .LBB0_1003
	s_barrier

; #define PG8_STAGE(bufoff, gbase, voff) do { _Pragma("unroll") for (int _i = 0; _i < 2; ++_i) \
;         __builtin_amdgcn_global_load_lds((const unsigned*)((const char*)(gbase) + (voff)[_i]), (PG8_LAS unsigned*)(lds + (bufoff) + ldsw + _i * 8192), 16, 0, 0); } while (0)
; #define PG8_LDA(dst, b, h) do { _Pragma("unroll") for (int m = 0; m < 4; ++m) _Pragma("unroll") for (int k = 0; k < 2; ++k) dst[m][k] = *(const PG8_LAS bf16x8*)(lds + PG8_SA(b, h) + aoff + m * 2048 + k * 1024); } while (0)
; #define PG8_LDB(dst, b, h) do { _Pragma("unroll") for (int n = 0; n < 2; ++n) _Pragma("unroll") for (int k = 0; k < 2; ++k) dst[n][k] = *(const PG8_LAS bf16x8*)(lds + PG8_SB(b, h) + boff + n * 2048 + k * 1024); } while (0)
; #define PG8_MMA(ai, bj, At, Bt) do { __builtin_amdgcn_s_setprio(1); _Pragma("unroll") for (int m = 0; m < 4; ++m) _Pragma("unroll") for (int n = 0; n < 2; ++n) _Pragma("unroll") for (int k = 0; k < 2; ++k) \
;         acc[ai][bj][m][n] = __builtin_amdgcn_mfma_f32_16x16x32_bf16(Bt[n][k], At[m][k], acc[ai][bj][m][n], 0, 0, 0); __builtin_amdgcn_s_setprio(0); } while (0)
; #define PG8_WAIT_V(n) asm volatile("s_waitcnt vmcnt(" #n ")" ::: "memory")
; #define PG8_WAIT_L(n) asm volatile("s_waitcnt lgkmcnt(" #n ")" ::: "memory")
; template <class Epi, class Sched, bool ALIGN_EPI = false, bool SP2 = false>
; __device__ __forceinline__ void gemm_phase(PG8_LAS unsigned char* lds, const Gemm g, const Sched& S, const Epi& E, const int wid) {
;     ...
;             const bool last = (t == nt - 2);
;             const char* a1 = cA + (size_t)(t + 1) * kstep;
;             const char* a2 = last ? nA : cA + (size_t)(t + 2) * kstep; const char* b2 = last ? nB : cB + (size_t)(t + 2) * kstep;
;             const char* a3 = a2 + kstep; const char* b3 = b2 + kstep;
;             if (last && has_next) S.a_ready(nxt);
;             if constexpr (SP2) {
;             PG8_LDB(B0, 0, 0); PG8_LDB(B1, 0, 1); PG8_SCHED; PG8_LDA(At, 0, 0); PG8_STAGE(PG8_SA(1, 1), a1 + hstep, voffA);
;             PG8_WAIT_V(8); PG8_WAIT_L(0); PG8_BAR; PG8_MMA(0, 0, At, B0); PG8_MMA(0, 1, At, B1); PG8_BAR; PG8_SCHED;
;             PG8_LDA(At, 0, 1); PG8_STAGE(PG8_SB(0, 0), b2, voffB); PG8_STAGE(PG8_SB(0, 1), b2 + hstep, voffB); PG8_STAGE(PG8_SA(0, 0), a2, voffA);
;             PG8_WAIT_V(8); PG8_WAIT_L(0); PG8_BAR; PG8_MMA(1, 0, At, B0); PG8_MMA(1, 1, At, B1); PG8_BAR; PG8_SCHED;
.LBB0_1389:
	ds_read_b128 v[128:131], v239
	ds_read_b128 v[132:135], v239 offset:1024
	ds_read_b128 v[136:139], v239 offset:2048
	ds_read_b128 v[140:143], v239 offset:3072
	ds_read_b128 v[144:147], v240
	ds_read_b128 v[148:151], v240 offset:1024
	ds_read_b128 v[152:155], v240 offset:2048
	ds_read_b128 v[156:159], v240 offset:3072
	s_add_u32 s8, s58, 0xfff80080
	s_addc_u32 s9, s59, -1
	s_cmp_eq_u32 s88, 28
	s_cselect_b32 s63, s15, s9
	s_cselect_b32 s62, s51, s8
	s_cselect_b32 s61, s49, s87
	s_cselect_b32 s60, s83, s86
	v_lshl_add_u64 v[208:209], s[58:59], 0, v[180:181]
	s_add_i32 m0, s57, 0xc000
	ds_read_b128 v[160:163], v241
	ds_read_b128 v[164:167], v241 offset:1024
	ds_read_b128 v[168:171], v241 offset:2048
	ds_read_b128 v[188:191], v241 offset:3072
	ds_read_b128 v[192:195], v241 offset:4096
	ds_read_b128 v[196:199], v241 offset:5120
	ds_read_b128 v[200:203], v241 offset:6144
	ds_read_b128 v[204:207], v241 offset:7168
	global_load_lds_dwordx4 v[208:209], off
	v_lshl_add_u64 v[208:209], s[58:59], 0, v[182:183]
	s_add_i32 m0, s57, 0xe000
	s_nop 0
	global_load_lds_dwordx4 v[208:209], off
	s_waitcnt vmcnt(8)
	s_waitcnt lgkmcnt(0)
	s_setprio 1
	s_barrier
	v_mfma_f32_16x16x32_bf16 v[124:127], v[128:131], v[160:163], v[124:127]
	v_mfma_f32_16x16x32_bf16 v[120:123], v[136:139], v[160:163], v[120:123]
	v_mfma_f32_16x16x32_bf16 v[116:119], v[128:131], v[168:171], v[116:119]
	v_mfma_f32_16x16x32_bf16 v[112:115], v[136:139], v[168:171], v[112:115]
	v_mfma_f32_16x16x32_bf16 v[108:111], v[128:131], v[192:195], v[108:111]
	v_mfma_f32_16x16x32_bf16 v[104:107], v[136:139], v[192:195], v[104:107]
	v_mfma_f32_16x16x32_bf16 v[100:103], v[128:131], v[200:203], v[100:103]
	v_mfma_f32_16x16x32_bf16 v[96:99], v[136:139], v[200:203], v[96:99]
	v_mfma_f32_16x16x32_bf16 v[124:127], v[132:135], v[164:167], v[124:127]
	v_mfma_f32_16x16x32_bf16 v[120:123], v[140:143], v[164:167], v[120:123]
	v_mfma_f32_16x16x32_bf16 v[116:119], v[132:135], v[188:191], v[116:119]
	v_mfma_f32_16x16x32_bf16 v[112:115], v[140:143], v[188:191], v[112:115]
	v_mfma_f32_16x16x32_bf16 v[108:111], v[132:135], v[196:199], v[108:111]
	v_mfma_f32_16x16x32_bf16 v[104:107], v[140:143], v[196:199], v[104:107]
	v_mfma_f32_16x16x32_bf16 v[100:103], v[132:135], v[204:207], v[100:103]
	v_mfma_f32_16x16x32_bf16 v[96:99], v[140:143], v[204:207], v[96:99]
	s_setprio 0
	s_setprio 1
	v_mfma_f32_16x16x32_bf16 v[60:63], v[144:147], v[160:163], v[60:63]
	v_mfma_f32_16x16x32_bf16 v[56:59], v[152:155], v[160:163], v[56:59]
	v_mfma_f32_16x16x32_bf16 v[52:55], v[144:147], v[168:171], v[52:55]
	v_mfma_f32_16x16x32_bf16 v[48:51], v[152:155], v[168:171], v[48:51]
	v_mfma_f32_16x16x32_bf16 v[44:47], v[144:147], v[192:195], v[44:47]
	v_mfma_f32_16x16x32_bf16 v[40:43], v[152:155], v[192:195], v[40:43]
	v_mfma_f32_16x16x32_bf16 v[36:39], v[144:147], v[200:203], v[36:39]
	v_mfma_f32_16x16x32_bf16 v[32:35], v[152:155], v[200:203], v[32:35]
	v_mfma_f32_16x16x32_bf16 v[60:63], v[148:151], v[164:167], v[60:63]
	v_mfma_f32_16x16x32_bf16 v[56:59], v[156:159], v[164:167], v[56:59]
	v_mfma_f32_16x16x32_bf16 v[52:55], v[148:151], v[188:191], v[52:55]
	v_mfma_f32_16x16x32_bf16 v[48:51], v[156:159], v[188:191], v[48:51]
	v_mfma_f32_16x16x32_bf16 v[44:47], v[148:151], v[196:199], v[44:47]
	v_mfma_f32_16x16x32_bf16 v[40:43], v[156:159], v[196:199], v[40:43]
	v_mfma_f32_16x16x32_bf16 v[36:39], v[148:151], v[204:207], v[36:39]
	v_mfma_f32_16x16x32_bf16 v[32:35], v[156:159], v[204:207], v[32:35]
	s_barrier
	s_setprio 0
	s_add_i32 s8, s73, s3
	v_lshl_add_u64 v[208:209], s[60:61], 0, v[174:175]
	s_mov_b32 m0, s8
	ds_read_b128 v[160:163], v241 offset:16384
	ds_read_b128 v[164:167], v241 offset:17408
	ds_read_b128 v[168:171], v241 offset:18432
	ds_read_b128 v[188:191], v241 offset:19456
	ds_read_b128 v[192:195], v241 offset:20480
	ds_read_b128 v[196:199], v241 offset:21504
	ds_read_b128 v[200:203], v241 offset:22528
	ds_read_b128 v[204:207], v241 offset:23552
	global_load_lds_dwordx4 v[208:209], off
	s_add_i32 m0, s8, 0x2000
	s_add_u32 s8, s60, 0x80000
	v_lshl_add_u64 v[210:211], s[60:61], 0, v[178:179]
	s_addc_u32 s9, s61, 0
	s_add_i32 s37, s74, s3
	global_load_lds_dwordx4 v[210:211], off
	v_lshl_add_u64 v[212:213], s[8:9], 0, v[174:175]
	s_mov_b32 m0, s37
	v_lshl_add_u64 v[216:217], s[62:63], 0, v[176:177]
	global_load_lds_dwordx4 v[212:213], off
	v_lshl_add_u64 v[212:213], s[8:9], 0, v[178:179]
	s_add_i32 m0, s37, 0x2000
	s_nop 0
	global_load_lds_dwordx4 v[212:213], off
	v_lshl_add_u64 v[212:213], s[62:63], 0, v[172:173]
	s_mov_b32 m0, s57
	s_nop 0
	global_load_lds_dwordx4 v[212:213], off
	s_mov_b32 m0, s64
	s_nop 0
	global_load_lds_dwordx4 v[216:217], off
	s_waitcnt vmcnt(8)
	s_waitcnt lgkmcnt(0)
	s_setprio 1
	s_barrier
; #define PG8_STAGE(bufoff, gbase, voff) do { _Pragma("unroll") for (int _i = 0; _i < 2; ++_i) \
;         __builtin_amdgcn_global_load_lds((const unsigned*)((const char*)(gbase) + (voff)[_i]), (PG8_LAS unsigned*)(lds + (bufoff) + ldsw + _i * 8192), 16, 0, 0); } while (0)
; #define PG8_LDA(dst, b, h) do { _Pragma("unroll") for (int m = 0; m < 4; ++m) _Pragma("unroll") for (int k = 0; k < 2; ++k) dst[m][k] = *(const PG8_LAS bf16x8*)(lds + PG8_SA(b, h) + aoff + m * 2048 + k * 1024); } while (0)
; #define PG8_LDB(dst, b, h) do { _Pragma("unroll") for (int n = 0; n < 2; ++n) _Pragma("unroll") for (int k = 0; k < 2; ++k) dst[n][k] = *(const PG8_LAS bf16x8*)(lds + PG8_SB(b, h) + boff + n * 2048 + k * 1024); } while (0)
; #define PG8_MMA(ai, bj, At, Bt) do { __builtin_amdgcn_s_setprio(1); _Pragma("unroll") for (int m = 0; m < 4; ++m) _Pragma("unroll") for (int n = 0; n < 2; ++n) _Pragma("unroll") for (int k = 0; k < 2; ++k) \
;         acc[ai][bj][m][n] = __builtin_amdgcn_mfma_f32_16x16x32_bf16(Bt[n][k], At[m][k], acc[ai][bj][m][n], 0, 0, 0); __builtin_amdgcn_s_setprio(0); } while (0)
; #define PG8_WAIT_V(n) asm volatile("s_waitcnt vmcnt(" #n ")" ::: "memory")
; #define PG8_WAIT_L(n) asm volatile("s_waitcnt lgkmcnt(" #n ")" ::: "memory")
; #define PG8_BAR __builtin_amdgcn_s_barrier()
; #define PG8_SCHED __builtin_amdgcn_sched_barrier(0)
; template <class Epi, class Sched, bool ALIGN_EPI = false, bool SP2 = false>
; __device__ __forceinline__ void gemm_phase(PG8_LAS unsigned char* lds, const Gemm g, const Sched& S, const Epi& E, const int wid) {
;     ...
;             PG8_WAIT_V(8); PG8_WAIT_L(0); PG8_BAR; PG8_MMA(1, 0, At, B0); PG8_MMA(1, 1, At, B1); PG8_BAR; PG8_SCHED;
;             PG8_LDB(B0, 1, 0); PG8_LDB(B1, 1, 1); PG8_SCHED; PG8_LDA(At, 1, 0); PG8_STAGE(PG8_SA(0, 1), a2 + hstep, voffA);
;             PG8_WAIT_V(8); PG8_WAIT_L(0); PG8_BAR; PG8_MMA(0, 0, At, B0); PG8_MMA(0, 1, At, B1); PG8_BAR; PG8_SCHED;
	v_mfma_f32_16x16x32_bf16 v[92:95], v[128:131], v[160:163], v[92:95]
	v_mfma_f32_16x16x32_bf16 v[88:91], v[136:139], v[160:163], v[88:91]
	v_mfma_f32_16x16x32_bf16 v[84:87], v[128:131], v[168:171], v[84:87]
	v_mfma_f32_16x16x32_bf16 v[80:83], v[136:139], v[168:171], v[80:83]
	v_mfma_f32_16x16x32_bf16 v[76:79], v[128:131], v[192:195], v[76:79]
	v_mfma_f32_16x16x32_bf16 v[72:75], v[136:139], v[192:195], v[72:75]
	v_mfma_f32_16x16x32_bf16 v[68:71], v[128:131], v[200:203], v[68:71]
	v_mfma_f32_16x16x32_bf16 v[64:67], v[136:139], v[200:203], v[64:67]
	v_mfma_f32_16x16x32_bf16 v[92:95], v[132:135], v[164:167], v[92:95]
	v_mfma_f32_16x16x32_bf16 v[88:91], v[140:143], v[164:167], v[88:91]
	v_mfma_f32_16x16x32_bf16 v[84:87], v[132:135], v[188:191], v[84:87]
	v_mfma_f32_16x16x32_bf16 v[80:83], v[140:143], v[188:191], v[80:83]
	v_mfma_f32_16x16x32_bf16 v[76:79], v[132:135], v[196:199], v[76:79]
	v_mfma_f32_16x16x32_bf16 v[72:75], v[140:143], v[196:199], v[72:75]
	v_mfma_f32_16x16x32_bf16 v[68:71], v[132:135], v[204:207], v[68:71]
	v_mfma_f32_16x16x32_bf16 v[64:67], v[140:143], v[204:207], v[64:67]
	s_setprio 0
	s_setprio 1
	v_mfma_f32_16x16x32_bf16 v[28:31], v[144:147], v[160:163], v[28:31]
	v_mfma_f32_16x16x32_bf16 v[24:27], v[152:155], v[160:163], v[24:27]
	v_mfma_f32_16x16x32_bf16 v[20:23], v[144:147], v[168:171], v[20:23]
	v_mfma_f32_16x16x32_bf16 v[16:19], v[152:155], v[168:171], v[16:19]
	v_mfma_f32_16x16x32_bf16 v[12:15], v[144:147], v[192:195], v[12:15]
	v_mfma_f32_16x16x32_bf16 v[8:11], v[152:155], v[192:195], v[8:11]
	v_mfma_f32_16x16x32_bf16 v[4:7], v[144:147], v[200:203], v[4:7]
	v_mfma_f32_16x16x32_bf16 v[0:3], v[152:155], v[200:203], v[0:3]
	v_mfma_f32_16x16x32_bf16 v[28:31], v[148:151], v[164:167], v[28:31]
	v_mfma_f32_16x16x32_bf16 v[24:27], v[156:159], v[164:167], v[24:27]
	v_mfma_f32_16x16x32_bf16 v[20:23], v[148:151], v[188:191], v[20:23]
	v_mfma_f32_16x16x32_bf16 v[16:19], v[156:159], v[188:191], v[16:19]
	v_mfma_f32_16x16x32_bf16 v[12:15], v[148:151], v[196:199], v[12:15]
	v_mfma_f32_16x16x32_bf16 v[8:11], v[156:159], v[196:199], v[8:11]
	v_mfma_f32_16x16x32_bf16 v[4:7], v[148:151], v[204:207], v[4:7]
	v_mfma_f32_16x16x32_bf16 v[0:3], v[156:159], v[204:207], v[0:3]
	s_barrier
	s_setprio 0
	s_add_i32 s37, 0, 0x18000
	s_add_i32 s79, 0, 0x1c000
	v_add_u32_e32 v140, s37, v231
	v_add_u32_e32 v156, s79, v231
	ds_read_b128 v[128:131], v140
	ds_read_b128 v[132:135], v140 offset:1024
	ds_read_b128 v[136:139], v140 offset:2048
	ds_read_b128 v[140:143], v140 offset:3072
	ds_read_b128 v[144:147], v156
	ds_read_b128 v[148:151], v156 offset:1024
	ds_read_b128 v[152:155], v156 offset:2048
	ds_read_b128 v[156:159], v156 offset:3072
	s_add_u32 s8, s62, 0x80000
	s_addc_u32 s9, s63, 0
	s_mov_b32 m0, s65
	v_lshl_add_u64 v[218:219], s[8:9], 0, v[172:173]
	ds_read_b128 v[160:163], v241 offset:32768
	ds_read_b128 v[164:167], v241 offset:33792
	ds_read_b128 v[168:171], v241 offset:34816
	ds_read_b128 v[188:191], v241 offset:35840
	ds_read_b128 v[192:195], v241 offset:36864
	ds_read_b128 v[196:199], v241 offset:37888
	ds_read_b128 v[200:203], v241 offset:38912
	ds_read_b128 v[204:207], v241 offset:39936
	global_load_lds_dwordx4 v[218:219], off
	v_lshl_add_u64 v[218:219], s[8:9], 0, v[176:177]
	s_mov_b32 m0, s66
	s_nop 0
	global_load_lds_dwordx4 v[218:219], off
	s_waitcnt vmcnt(8)
	s_waitcnt lgkmcnt(0)
	s_setprio 1
	s_barrier
	v_mfma_f32_16x16x32_bf16 v[124:127], v[128:131], v[160:163], v[124:127]
	v_mfma_f32_16x16x32_bf16 v[120:123], v[136:139], v[160:163], v[120:123]
	v_mfma_f32_16x16x32_bf16 v[116:119], v[128:131], v[168:171], v[116:119]
	v_mfma_f32_16x16x32_bf16 v[112:115], v[136:139], v[168:171], v[112:115]
	v_mfma_f32_16x16x32_bf16 v[108:111], v[128:131], v[192:195], v[108:111]
	v_mfma_f32_16x16x32_bf16 v[104:107], v[136:139], v[192:195], v[104:107]
	v_mfma_f32_16x16x32_bf16 v[100:103], v[128:131], v[200:203], v[100:103]
	v_mfma_f32_16x16x32_bf16 v[96:99], v[136:139], v[200:203], v[96:99]
	v_mfma_f32_16x16x32_bf16 v[124:127], v[132:135], v[164:167], v[124:127]
	v_mfma_f32_16x16x32_bf16 v[120:123], v[140:143], v[164:167], v[120:123]
	v_mfma_f32_16x16x32_bf16 v[116:119], v[132:135], v[188:191], v[116:119]
	v_mfma_f32_16x16x32_bf16 v[112:115], v[140:143], v[188:191], v[112:115]
	v_mfma_f32_16x16x32_bf16 v[108:111], v[132:135], v[196:199], v[108:111]
	v_mfma_f32_16x16x32_bf16 v[104:107], v[140:143], v[196:199], v[104:107]
	v_mfma_f32_16x16x32_bf16 v[100:103], v[132:135], v[204:207], v[100:103]
	v_mfma_f32_16x16x32_bf16 v[96:99], v[140:143], v[204:207], v[96:99]
	s_setprio 0
	s_setprio 1
	v_mfma_f32_16x16x32_bf16 v[60:63], v[144:147], v[160:163], v[60:63]
	v_mfma_f32_16x16x32_bf16 v[56:59], v[152:155], v[160:163], v[56:59]
	v_mfma_f32_16x16x32_bf16 v[52:55], v[144:147], v[168:171], v[52:55]
	v_mfma_f32_16x16x32_bf16 v[48:51], v[152:155], v[168:171], v[48:51]
	v_mfma_f32_16x16x32_bf16 v[44:47], v[144:147], v[192:195], v[44:47]
	v_mfma_f32_16x16x32_bf16 v[40:43], v[152:155], v[192:195], v[40:43]
	v_mfma_f32_16x16x32_bf16 v[36:39], v[144:147], v[200:203], v[36:39]
	v_mfma_f32_16x16x32_bf16 v[32:35], v[152:155], v[200:203], v[32:35]
	v_mfma_f32_16x16x32_bf16 v[60:63], v[148:151], v[164:167], v[60:63]
	v_mfma_f32_16x16x32_bf16 v[56:59], v[156:159], v[164:167], v[56:59]
	v_mfma_f32_16x16x32_bf16 v[52:55], v[148:151], v[188:191], v[52:55]
	v_mfma_f32_16x16x32_bf16 v[48:51], v[156:159], v[188:191], v[48:51]
	v_mfma_f32_16x16x32_bf16 v[44:47], v[148:151], v[196:199], v[44:47]
	v_mfma_f32_16x16x32_bf16 v[40:43], v[156:159], v[196:199], v[40:43]
	v_mfma_f32_16x16x32_bf16 v[36:39], v[148:151], v[204:207], v[36:39]
	v_mfma_f32_16x16x32_bf16 v[32:35], v[156:159], v[204:207], v[32:35]
	s_barrier
; #define PG8_STAGE(bufoff, gbase, voff) do { _Pragma("unroll") for (int _i = 0; _i < 2; ++_i) \
;         __builtin_amdgcn_global_load_lds((const unsigned*)((const char*)(gbase) + (voff)[_i]), (PG8_LAS unsigned*)(lds + (bufoff) + ldsw + _i * 8192), 16, 0, 0); } while (0)
; #define PG8_LDA(dst, b, h) do { _Pragma("unroll") for (int m = 0; m < 4; ++m) _Pragma("unroll") for (int k = 0; k < 2; ++k) dst[m][k] = *(const PG8_LAS bf16x8*)(lds + PG8_SA(b, h) + aoff + m * 2048 + k * 1024); } while (0)
; #define PG8_MMA(ai, bj, At, Bt) do { __builtin_amdgcn_s_setprio(1); _Pragma("unroll") for (int m = 0; m < 4; ++m) _Pragma("unroll") for (int n = 0; n < 2; ++n) _Pragma("unroll") for (int k = 0; k < 2; ++k) \
;         acc[ai][bj][m][n] = __builtin_amdgcn_mfma_f32_16x16x32_bf16(Bt[n][k], At[m][k], acc[ai][bj][m][n], 0, 0, 0); __builtin_amdgcn_s_setprio(0); } while (0)
; #define PG8_WAIT_V(n) asm volatile("s_waitcnt vmcnt(" #n ")" ::: "memory")
; #define PG8_WAIT_L(n) asm volatile("s_waitcnt lgkmcnt(" #n ")" ::: "memory")
; #define PG8_BAR __builtin_amdgcn_s_barrier()
; #define PG8_SCHED __builtin_amdgcn_sched_barrier(0)
; template <class Epi, class Sched, bool ALIGN_EPI = false, bool SP2 = false>
; __device__ __forceinline__ void gemm_phase(PG8_LAS unsigned char* lds, const Gemm g, const Sched& S, const Epi& E, const int wid) {
;     ...
;             PG8_LDA(At, 1, 1); PG8_STAGE(PG8_SB(1, 0), b3, voffB); PG8_STAGE(PG8_SB(1, 1), b3 + hstep, voffB); PG8_STAGE(PG8_SA(1, 0), a3, voffA);
;             PG8_WAIT_V(8); PG8_WAIT_L(0); PG8_BAR; PG8_MMA(1, 0, At, B0); PG8_MMA(1, 1, At, B1); PG8_BAR; PG8_SCHED;
;     ...
;         if constexpr (ALIGN_EPI) { if (wr == 0) PG8_BAR; }
	s_setprio 0
	s_add_i32 s8, s37, s3
	v_lshl_add_u64 v[208:209], v[208:209], 0, s[44:45]
	s_mov_b32 m0, s8
	ds_read_b128 v[160:163], v241 offset:49152
	ds_read_b128 v[164:167], v241 offset:50176
	ds_read_b128 v[168:171], v241 offset:51200
	ds_read_b128 v[188:191], v241 offset:52224
	ds_read_b128 v[192:195], v241 offset:53248
	ds_read_b128 v[196:199], v241 offset:54272
	ds_read_b128 v[200:203], v241 offset:55296
	ds_read_b128 v[204:207], v241 offset:56320
	global_load_lds_dwordx4 v[208:209], off
	s_add_i32 m0, s8, 0x2000
	s_add_u32 s8, s60, 0x80080
	v_lshl_add_u64 v[208:209], v[210:211], 0, s[44:45]
	s_addc_u32 s9, s61, 0
	s_add_i32 s37, s79, s3
	global_load_lds_dwordx4 v[208:209], off
	v_lshl_add_u64 v[208:209], s[8:9], 0, v[174:175]
	s_mov_b32 m0, s37
	s_nop 0
	global_load_lds_dwordx4 v[208:209], off
	v_lshl_add_u64 v[208:209], s[8:9], 0, v[178:179]
	s_add_i32 m0, s37, 0x2000
	s_nop 0
	global_load_lds_dwordx4 v[208:209], off
	v_lshl_add_u64 v[208:209], v[212:213], 0, s[44:45]
	s_mov_b32 m0, s68
	s_nop 0
	global_load_lds_dwordx4 v[208:209], off
	v_lshl_add_u64 v[208:209], v[216:217], 0, s[44:45]
	s_mov_b32 m0, s69
	s_nop 0
	global_load_lds_dwordx4 v[208:209], off
	s_waitcnt vmcnt(8)
	s_waitcnt lgkmcnt(0)
	s_setprio 1
	s_barrier
	v_mfma_f32_16x16x32_bf16 v[92:95], v[128:131], v[160:163], v[92:95]
	v_mfma_f32_16x16x32_bf16 v[88:91], v[136:139], v[160:163], v[88:91]
	v_mfma_f32_16x16x32_bf16 v[84:87], v[128:131], v[168:171], v[84:87]
	v_mfma_f32_16x16x32_bf16 v[80:83], v[136:139], v[168:171], v[80:83]
	v_mfma_f32_16x16x32_bf16 v[76:79], v[128:131], v[192:195], v[76:79]
	v_mfma_f32_16x16x32_bf16 v[72:75], v[136:139], v[192:195], v[72:75]
	v_mfma_f32_16x16x32_bf16 v[68:71], v[128:131], v[200:203], v[68:71]
	v_mfma_f32_16x16x32_bf16 v[64:67], v[136:139], v[200:203], v[64:67]
	v_mfma_f32_16x16x32_bf16 v[92:95], v[132:135], v[164:167], v[92:95]
	v_mfma_f32_16x16x32_bf16 v[88:91], v[140:143], v[164:167], v[88:91]
	v_mfma_f32_16x16x32_bf16 v[84:87], v[132:135], v[188:191], v[84:87]
	v_mfma_f32_16x16x32_bf16 v[80:83], v[140:143], v[188:191], v[80:83]
	v_mfma_f32_16x16x32_bf16 v[76:79], v[132:135], v[196:199], v[76:79]
	v_mfma_f32_16x16x32_bf16 v[72:75], v[140:143], v[196:199], v[72:75]
	v_mfma_f32_16x16x32_bf16 v[68:71], v[132:135], v[204:207], v[68:71]
	v_mfma_f32_16x16x32_bf16 v[64:67], v[140:143], v[204:207], v[64:67]
	s_setprio 0
	s_setprio 1
	v_mfma_f32_16x16x32_bf16 v[28:31], v[144:147], v[160:163], v[28:31]
	v_mfma_f32_16x16x32_bf16 v[24:27], v[152:155], v[160:163], v[24:27]
	v_mfma_f32_16x16x32_bf16 v[20:23], v[144:147], v[168:171], v[20:23]
	v_mfma_f32_16x16x32_bf16 v[16:19], v[152:155], v[168:171], v[16:19]
	v_mfma_f32_16x16x32_bf16 v[12:15], v[144:147], v[192:195], v[12:15]
	v_mfma_f32_16x16x32_bf16 v[8:11], v[152:155], v[192:195], v[8:11]
	v_mfma_f32_16x16x32_bf16 v[4:7], v[144:147], v[200:203], v[4:7]
	v_mfma_f32_16x16x32_bf16 v[0:3], v[152:155], v[200:203], v[0:3]
	v_mfma_f32_16x16x32_bf16 v[28:31], v[148:151], v[164:167], v[28:31]
	v_mfma_f32_16x16x32_bf16 v[24:27], v[156:159], v[164:167], v[24:27]
	v_mfma_f32_16x16x32_bf16 v[20:23], v[148:151], v[188:191], v[20:23]
	v_mfma_f32_16x16x32_bf16 v[16:19], v[156:159], v[188:191], v[16:19]
	v_mfma_f32_16x16x32_bf16 v[12:15], v[148:151], v[196:199], v[12:15]
	v_mfma_f32_16x16x32_bf16 v[8:11], v[156:159], v[196:199], v[8:11]
	v_mfma_f32_16x16x32_bf16 v[4:7], v[148:151], v[204:207], v[4:7]
	v_mfma_f32_16x16x32_bf16 v[0:3], v[156:159], v[204:207], v[0:3]
	s_barrier
	s_setprio 0
	s_add_i32 s88, s88, 2
	s_add_u32 s58, s58, 0x100
	s_addc_u32 s59, s59, 0
	s_add_u32 s86, s86, 0x100
	s_addc_u32 s87, s87, 0
	s_cmp_gt_u32 s88, 29
	s_cbranch_scc0 .LBB0_1389
	s_and_b64 vcc, exec, s[20:21]
	s_cbranch_vccz .LBB0_1392
	s_barrier

; #define PG8_STAGE(bufoff, gbase, voff) do { _Pragma("unroll") for (int _i = 0; _i < 2; ++_i) \
;         __builtin_amdgcn_global_load_lds((const unsigned*)((const char*)(gbase) + (voff)[_i]), (PG8_LAS unsigned*)(lds + (bufoff) + ldsw + _i * 8192), 16, 0, 0); } while (0)
; #define PG8_LDA(dst, b, h) do { _Pragma("unroll") for (int m = 0; m < 4; ++m) _Pragma("unroll") for (int k = 0; k < 2; ++k) dst[m][k] = *(const PG8_LAS bf16x8*)(lds + PG8_SA(b, h) + aoff + m * 2048 + k * 1024); } while (0)
; #define PG8_LDB(dst, b, h) do { _Pragma("unroll") for (int n = 0; n < 2; ++n) _Pragma("unroll") for (int k = 0; k < 2; ++k) dst[n][k] = *(const PG8_LAS bf16x8*)(lds + PG8_SB(b, h) + boff + n * 2048 + k * 1024); } while (0)
; #define PG8_MMA(ai, bj, At, Bt) do { __builtin_amdgcn_s_setprio(1); _Pragma("unroll") for (int m = 0; m < 4; ++m) _Pragma("unroll") for (int n = 0; n < 2; ++n) _Pragma("unroll") for (int k = 0; k < 2; ++k) \
;         acc[ai][bj][m][n] = __builtin_amdgcn_mfma_f32_16x16x32_bf16(Bt[n][k], At[m][k], acc[ai][bj][m][n], 0, 0, 0); __builtin_amdgcn_s_setprio(0); } while (0)
; #define PG8_WAIT_V(n) asm volatile("s_waitcnt vmcnt(" #n ")" ::: "memory")
; #define PG8_WAIT_L(n) asm volatile("s_waitcnt lgkmcnt(" #n ")" ::: "memory")
; template <class Epi, class Sched, bool ALIGN_EPI = false, bool SP2 = false>
; __device__ __forceinline__ void gemm_phase(PG8_LAS unsigned char* lds, const Gemm g, const Sched& S, const Epi& E, const int wid) {
;     ...
;             const bool last = (t == nt - 2);
;             const char* a1 = cA + (size_t)(t + 1) * kstep;
;             const char* a2 = last ? nA : cA + (size_t)(t + 2) * kstep; const char* b2 = last ? nB : cB + (size_t)(t + 2) * kstep;
;             const char* a3 = a2 + kstep; const char* b3 = b2 + kstep;
;             if (last && has_next) S.a_ready(nxt);
;             if constexpr (SP2) {
;             PG8_LDB(B0, 0, 0); PG8_LDB(B1, 0, 1); PG8_SCHED; PG8_LDA(At, 0, 0); PG8_STAGE(PG8_SA(1, 1), a1 + hstep, voffA);
;             PG8_WAIT_V(8); PG8_WAIT_L(0); PG8_BAR; PG8_MMA(0, 0, At, B0); PG8_MMA(0, 1, At, B1); PG8_BAR; PG8_SCHED;
;             PG8_LDA(At, 0, 1); PG8_STAGE(PG8_SB(0, 0), b2, voffB); PG8_STAGE(PG8_SB(0, 1), b2 + hstep, voffB); PG8_STAGE(PG8_SA(0, 0), a2, voffA);
;             PG8_WAIT_V(8); PG8_WAIT_L(0); PG8_BAR; PG8_MMA(1, 0, At, B0); PG8_MMA(1, 1, At, B1); PG8_BAR; PG8_SCHED;
.LBB0_1475:
	ds_read_b128 v[128:131], v167
	ds_read_b128 v[132:135], v167 offset:1024
	ds_read_b128 v[136:139], v167 offset:2048
	ds_read_b128 v[140:143], v167 offset:3072
	ds_read_b128 v[174:177], v169
	ds_read_b128 v[178:181], v169 offset:1024
	ds_read_b128 v[182:185], v169 offset:2048
	ds_read_b128 v[186:189], v169 offset:3072
	s_add_u32 s8, s14, 0xfff80080
	s_addc_u32 s9, s15, -1
	s_cmp_eq_u32 s72, 28
	s_cselect_b32 s53, s13, s9
	s_cselect_b32 s52, s45, s8
	s_cselect_b32 s51, s31, s71
	s_cselect_b32 s50, s69, s70
	v_lshl_add_u64 v[222:223], s[14:15], 0, v[154:155]
	s_add_i32 m0, s55, 0xc000
	ds_read_b128 v[190:193], v171
	ds_read_b128 v[194:197], v171 offset:1024
	ds_read_b128 v[198:201], v171 offset:2048
	ds_read_b128 v[202:205], v171 offset:3072
	ds_read_b128 v[206:209], v171 offset:4096
	ds_read_b128 v[210:213], v171 offset:5120
	ds_read_b128 v[214:217], v171 offset:6144
	ds_read_b128 v[218:221], v171 offset:7168
	global_load_lds_dwordx4 v[222:223], off
	v_lshl_add_u64 v[222:223], s[14:15], 0, v[152:153]
	s_add_i32 m0, s55, 0xe000
	s_nop 0
	global_load_lds_dwordx4 v[222:223], off
	s_waitcnt vmcnt(8)
	s_waitcnt lgkmcnt(0)
	s_setprio 1
	s_barrier
	v_mfma_f32_16x16x32_bf16 v[124:127], v[128:131], v[190:193], v[124:127]
	v_mfma_f32_16x16x32_bf16 v[120:123], v[136:139], v[190:193], v[120:123]
	v_mfma_f32_16x16x32_bf16 v[116:119], v[128:131], v[198:201], v[116:119]
	v_mfma_f32_16x16x32_bf16 v[112:115], v[136:139], v[198:201], v[112:115]
	v_mfma_f32_16x16x32_bf16 v[108:111], v[128:131], v[206:209], v[108:111]
	v_mfma_f32_16x16x32_bf16 v[104:107], v[136:139], v[206:209], v[104:107]
	v_mfma_f32_16x16x32_bf16 v[100:103], v[128:131], v[214:217], v[100:103]
	v_mfma_f32_16x16x32_bf16 v[96:99], v[136:139], v[214:217], v[96:99]
	v_mfma_f32_16x16x32_bf16 v[124:127], v[132:135], v[194:197], v[124:127]
	v_mfma_f32_16x16x32_bf16 v[120:123], v[140:143], v[194:197], v[120:123]
	v_mfma_f32_16x16x32_bf16 v[116:119], v[132:135], v[202:205], v[116:119]
	v_mfma_f32_16x16x32_bf16 v[112:115], v[140:143], v[202:205], v[112:115]
	v_mfma_f32_16x16x32_bf16 v[108:111], v[132:135], v[210:213], v[108:111]
	v_mfma_f32_16x16x32_bf16 v[104:107], v[140:143], v[210:213], v[104:107]
	v_mfma_f32_16x16x32_bf16 v[100:103], v[132:135], v[218:221], v[100:103]
	v_mfma_f32_16x16x32_bf16 v[96:99], v[140:143], v[218:221], v[96:99]
	s_setprio 0
	s_setprio 1
	v_mfma_f32_16x16x32_bf16 v[68:71], v[174:177], v[190:193], v[68:71]
	v_mfma_f32_16x16x32_bf16 v[60:63], v[182:185], v[190:193], v[60:63]
	v_mfma_f32_16x16x32_bf16 v[52:55], v[174:177], v[198:201], v[52:55]
	v_mfma_f32_16x16x32_bf16 v[48:51], v[182:185], v[198:201], v[48:51]
	v_mfma_f32_16x16x32_bf16 v[44:47], v[174:177], v[206:209], v[44:47]
	v_mfma_f32_16x16x32_bf16 v[40:43], v[182:185], v[206:209], v[40:43]
	v_mfma_f32_16x16x32_bf16 v[36:39], v[174:177], v[214:217], v[36:39]
	v_mfma_f32_16x16x32_bf16 v[32:35], v[182:185], v[214:217], v[32:35]
	v_mfma_f32_16x16x32_bf16 v[68:71], v[178:181], v[194:197], v[68:71]
	v_mfma_f32_16x16x32_bf16 v[60:63], v[186:189], v[194:197], v[60:63]
	v_mfma_f32_16x16x32_bf16 v[52:55], v[178:181], v[202:205], v[52:55]
	v_mfma_f32_16x16x32_bf16 v[48:51], v[186:189], v[202:205], v[48:51]
	v_mfma_f32_16x16x32_bf16 v[44:47], v[178:181], v[210:213], v[44:47]
	v_mfma_f32_16x16x32_bf16 v[40:43], v[186:189], v[210:213], v[40:43]
	v_mfma_f32_16x16x32_bf16 v[36:39], v[178:181], v[218:221], v[36:39]
	v_mfma_f32_16x16x32_bf16 v[32:35], v[186:189], v[218:221], v[32:35]
	s_barrier
	s_setprio 0
	s_add_i32 s8, s63, s3
	v_lshl_add_u64 v[222:223], s[50:51], 0, v[148:149]
	s_mov_b32 m0, s8
	ds_read_b128 v[190:193], v171 offset:16384
	ds_read_b128 v[194:197], v171 offset:17408
	ds_read_b128 v[198:201], v171 offset:18432
	ds_read_b128 v[202:205], v171 offset:19456
	ds_read_b128 v[206:209], v171 offset:20480
	ds_read_b128 v[210:213], v171 offset:21504
	ds_read_b128 v[214:217], v171 offset:22528
	ds_read_b128 v[218:221], v171 offset:23552
	global_load_lds_dwordx4 v[222:223], off
	s_add_i32 m0, s8, 0x2000
	s_add_u32 s8, s50, 0x80000
	v_lshl_add_u64 v[224:225], s[50:51], 0, v[144:145]
	s_addc_u32 s9, s51, 0
	s_add_i32 s37, s64, s3
	global_load_lds_dwordx4 v[224:225], off
	v_lshl_add_u64 v[226:227], s[8:9], 0, v[148:149]
	s_mov_b32 m0, s37
	v_lshl_add_u64 v[228:229], s[52:53], 0, v[146:147]
	global_load_lds_dwordx4 v[226:227], off
	v_lshl_add_u64 v[226:227], s[8:9], 0, v[144:145]
	s_add_i32 m0, s37, 0x2000
	s_nop 0
	global_load_lds_dwordx4 v[226:227], off
	v_lshl_add_u64 v[226:227], s[52:53], 0, v[150:151]
	s_mov_b32 m0, s55
	s_nop 0
	global_load_lds_dwordx4 v[226:227], off
	s_mov_b32 m0, s56
	s_nop 0
	global_load_lds_dwordx4 v[228:229], off
	s_waitcnt vmcnt(8)
	s_waitcnt lgkmcnt(0)
	s_setprio 1
	s_barrier
; #define PG8_STAGE(bufoff, gbase, voff) do { _Pragma("unroll") for (int _i = 0; _i < 2; ++_i) \
;         __builtin_amdgcn_global_load_lds((const unsigned*)((const char*)(gbase) + (voff)[_i]), (PG8_LAS unsigned*)(lds + (bufoff) + ldsw + _i * 8192), 16, 0, 0); } while (0)
; #define PG8_LDA(dst, b, h) do { _Pragma("unroll") for (int m = 0; m < 4; ++m) _Pragma("unroll") for (int k = 0; k < 2; ++k) dst[m][k] = *(const PG8_LAS bf16x8*)(lds + PG8_SA(b, h) + aoff + m * 2048 + k * 1024); } while (0)
; #define PG8_LDB(dst, b, h) do { _Pragma("unroll") for (int n = 0; n < 2; ++n) _Pragma("unroll") for (int k = 0; k < 2; ++k) dst[n][k] = *(const PG8_LAS bf16x8*)(lds + PG8_SB(b, h) + boff + n * 2048 + k * 1024); } while (0)
; #define PG8_MMA(ai, bj, At, Bt) do { __builtin_amdgcn_s_setprio(1); _Pragma("unroll") for (int m = 0; m < 4; ++m) _Pragma("unroll") for (int n = 0; n < 2; ++n) _Pragma("unroll") for (int k = 0; k < 2; ++k) \
;         acc[ai][bj][m][n] = __builtin_amdgcn_mfma_f32_16x16x32_bf16(Bt[n][k], At[m][k], acc[ai][bj][m][n], 0, 0, 0); __builtin_amdgcn_s_setprio(0); } while (0)
; #define PG8_WAIT_V(n) asm volatile("s_waitcnt vmcnt(" #n ")" ::: "memory")
; #define PG8_WAIT_L(n) asm volatile("s_waitcnt lgkmcnt(" #n ")" ::: "memory")
; #define PG8_BAR __builtin_amdgcn_s_barrier()
; #define PG8_SCHED __builtin_amdgcn_sched_barrier(0)
; template <class Epi, class Sched, bool ALIGN_EPI = false, bool SP2 = false>
; __device__ __forceinline__ void gemm_phase(PG8_LAS unsigned char* lds, const Gemm g, const Sched& S, const Epi& E, const int wid) {
;     ...
;             PG8_WAIT_V(8); PG8_WAIT_L(0); PG8_BAR; PG8_MMA(1, 0, At, B0); PG8_MMA(1, 1, At, B1); PG8_BAR; PG8_SCHED;
;             PG8_LDB(B0, 1, 0); PG8_LDB(B1, 1, 1); PG8_SCHED; PG8_LDA(At, 1, 0); PG8_STAGE(PG8_SA(0, 1), a2 + hstep, voffA);
;             PG8_WAIT_V(8); PG8_WAIT_L(0); PG8_BAR; PG8_MMA(0, 0, At, B0); PG8_MMA(0, 1, At, B1); PG8_BAR; PG8_SCHED;
	v_mfma_f32_16x16x32_bf16 v[92:95], v[128:131], v[190:193], v[92:95]
	v_mfma_f32_16x16x32_bf16 v[88:91], v[136:139], v[190:193], v[88:91]
	v_mfma_f32_16x16x32_bf16 v[84:87], v[128:131], v[198:201], v[84:87]
	v_mfma_f32_16x16x32_bf16 v[80:83], v[136:139], v[198:201], v[80:83]
	v_mfma_f32_16x16x32_bf16 v[76:79], v[128:131], v[206:209], v[76:79]
	v_mfma_f32_16x16x32_bf16 v[72:75], v[136:139], v[206:209], v[72:75]
	v_mfma_f32_16x16x32_bf16 v[64:67], v[128:131], v[214:217], v[64:67]
	v_mfma_f32_16x16x32_bf16 v[56:59], v[136:139], v[214:217], v[56:59]
	v_mfma_f32_16x16x32_bf16 v[92:95], v[132:135], v[194:197], v[92:95]
	v_mfma_f32_16x16x32_bf16 v[88:91], v[140:143], v[194:197], v[88:91]
	v_mfma_f32_16x16x32_bf16 v[84:87], v[132:135], v[202:205], v[84:87]
	v_mfma_f32_16x16x32_bf16 v[80:83], v[140:143], v[202:205], v[80:83]
	v_mfma_f32_16x16x32_bf16 v[76:79], v[132:135], v[210:213], v[76:79]
	v_mfma_f32_16x16x32_bf16 v[72:75], v[140:143], v[210:213], v[72:75]
	v_mfma_f32_16x16x32_bf16 v[64:67], v[132:135], v[218:221], v[64:67]
	v_mfma_f32_16x16x32_bf16 v[56:59], v[140:143], v[218:221], v[56:59]
	s_setprio 0
	s_setprio 1
	v_mfma_f32_16x16x32_bf16 v[28:31], v[174:177], v[190:193], v[28:31]
	v_mfma_f32_16x16x32_bf16 v[24:27], v[182:185], v[190:193], v[24:27]
	v_mfma_f32_16x16x32_bf16 v[20:23], v[174:177], v[198:201], v[20:23]
	v_mfma_f32_16x16x32_bf16 v[16:19], v[182:185], v[198:201], v[16:19]
	v_mfma_f32_16x16x32_bf16 v[12:15], v[174:177], v[206:209], v[12:15]
	v_mfma_f32_16x16x32_bf16 v[8:11], v[182:185], v[206:209], v[8:11]
	v_mfma_f32_16x16x32_bf16 v[4:7], v[174:177], v[214:217], v[4:7]
	v_mfma_f32_16x16x32_bf16 v[0:3], v[182:185], v[214:217], v[0:3]
	v_mfma_f32_16x16x32_bf16 v[28:31], v[178:181], v[194:197], v[28:31]
	v_mfma_f32_16x16x32_bf16 v[24:27], v[186:189], v[194:197], v[24:27]
	v_mfma_f32_16x16x32_bf16 v[20:23], v[178:181], v[202:205], v[20:23]
	v_mfma_f32_16x16x32_bf16 v[16:19], v[186:189], v[202:205], v[16:19]
	v_mfma_f32_16x16x32_bf16 v[12:15], v[178:181], v[210:213], v[12:15]
	v_mfma_f32_16x16x32_bf16 v[8:11], v[186:189], v[210:213], v[8:11]
	v_mfma_f32_16x16x32_bf16 v[4:7], v[178:181], v[218:221], v[4:7]
	v_mfma_f32_16x16x32_bf16 v[0:3], v[186:189], v[218:221], v[0:3]
	s_barrier
	s_setprio 0
	s_add_i32 s37, 0, 0x18000
	s_add_i32 s73, 0, 0x1c000
	v_add_u32_e32 v140, s37, v163
	v_add_u32_e32 v160, s73, v163
	ds_read_b128 v[128:131], v140
	ds_read_b128 v[132:135], v140 offset:1024
	ds_read_b128 v[136:139], v140 offset:2048
	ds_read_b128 v[140:143], v140 offset:3072
	ds_read_b128 v[174:177], v160
	ds_read_b128 v[178:181], v160 offset:1024
	ds_read_b128 v[182:185], v160 offset:2048
	ds_read_b128 v[186:189], v160 offset:3072
	s_add_u32 s8, s52, 0x80000
	s_addc_u32 s9, s53, 0
	s_mov_b32 m0, s57
	v_lshl_add_u64 v[230:231], s[8:9], 0, v[150:151]
	ds_read_b128 v[190:193], v171 offset:32768
	ds_read_b128 v[194:197], v171 offset:33792
	ds_read_b128 v[198:201], v171 offset:34816
	ds_read_b128 v[202:205], v171 offset:35840
	ds_read_b128 v[206:209], v171 offset:36864
	ds_read_b128 v[210:213], v171 offset:37888
	ds_read_b128 v[214:217], v171 offset:38912
	ds_read_b128 v[218:221], v171 offset:39936
	global_load_lds_dwordx4 v[230:231], off
	v_lshl_add_u64 v[230:231], s[8:9], 0, v[146:147]
	s_mov_b32 m0, s58
	s_nop 0
	global_load_lds_dwordx4 v[230:231], off
	s_waitcnt vmcnt(8)
	s_waitcnt lgkmcnt(0)
	s_setprio 1
	s_barrier
	v_mfma_f32_16x16x32_bf16 v[124:127], v[128:131], v[190:193], v[124:127]
	v_mfma_f32_16x16x32_bf16 v[120:123], v[136:139], v[190:193], v[120:123]
	v_mfma_f32_16x16x32_bf16 v[116:119], v[128:131], v[198:201], v[116:119]
	v_mfma_f32_16x16x32_bf16 v[112:115], v[136:139], v[198:201], v[112:115]
	v_mfma_f32_16x16x32_bf16 v[108:111], v[128:131], v[206:209], v[108:111]
	v_mfma_f32_16x16x32_bf16 v[104:107], v[136:139], v[206:209], v[104:107]
	v_mfma_f32_16x16x32_bf16 v[100:103], v[128:131], v[214:217], v[100:103]
	v_mfma_f32_16x16x32_bf16 v[96:99], v[136:139], v[214:217], v[96:99]
	v_mfma_f32_16x16x32_bf16 v[124:127], v[132:135], v[194:197], v[124:127]
	v_mfma_f32_16x16x32_bf16 v[120:123], v[140:143], v[194:197], v[120:123]
	v_mfma_f32_16x16x32_bf16 v[116:119], v[132:135], v[202:205], v[116:119]
	v_mfma_f32_16x16x32_bf16 v[112:115], v[140:143], v[202:205], v[112:115]
	v_mfma_f32_16x16x32_bf16 v[108:111], v[132:135], v[210:213], v[108:111]
	v_mfma_f32_16x16x32_bf16 v[104:107], v[140:143], v[210:213], v[104:107]
	v_mfma_f32_16x16x32_bf16 v[100:103], v[132:135], v[218:221], v[100:103]
	v_mfma_f32_16x16x32_bf16 v[96:99], v[140:143], v[218:221], v[96:99]
	s_setprio 0
	s_setprio 1
	v_mfma_f32_16x16x32_bf16 v[68:71], v[174:177], v[190:193], v[68:71]
	v_mfma_f32_16x16x32_bf16 v[60:63], v[182:185], v[190:193], v[60:63]
	v_mfma_f32_16x16x32_bf16 v[52:55], v[174:177], v[198:201], v[52:55]
	v_mfma_f32_16x16x32_bf16 v[48:51], v[182:185], v[198:201], v[48:51]
	v_mfma_f32_16x16x32_bf16 v[44:47], v[174:177], v[206:209], v[44:47]
	v_mfma_f32_16x16x32_bf16 v[40:43], v[182:185], v[206:209], v[40:43]
	v_mfma_f32_16x16x32_bf16 v[36:39], v[174:177], v[214:217], v[36:39]
	v_mfma_f32_16x16x32_bf16 v[32:35], v[182:185], v[214:217], v[32:35]
	v_mfma_f32_16x16x32_bf16 v[68:71], v[178:181], v[194:197], v[68:71]
	v_mfma_f32_16x16x32_bf16 v[60:63], v[186:189], v[194:197], v[60:63]
	v_mfma_f32_16x16x32_bf16 v[52:55], v[178:181], v[202:205], v[52:55]
	v_mfma_f32_16x16x32_bf16 v[48:51], v[186:189], v[202:205], v[48:51]
	v_mfma_f32_16x16x32_bf16 v[44:47], v[178:181], v[210:213], v[44:47]
	v_mfma_f32_16x16x32_bf16 v[40:43], v[186:189], v[210:213], v[40:43]
	v_mfma_f32_16x16x32_bf16 v[36:39], v[178:181], v[218:221], v[36:39]
	v_mfma_f32_16x16x32_bf16 v[32:35], v[186:189], v[218:221], v[32:35]
	s_barrier
; #define PG8_STAGE(bufoff, gbase, voff) do { _Pragma("unroll") for (int _i = 0; _i < 2; ++_i) \
;         __builtin_amdgcn_global_load_lds((const unsigned*)((const char*)(gbase) + (voff)[_i]), (PG8_LAS unsigned*)(lds + (bufoff) + ldsw + _i * 8192), 16, 0, 0); } while (0)
; #define PG8_LDA(dst, b, h) do { _Pragma("unroll") for (int m = 0; m < 4; ++m) _Pragma("unroll") for (int k = 0; k < 2; ++k) dst[m][k] = *(const PG8_LAS bf16x8*)(lds + PG8_SA(b, h) + aoff + m * 2048 + k * 1024); } while (0)
; #define PG8_MMA(ai, bj, At, Bt) do { __builtin_amdgcn_s_setprio(1); _Pragma("unroll") for (int m = 0; m < 4; ++m) _Pragma("unroll") for (int n = 0; n < 2; ++n) _Pragma("unroll") for (int k = 0; k < 2; ++k) \
;         acc[ai][bj][m][n] = __builtin_amdgcn_mfma_f32_16x16x32_bf16(Bt[n][k], At[m][k], acc[ai][bj][m][n], 0, 0, 0); __builtin_amdgcn_s_setprio(0); } while (0)
; #define PG8_WAIT_V(n) asm volatile("s_waitcnt vmcnt(" #n ")" ::: "memory")
; #define PG8_WAIT_L(n) asm volatile("s_waitcnt lgkmcnt(" #n ")" ::: "memory")
; #define PG8_BAR __builtin_amdgcn_s_barrier()
; #define PG8_SCHED __builtin_amdgcn_sched_barrier(0)
; template <class Epi, class Sched, bool ALIGN_EPI = false, bool SP2 = false>
; __device__ __forceinline__ void gemm_phase(PG8_LAS unsigned char* lds, const Gemm g, const Sched& S, const Epi& E, const int wid) {
;     ...
;             PG8_LDA(At, 1, 1); PG8_STAGE(PG8_SB(1, 0), b3, voffB); PG8_STAGE(PG8_SB(1, 1), b3 + hstep, voffB); PG8_STAGE(PG8_SA(1, 0), a3, voffA);
;             PG8_WAIT_V(8); PG8_WAIT_L(0); PG8_BAR; PG8_MMA(1, 0, At, B0); PG8_MMA(1, 1, At, B1); PG8_BAR; PG8_SCHED;
;     ...
;         if constexpr (ALIGN_EPI) { if (wr == 0) PG8_BAR; }
	s_setprio 0
	s_add_i32 s8, s37, s3
	v_lshl_add_u64 v[222:223], v[222:223], 0, s[26:27]
	s_mov_b32 m0, s8
	ds_read_b128 v[190:193], v171 offset:49152
	ds_read_b128 v[194:197], v171 offset:50176
	ds_read_b128 v[198:201], v171 offset:51200
	ds_read_b128 v[202:205], v171 offset:52224
	ds_read_b128 v[206:209], v171 offset:53248
	ds_read_b128 v[210:213], v171 offset:54272
	ds_read_b128 v[214:217], v171 offset:55296
	ds_read_b128 v[218:221], v171 offset:56320
	global_load_lds_dwordx4 v[222:223], off
	s_add_i32 m0, s8, 0x2000
	s_add_u32 s8, s50, 0x80080
	v_lshl_add_u64 v[222:223], v[224:225], 0, s[26:27]
	s_addc_u32 s9, s51, 0
	s_add_i32 s37, s73, s3
	global_load_lds_dwordx4 v[222:223], off
	v_lshl_add_u64 v[222:223], s[8:9], 0, v[148:149]
	s_mov_b32 m0, s37
	s_nop 0
	global_load_lds_dwordx4 v[222:223], off
	v_lshl_add_u64 v[222:223], s[8:9], 0, v[144:145]
	s_add_i32 m0, s37, 0x2000
	s_nop 0
	global_load_lds_dwordx4 v[222:223], off
	v_lshl_add_u64 v[222:223], v[226:227], 0, s[26:27]
	s_mov_b32 m0, s60
	s_nop 0
	global_load_lds_dwordx4 v[222:223], off
	v_lshl_add_u64 v[222:223], v[228:229], 0, s[26:27]
	s_mov_b32 m0, s61
	s_nop 0
	global_load_lds_dwordx4 v[222:223], off
	s_waitcnt vmcnt(8)
	s_waitcnt lgkmcnt(0)
	s_setprio 1
	s_barrier
	v_mfma_f32_16x16x32_bf16 v[92:95], v[128:131], v[190:193], v[92:95]
	v_mfma_f32_16x16x32_bf16 v[88:91], v[136:139], v[190:193], v[88:91]
	v_mfma_f32_16x16x32_bf16 v[84:87], v[128:131], v[198:201], v[84:87]
	v_mfma_f32_16x16x32_bf16 v[80:83], v[136:139], v[198:201], v[80:83]
	v_mfma_f32_16x16x32_bf16 v[76:79], v[128:131], v[206:209], v[76:79]
	v_mfma_f32_16x16x32_bf16 v[72:75], v[136:139], v[206:209], v[72:75]
	v_mfma_f32_16x16x32_bf16 v[64:67], v[128:131], v[214:217], v[64:67]
	v_mfma_f32_16x16x32_bf16 v[56:59], v[136:139], v[214:217], v[56:59]
	v_mfma_f32_16x16x32_bf16 v[92:95], v[132:135], v[194:197], v[92:95]
	v_mfma_f32_16x16x32_bf16 v[88:91], v[140:143], v[194:197], v[88:91]
	v_mfma_f32_16x16x32_bf16 v[84:87], v[132:135], v[202:205], v[84:87]
	v_mfma_f32_16x16x32_bf16 v[80:83], v[140:143], v[202:205], v[80:83]
	v_mfma_f32_16x16x32_bf16 v[76:79], v[132:135], v[210:213], v[76:79]
	v_mfma_f32_16x16x32_bf16 v[72:75], v[140:143], v[210:213], v[72:75]
	v_mfma_f32_16x16x32_bf16 v[64:67], v[132:135], v[218:221], v[64:67]
	v_mfma_f32_16x16x32_bf16 v[56:59], v[140:143], v[218:221], v[56:59]
	s_setprio 0
	s_setprio 1
	v_mfma_f32_16x16x32_bf16 v[28:31], v[174:177], v[190:193], v[28:31]
	v_mfma_f32_16x16x32_bf16 v[24:27], v[182:185], v[190:193], v[24:27]
	v_mfma_f32_16x16x32_bf16 v[20:23], v[174:177], v[198:201], v[20:23]
	v_mfma_f32_16x16x32_bf16 v[16:19], v[182:185], v[198:201], v[16:19]
	v_mfma_f32_16x16x32_bf16 v[12:15], v[174:177], v[206:209], v[12:15]
	v_mfma_f32_16x16x32_bf16 v[8:11], v[182:185], v[206:209], v[8:11]
	v_mfma_f32_16x16x32_bf16 v[4:7], v[174:177], v[214:217], v[4:7]
	v_mfma_f32_16x16x32_bf16 v[0:3], v[182:185], v[214:217], v[0:3]
	v_mfma_f32_16x16x32_bf16 v[28:31], v[178:181], v[194:197], v[28:31]
	v_mfma_f32_16x16x32_bf16 v[24:27], v[186:189], v[194:197], v[24:27]
	v_mfma_f32_16x16x32_bf16 v[20:23], v[178:181], v[202:205], v[20:23]
	v_mfma_f32_16x16x32_bf16 v[16:19], v[186:189], v[202:205], v[16:19]
	v_mfma_f32_16x16x32_bf16 v[12:15], v[178:181], v[210:213], v[12:15]
	v_mfma_f32_16x16x32_bf16 v[8:11], v[186:189], v[210:213], v[8:11]
	v_mfma_f32_16x16x32_bf16 v[4:7], v[178:181], v[218:221], v[4:7]
	v_mfma_f32_16x16x32_bf16 v[0:3], v[186:189], v[218:221], v[0:3]
	s_barrier
	s_setprio 0
	s_add_i32 s72, s72, 2
	s_add_u32 s70, s70, 0x100
	s_addc_u32 s71, s71, 0
	s_add_u32 s14, s14, 0x100
	s_addc_u32 s15, s15, 0
	s_cmp_gt_u32 s72, 29
	s_cbranch_scc0 .LBB0_1475
	s_and_b64 vcc, exec, s[20:21]
	s_cbranch_vccz .LBB0_1478
	s_barrier

; #define PG8_STAGE(bufoff, gbase, voff) do { _Pragma("unroll") for (int _i = 0; _i < 2; ++_i) \
;         __builtin_amdgcn_global_load_lds((const unsigned*)((const char*)(gbase) + (voff)[_i]), (PG8_LAS unsigned*)(lds + (bufoff) + ldsw + _i * 8192), 16, 0, 0); } while (0)
; #define PG8_LDA(dst, b, h) do { _Pragma("unroll") for (int m = 0; m < 4; ++m) _Pragma("unroll") for (int k = 0; k < 2; ++k) dst[m][k] = *(const PG8_LAS bf16x8*)(lds + PG8_SA(b, h) + aoff + m * 2048 + k * 1024); } while (0)
; #define PG8_LDB(dst, b, h) do { _Pragma("unroll") for (int n = 0; n < 2; ++n) _Pragma("unroll") for (int k = 0; k < 2; ++k) dst[n][k] = *(const PG8_LAS bf16x8*)(lds + PG8_SB(b, h) + boff + n * 2048 + k * 1024); } while (0)
; #define PG8_MMA(ai, bj, At, Bt) do { __builtin_amdgcn_s_setprio(1); _Pragma("unroll") for (int m = 0; m < 4; ++m) _Pragma("unroll") for (int n = 0; n < 2; ++n) _Pragma("unroll") for (int k = 0; k < 2; ++k) \
;         acc[ai][bj][m][n] = __builtin_amdgcn_mfma_f32_16x16x32_bf16(Bt[n][k], At[m][k], acc[ai][bj][m][n], 0, 0, 0); __builtin_amdgcn_s_setprio(0); } while (0)
; #define PG8_WAIT_V(n) asm volatile("s_waitcnt vmcnt(" #n ")" ::: "memory")
; #define PG8_WAIT_L(n) asm volatile("s_waitcnt lgkmcnt(" #n ")" ::: "memory")
; template <class Epi, class Sched, bool ALIGN_EPI = false, bool SP2 = false>
; __device__ __forceinline__ void gemm_phase(PG8_LAS unsigned char* lds, const Gemm g, const Sched& S, const Epi& E, const int wid) {
;     ...
;             const bool last = (t == nt - 2);
;             const char* a1 = cA + (size_t)(t + 1) * kstep;
;             const char* a2 = last ? nA : cA + (size_t)(t + 2) * kstep; const char* b2 = last ? nB : cB + (size_t)(t + 2) * kstep;
;             const char* a3 = a2 + kstep; const char* b3 = b2 + kstep;
;             if (last && has_next) S.a_ready(nxt);
;             if constexpr (SP2) {
;             PG8_LDB(B0, 0, 0); PG8_LDB(B1, 0, 1); PG8_SCHED; PG8_LDA(At, 0, 0); PG8_STAGE(PG8_SA(1, 1), a1 + hstep, voffA);
;             PG8_WAIT_V(8); PG8_WAIT_L(0); PG8_BAR; PG8_MMA(0, 0, At, B0); PG8_MMA(0, 1, At, B1); PG8_BAR; PG8_SCHED;
;             PG8_LDA(At, 0, 1); PG8_STAGE(PG8_SB(0, 0), b2, voffB); PG8_STAGE(PG8_SB(0, 1), b2 + hstep, voffB); PG8_STAGE(PG8_SA(0, 0), a2, voffA);
;             PG8_WAIT_V(8); PG8_WAIT_L(0); PG8_BAR; PG8_MMA(1, 0, At, B0); PG8_MMA(1, 1, At, B1); PG8_BAR; PG8_SCHED;
.LBB0_1545:
	ds_read_b128 v[128:131], v209
	ds_read_b128 v[132:135], v209 offset:1024
	ds_read_b128 v[136:139], v209 offset:2048
	ds_read_b128 v[140:143], v209 offset:3072
	ds_read_b128 v[144:147], v210
	ds_read_b128 v[148:151], v210 offset:1024
	ds_read_b128 v[152:155], v210 offset:2048
	ds_read_b128 v[156:159], v210 offset:3072
	s_add_u32 s8, s12, 0xffe00080
	s_addc_u32 s9, s13, -1
	s_cmpk_eq_i32 s75, 0x7c
	s_cselect_b32 s57, s47, s9
	s_cselect_b32 s56, s71, s8
	s_cselect_b32 s55, s45, s74
	s_cselect_b32 s54, s72, s73
	v_lshl_add_u64 v[204:205], s[12:13], 0, v[178:179]
	s_add_i32 m0, s53, 0xc000
	ds_read_b128 v[160:163], v211
	ds_read_b128 v[164:167], v211 offset:1024
	ds_read_b128 v[184:187], v211 offset:2048
	ds_read_b128 v[188:191], v211 offset:3072
	ds_read_b128 v[192:195], v211 offset:4096
	ds_read_b128 v[196:199], v211 offset:5120
	ds_read_b128 v[200:203], v211 offset:6144
	ds_read_b128 v[214:217], v211 offset:7168
	global_load_lds_dwordx4 v[204:205], off
	v_lshl_add_u64 v[204:205], s[12:13], 0, v[176:177]
	s_add_i32 m0, s53, 0xe000
	s_nop 0
	global_load_lds_dwordx4 v[204:205], off
	s_waitcnt vmcnt(8)
	s_waitcnt lgkmcnt(0)
	s_setprio 1
	s_barrier
	v_mfma_f32_16x16x32_bf16 v[124:127], v[128:131], v[160:163], v[124:127]
	v_mfma_f32_16x16x32_bf16 v[120:123], v[136:139], v[160:163], v[120:123]
	v_mfma_f32_16x16x32_bf16 v[116:119], v[128:131], v[184:187], v[116:119]
	v_mfma_f32_16x16x32_bf16 v[112:115], v[136:139], v[184:187], v[112:115]
	v_mfma_f32_16x16x32_bf16 v[108:111], v[128:131], v[192:195], v[108:111]
	v_mfma_f32_16x16x32_bf16 v[104:107], v[136:139], v[192:195], v[104:107]
	v_mfma_f32_16x16x32_bf16 v[100:103], v[128:131], v[200:203], v[100:103]
	v_mfma_f32_16x16x32_bf16 v[96:99], v[136:139], v[200:203], v[96:99]
	v_mfma_f32_16x16x32_bf16 v[124:127], v[132:135], v[164:167], v[124:127]
	v_mfma_f32_16x16x32_bf16 v[120:123], v[140:143], v[164:167], v[120:123]
	v_mfma_f32_16x16x32_bf16 v[116:119], v[132:135], v[188:191], v[116:119]
	v_mfma_f32_16x16x32_bf16 v[112:115], v[140:143], v[188:191], v[112:115]
	v_mfma_f32_16x16x32_bf16 v[108:111], v[132:135], v[196:199], v[108:111]
	v_mfma_f32_16x16x32_bf16 v[104:107], v[140:143], v[196:199], v[104:107]
	v_mfma_f32_16x16x32_bf16 v[100:103], v[132:135], v[214:217], v[100:103]
	v_mfma_f32_16x16x32_bf16 v[96:99], v[140:143], v[214:217], v[96:99]
	s_setprio 0
	s_setprio 1
	v_mfma_f32_16x16x32_bf16 v[60:63], v[144:147], v[160:163], v[60:63]
	v_mfma_f32_16x16x32_bf16 v[56:59], v[152:155], v[160:163], v[56:59]
	v_mfma_f32_16x16x32_bf16 v[52:55], v[144:147], v[184:187], v[52:55]
	v_mfma_f32_16x16x32_bf16 v[48:51], v[152:155], v[184:187], v[48:51]
	v_mfma_f32_16x16x32_bf16 v[44:47], v[144:147], v[192:195], v[44:47]
	v_mfma_f32_16x16x32_bf16 v[40:43], v[152:155], v[192:195], v[40:43]
	v_mfma_f32_16x16x32_bf16 v[36:39], v[144:147], v[200:203], v[36:39]
	v_mfma_f32_16x16x32_bf16 v[32:35], v[152:155], v[200:203], v[32:35]
	v_mfma_f32_16x16x32_bf16 v[60:63], v[148:151], v[164:167], v[60:63]
	v_mfma_f32_16x16x32_bf16 v[56:59], v[156:159], v[164:167], v[56:59]
	v_mfma_f32_16x16x32_bf16 v[52:55], v[148:151], v[188:191], v[52:55]
	v_mfma_f32_16x16x32_bf16 v[48:51], v[156:159], v[188:191], v[48:51]
	v_mfma_f32_16x16x32_bf16 v[44:47], v[148:151], v[196:199], v[44:47]
	v_mfma_f32_16x16x32_bf16 v[40:43], v[156:159], v[196:199], v[40:43]
	v_mfma_f32_16x16x32_bf16 v[36:39], v[148:151], v[214:217], v[36:39]
	v_mfma_f32_16x16x32_bf16 v[32:35], v[156:159], v[214:217], v[32:35]
	s_barrier
	s_setprio 0
	s_add_i32 s8, s65, s3
	v_lshl_add_u64 v[204:205], s[54:55], 0, v[172:173]
	s_mov_b32 m0, s8
	ds_read_b128 v[160:163], v211 offset:16384
	ds_read_b128 v[164:167], v211 offset:17408
	ds_read_b128 v[184:187], v211 offset:18432
	ds_read_b128 v[188:191], v211 offset:19456
	ds_read_b128 v[192:195], v211 offset:20480
	ds_read_b128 v[196:199], v211 offset:21504
	ds_read_b128 v[200:203], v211 offset:22528
	ds_read_b128 v[214:217], v211 offset:23552
	global_load_lds_dwordx4 v[204:205], off
	s_add_i32 m0, s8, 0x2000
	s_add_u32 s8, s54, 0x200000
	v_lshl_add_u64 v[218:219], s[54:55], 0, v[168:169]
	s_addc_u32 s9, s55, 0
	s_add_i32 s37, s66, s3
	global_load_lds_dwordx4 v[218:219], off
	v_lshl_add_u64 v[220:221], s[8:9], 0, v[172:173]
	s_mov_b32 m0, s37
	v_lshl_add_u64 v[222:223], s[56:57], 0, v[170:171]
	global_load_lds_dwordx4 v[220:221], off
	v_lshl_add_u64 v[220:221], s[8:9], 0, v[168:169]
	s_add_i32 m0, s37, 0x2000
	s_nop 0
	global_load_lds_dwordx4 v[220:221], off
	v_lshl_add_u64 v[220:221], s[56:57], 0, v[174:175]
	s_mov_b32 m0, s53
	s_nop 0
	global_load_lds_dwordx4 v[220:221], off
	s_mov_b32 m0, s58
	s_nop 0
	global_load_lds_dwordx4 v[222:223], off
	s_waitcnt vmcnt(8)
	s_waitcnt lgkmcnt(0)
	s_setprio 1
	s_barrier
; #define PG8_STAGE(bufoff, gbase, voff) do { _Pragma("unroll") for (int _i = 0; _i < 2; ++_i) \
;         __builtin_amdgcn_global_load_lds((const unsigned*)((const char*)(gbase) + (voff)[_i]), (PG8_LAS unsigned*)(lds + (bufoff) + ldsw + _i * 8192), 16, 0, 0); } while (0)
; #define PG8_LDA(dst, b, h) do { _Pragma("unroll") for (int m = 0; m < 4; ++m) _Pragma("unroll") for (int k = 0; k < 2; ++k) dst[m][k] = *(const PG8_LAS bf16x8*)(lds + PG8_SA(b, h) + aoff + m * 2048 + k * 1024); } while (0)
; #define PG8_LDB(dst, b, h) do { _Pragma("unroll") for (int n = 0; n < 2; ++n) _Pragma("unroll") for (int k = 0; k < 2; ++k) dst[n][k] = *(const PG8_LAS bf16x8*)(lds + PG8_SB(b, h) + boff + n * 2048 + k * 1024); } while (0)
; #define PG8_MMA(ai, bj, At, Bt) do { __builtin_amdgcn_s_setprio(1); _Pragma("unroll") for (int m = 0; m < 4; ++m) _Pragma("unroll") for (int n = 0; n < 2; ++n) _Pragma("unroll") for (int k = 0; k < 2; ++k) \
;         acc[ai][bj][m][n] = __builtin_amdgcn_mfma_f32_16x16x32_bf16(Bt[n][k], At[m][k], acc[ai][bj][m][n], 0, 0, 0); __builtin_amdgcn_s_setprio(0); } while (0)
; #define PG8_WAIT_V(n) asm volatile("s_waitcnt vmcnt(" #n ")" ::: "memory")
; #define PG8_WAIT_L(n) asm volatile("s_waitcnt lgkmcnt(" #n ")" ::: "memory")
; #define PG8_BAR __builtin_amdgcn_s_barrier()
; #define PG8_SCHED __builtin_amdgcn_sched_barrier(0)
; template <class Epi, class Sched, bool ALIGN_EPI = false, bool SP2 = false>
; __device__ __forceinline__ void gemm_phase(PG8_LAS unsigned char* lds, const Gemm g, const Sched& S, const Epi& E, const int wid) {
;     ...
;             PG8_WAIT_V(8); PG8_WAIT_L(0); PG8_BAR; PG8_MMA(1, 0, At, B0); PG8_MMA(1, 1, At, B1); PG8_BAR; PG8_SCHED;
;             PG8_LDB(B0, 1, 0); PG8_LDB(B1, 1, 1); PG8_SCHED; PG8_LDA(At, 1, 0); PG8_STAGE(PG8_SA(0, 1), a2 + hstep, voffA);
;             PG8_WAIT_V(8); PG8_WAIT_L(0); PG8_BAR; PG8_MMA(0, 0, At, B0); PG8_MMA(0, 1, At, B1); PG8_BAR; PG8_SCHED;
	v_mfma_f32_16x16x32_bf16 v[92:95], v[128:131], v[160:163], v[92:95]
	v_mfma_f32_16x16x32_bf16 v[88:91], v[136:139], v[160:163], v[88:91]
	v_mfma_f32_16x16x32_bf16 v[84:87], v[128:131], v[184:187], v[84:87]
	v_mfma_f32_16x16x32_bf16 v[80:83], v[136:139], v[184:187], v[80:83]
	v_mfma_f32_16x16x32_bf16 v[76:79], v[128:131], v[192:195], v[76:79]
	v_mfma_f32_16x16x32_bf16 v[72:75], v[136:139], v[192:195], v[72:75]
	v_mfma_f32_16x16x32_bf16 v[68:71], v[128:131], v[200:203], v[68:71]
	v_mfma_f32_16x16x32_bf16 v[64:67], v[136:139], v[200:203], v[64:67]
	v_mfma_f32_16x16x32_bf16 v[92:95], v[132:135], v[164:167], v[92:95]
	v_mfma_f32_16x16x32_bf16 v[88:91], v[140:143], v[164:167], v[88:91]
	v_mfma_f32_16x16x32_bf16 v[84:87], v[132:135], v[188:191], v[84:87]
	v_mfma_f32_16x16x32_bf16 v[80:83], v[140:143], v[188:191], v[80:83]
	v_mfma_f32_16x16x32_bf16 v[76:79], v[132:135], v[196:199], v[76:79]
	v_mfma_f32_16x16x32_bf16 v[72:75], v[140:143], v[196:199], v[72:75]
	v_mfma_f32_16x16x32_bf16 v[68:71], v[132:135], v[214:217], v[68:71]
	v_mfma_f32_16x16x32_bf16 v[64:67], v[140:143], v[214:217], v[64:67]
	s_setprio 0
	s_setprio 1
	v_mfma_f32_16x16x32_bf16 v[28:31], v[144:147], v[160:163], v[28:31]
	v_mfma_f32_16x16x32_bf16 v[24:27], v[152:155], v[160:163], v[24:27]
	v_mfma_f32_16x16x32_bf16 v[20:23], v[144:147], v[184:187], v[20:23]
	v_mfma_f32_16x16x32_bf16 v[16:19], v[152:155], v[184:187], v[16:19]
	v_mfma_f32_16x16x32_bf16 v[12:15], v[144:147], v[192:195], v[12:15]
	v_mfma_f32_16x16x32_bf16 v[8:11], v[152:155], v[192:195], v[8:11]
	v_mfma_f32_16x16x32_bf16 v[4:7], v[144:147], v[200:203], v[4:7]
	v_mfma_f32_16x16x32_bf16 v[0:3], v[152:155], v[200:203], v[0:3]
	v_mfma_f32_16x16x32_bf16 v[28:31], v[148:151], v[164:167], v[28:31]
	v_mfma_f32_16x16x32_bf16 v[24:27], v[156:159], v[164:167], v[24:27]
	v_mfma_f32_16x16x32_bf16 v[20:23], v[148:151], v[188:191], v[20:23]
	v_mfma_f32_16x16x32_bf16 v[16:19], v[156:159], v[188:191], v[16:19]
	v_mfma_f32_16x16x32_bf16 v[12:15], v[148:151], v[196:199], v[12:15]
	v_mfma_f32_16x16x32_bf16 v[8:11], v[156:159], v[196:199], v[8:11]
	v_mfma_f32_16x16x32_bf16 v[4:7], v[148:151], v[214:217], v[4:7]
	v_mfma_f32_16x16x32_bf16 v[0:3], v[156:159], v[214:217], v[0:3]
	s_barrier
	s_setprio 0
	s_add_i32 s37, 0, 0x18000
	s_add_i32 s76, 0, 0x1c000
	v_add_u32_e32 v140, s37, v207
	v_add_u32_e32 v156, s76, v207
	ds_read_b128 v[128:131], v140
	ds_read_b128 v[132:135], v140 offset:1024
	ds_read_b128 v[136:139], v140 offset:2048
	ds_read_b128 v[140:143], v140 offset:3072
	ds_read_b128 v[144:147], v156
	ds_read_b128 v[148:151], v156 offset:1024
	ds_read_b128 v[152:155], v156 offset:2048
	ds_read_b128 v[156:159], v156 offset:3072
	s_add_u32 s8, s56, 0x200000
	s_addc_u32 s9, s57, 0
	s_mov_b32 m0, s59
	v_lshl_add_u64 v[224:225], s[8:9], 0, v[174:175]
	ds_read_b128 v[160:163], v211 offset:32768
	ds_read_b128 v[164:167], v211 offset:33792
	ds_read_b128 v[184:187], v211 offset:34816
	ds_read_b128 v[188:191], v211 offset:35840
	ds_read_b128 v[192:195], v211 offset:36864
	ds_read_b128 v[196:199], v211 offset:37888
	ds_read_b128 v[200:203], v211 offset:38912
	ds_read_b128 v[214:217], v211 offset:39936
	global_load_lds_dwordx4 v[224:225], off
	v_lshl_add_u64 v[224:225], s[8:9], 0, v[170:171]
	s_mov_b32 m0, s60
	s_nop 0
	global_load_lds_dwordx4 v[224:225], off
	s_waitcnt vmcnt(8)
	s_waitcnt lgkmcnt(0)
	s_setprio 1
	s_barrier
	v_mfma_f32_16x16x32_bf16 v[124:127], v[128:131], v[160:163], v[124:127]
	v_mfma_f32_16x16x32_bf16 v[120:123], v[136:139], v[160:163], v[120:123]
	v_mfma_f32_16x16x32_bf16 v[116:119], v[128:131], v[184:187], v[116:119]
	v_mfma_f32_16x16x32_bf16 v[112:115], v[136:139], v[184:187], v[112:115]
	v_mfma_f32_16x16x32_bf16 v[108:111], v[128:131], v[192:195], v[108:111]
	v_mfma_f32_16x16x32_bf16 v[104:107], v[136:139], v[192:195], v[104:107]
	v_mfma_f32_16x16x32_bf16 v[100:103], v[128:131], v[200:203], v[100:103]
	v_mfma_f32_16x16x32_bf16 v[96:99], v[136:139], v[200:203], v[96:99]
	v_mfma_f32_16x16x32_bf16 v[124:127], v[132:135], v[164:167], v[124:127]
	v_mfma_f32_16x16x32_bf16 v[120:123], v[140:143], v[164:167], v[120:123]
	v_mfma_f32_16x16x32_bf16 v[116:119], v[132:135], v[188:191], v[116:119]
	v_mfma_f32_16x16x32_bf16 v[112:115], v[140:143], v[188:191], v[112:115]
	v_mfma_f32_16x16x32_bf16 v[108:111], v[132:135], v[196:199], v[108:111]
	v_mfma_f32_16x16x32_bf16 v[104:107], v[140:143], v[196:199], v[104:107]
	v_mfma_f32_16x16x32_bf16 v[100:103], v[132:135], v[214:217], v[100:103]
	v_mfma_f32_16x16x32_bf16 v[96:99], v[140:143], v[214:217], v[96:99]
	s_setprio 0
	s_setprio 1
	v_mfma_f32_16x16x32_bf16 v[60:63], v[144:147], v[160:163], v[60:63]
	v_mfma_f32_16x16x32_bf16 v[56:59], v[152:155], v[160:163], v[56:59]
	v_mfma_f32_16x16x32_bf16 v[52:55], v[144:147], v[184:187], v[52:55]
	v_mfma_f32_16x16x32_bf16 v[48:51], v[152:155], v[184:187], v[48:51]
	v_mfma_f32_16x16x32_bf16 v[44:47], v[144:147], v[192:195], v[44:47]
	v_mfma_f32_16x16x32_bf16 v[40:43], v[152:155], v[192:195], v[40:43]
	v_mfma_f32_16x16x32_bf16 v[36:39], v[144:147], v[200:203], v[36:39]
	v_mfma_f32_16x16x32_bf16 v[32:35], v[152:155], v[200:203], v[32:35]
	v_mfma_f32_16x16x32_bf16 v[60:63], v[148:151], v[164:167], v[60:63]
	v_mfma_f32_16x16x32_bf16 v[56:59], v[156:159], v[164:167], v[56:59]
	v_mfma_f32_16x16x32_bf16 v[52:55], v[148:151], v[188:191], v[52:55]
	v_mfma_f32_16x16x32_bf16 v[48:51], v[156:159], v[188:191], v[48:51]
	v_mfma_f32_16x16x32_bf16 v[44:47], v[148:151], v[196:199], v[44:47]
	v_mfma_f32_16x16x32_bf16 v[40:43], v[156:159], v[196:199], v[40:43]
	v_mfma_f32_16x16x32_bf16 v[36:39], v[148:151], v[214:217], v[36:39]
	v_mfma_f32_16x16x32_bf16 v[32:35], v[156:159], v[214:217], v[32:35]
	s_barrier
; #define PG8_STAGE(bufoff, gbase, voff) do { _Pragma("unroll") for (int _i = 0; _i < 2; ++_i) \
;         __builtin_amdgcn_global_load_lds((const unsigned*)((const char*)(gbase) + (voff)[_i]), (PG8_LAS unsigned*)(lds + (bufoff) + ldsw + _i * 8192), 16, 0, 0); } while (0)
; #define PG8_LDA(dst, b, h) do { _Pragma("unroll") for (int m = 0; m < 4; ++m) _Pragma("unroll") for (int k = 0; k < 2; ++k) dst[m][k] = *(const PG8_LAS bf16x8*)(lds + PG8_SA(b, h) + aoff + m * 2048 + k * 1024); } while (0)
; #define PG8_MMA(ai, bj, At, Bt) do { __builtin_amdgcn_s_setprio(1); _Pragma("unroll") for (int m = 0; m < 4; ++m) _Pragma("unroll") for (int n = 0; n < 2; ++n) _Pragma("unroll") for (int k = 0; k < 2; ++k) \
;         acc[ai][bj][m][n] = __builtin_amdgcn_mfma_f32_16x16x32_bf16(Bt[n][k], At[m][k], acc[ai][bj][m][n], 0, 0, 0); __builtin_amdgcn_s_setprio(0); } while (0)
; #define PG8_WAIT_V(n) asm volatile("s_waitcnt vmcnt(" #n ")" ::: "memory")
; #define PG8_WAIT_L(n) asm volatile("s_waitcnt lgkmcnt(" #n ")" ::: "memory")
; #define PG8_BAR __builtin_amdgcn_s_barrier()
; #define PG8_SCHED __builtin_amdgcn_sched_barrier(0)
; template <class Epi, class Sched, bool ALIGN_EPI = false, bool SP2 = false>
; __device__ __forceinline__ void gemm_phase(PG8_LAS unsigned char* lds, const Gemm g, const Sched& S, const Epi& E, const int wid) {
;     ...
;             PG8_LDA(At, 1, 1); PG8_STAGE(PG8_SB(1, 0), b3, voffB); PG8_STAGE(PG8_SB(1, 1), b3 + hstep, voffB); PG8_STAGE(PG8_SA(1, 0), a3, voffA);
;             PG8_WAIT_V(8); PG8_WAIT_L(0); PG8_BAR; PG8_MMA(1, 0, At, B0); PG8_MMA(1, 1, At, B1); PG8_BAR; PG8_SCHED;
;     ...
;         if constexpr (ALIGN_EPI) { if (wr == 0) PG8_BAR; }
	s_setprio 0
	s_add_i32 s8, s37, s3
	v_lshl_add_u64 v[204:205], v[204:205], 0, s[28:29]
	s_mov_b32 m0, s8
	ds_read_b128 v[160:163], v211 offset:49152
	ds_read_b128 v[164:167], v211 offset:50176
	ds_read_b128 v[184:187], v211 offset:51200
	ds_read_b128 v[188:191], v211 offset:52224
	ds_read_b128 v[192:195], v211 offset:53248
	ds_read_b128 v[196:199], v211 offset:54272
	ds_read_b128 v[200:203], v211 offset:55296
	ds_read_b128 v[214:217], v211 offset:56320
	global_load_lds_dwordx4 v[204:205], off
	s_add_i32 m0, s8, 0x2000
	s_add_u32 s8, s54, 0x200080
	v_lshl_add_u64 v[204:205], v[218:219], 0, s[28:29]
	s_addc_u32 s9, s55, 0
	s_add_i32 s37, s76, s3
	global_load_lds_dwordx4 v[204:205], off
	v_lshl_add_u64 v[204:205], s[8:9], 0, v[172:173]
	s_mov_b32 m0, s37
	s_nop 0
	global_load_lds_dwordx4 v[204:205], off
	v_lshl_add_u64 v[204:205], s[8:9], 0, v[168:169]
	s_add_i32 m0, s37, 0x2000
	s_nop 0
	global_load_lds_dwordx4 v[204:205], off
	v_lshl_add_u64 v[204:205], v[220:221], 0, s[28:29]
	s_mov_b32 m0, s62
	s_nop 0
	global_load_lds_dwordx4 v[204:205], off
	v_lshl_add_u64 v[204:205], v[222:223], 0, s[28:29]
	s_mov_b32 m0, s63
	s_nop 0
	global_load_lds_dwordx4 v[204:205], off
	s_waitcnt vmcnt(8)
	s_waitcnt lgkmcnt(0)
	s_setprio 1
	s_barrier
	v_mfma_f32_16x16x32_bf16 v[92:95], v[128:131], v[160:163], v[92:95]
	v_mfma_f32_16x16x32_bf16 v[88:91], v[136:139], v[160:163], v[88:91]
	v_mfma_f32_16x16x32_bf16 v[84:87], v[128:131], v[184:187], v[84:87]
	v_mfma_f32_16x16x32_bf16 v[80:83], v[136:139], v[184:187], v[80:83]
	v_mfma_f32_16x16x32_bf16 v[76:79], v[128:131], v[192:195], v[76:79]
	v_mfma_f32_16x16x32_bf16 v[72:75], v[136:139], v[192:195], v[72:75]
	v_mfma_f32_16x16x32_bf16 v[68:71], v[128:131], v[200:203], v[68:71]
	v_mfma_f32_16x16x32_bf16 v[64:67], v[136:139], v[200:203], v[64:67]
	v_mfma_f32_16x16x32_bf16 v[92:95], v[132:135], v[164:167], v[92:95]
	v_mfma_f32_16x16x32_bf16 v[88:91], v[140:143], v[164:167], v[88:91]
	v_mfma_f32_16x16x32_bf16 v[84:87], v[132:135], v[188:191], v[84:87]
	v_mfma_f32_16x16x32_bf16 v[80:83], v[140:143], v[188:191], v[80:83]
	v_mfma_f32_16x16x32_bf16 v[76:79], v[132:135], v[196:199], v[76:79]
	v_mfma_f32_16x16x32_bf16 v[72:75], v[140:143], v[196:199], v[72:75]
	v_mfma_f32_16x16x32_bf16 v[68:71], v[132:135], v[214:217], v[68:71]
	v_mfma_f32_16x16x32_bf16 v[64:67], v[140:143], v[214:217], v[64:67]
	s_setprio 0
	s_setprio 1
	v_mfma_f32_16x16x32_bf16 v[28:31], v[144:147], v[160:163], v[28:31]
	v_mfma_f32_16x16x32_bf16 v[24:27], v[152:155], v[160:163], v[24:27]
	v_mfma_f32_16x16x32_bf16 v[20:23], v[144:147], v[184:187], v[20:23]
	v_mfma_f32_16x16x32_bf16 v[16:19], v[152:155], v[184:187], v[16:19]
	v_mfma_f32_16x16x32_bf16 v[12:15], v[144:147], v[192:195], v[12:15]
	v_mfma_f32_16x16x32_bf16 v[8:11], v[152:155], v[192:195], v[8:11]
	v_mfma_f32_16x16x32_bf16 v[4:7], v[144:147], v[200:203], v[4:7]
	v_mfma_f32_16x16x32_bf16 v[0:3], v[152:155], v[200:203], v[0:3]
	v_mfma_f32_16x16x32_bf16 v[28:31], v[148:151], v[164:167], v[28:31]
	v_mfma_f32_16x16x32_bf16 v[24:27], v[156:159], v[164:167], v[24:27]
	v_mfma_f32_16x16x32_bf16 v[20:23], v[148:151], v[188:191], v[20:23]
	v_mfma_f32_16x16x32_bf16 v[16:19], v[156:159], v[188:191], v[16:19]
	v_mfma_f32_16x16x32_bf16 v[12:15], v[148:151], v[196:199], v[12:15]
	v_mfma_f32_16x16x32_bf16 v[8:11], v[156:159], v[196:199], v[8:11]
	v_mfma_f32_16x16x32_bf16 v[4:7], v[148:151], v[214:217], v[4:7]
	v_mfma_f32_16x16x32_bf16 v[0:3], v[156:159], v[214:217], v[0:3]
	s_barrier
	s_setprio 0
	s_add_i32 s75, s75, 2
	s_add_u32 s73, s73, 0x100
	s_addc_u32 s74, s74, 0
	s_add_u32 s12, s12, 0x100
	s_addc_u32 s13, s13, 0
	s_cmpk_gt_u32 s75, 0x7d
	s_cbranch_scc0 .LBB0_1545
	s_and_b64 vcc, exec, s[20:21]
	s_cbranch_vccz .LBB0_1548
	s_barrier

; #define PG8_STAGE(bufoff, gbase, voff) do { _Pragma("unroll") for (int _i = 0; _i < 2; ++_i) \
;         __builtin_amdgcn_global_load_lds((const unsigned*)((const char*)(gbase) + (voff)[_i]), (PG8_LAS unsigned*)(lds + (bufoff) + ldsw + _i * 8192), 16, 0, 0); } while (0)
; #define PG8_LDA(dst, b, h) do { _Pragma("unroll") for (int m = 0; m < 4; ++m) _Pragma("unroll") for (int k = 0; k < 2; ++k) dst[m][k] = *(const PG8_LAS bf16x8*)(lds + PG8_SA(b, h) + aoff + m * 2048 + k * 1024); } while (0)
; #define PG8_LDB(dst, b, h) do { _Pragma("unroll") for (int n = 0; n < 2; ++n) _Pragma("unroll") for (int k = 0; k < 2; ++k) dst[n][k] = *(const PG8_LAS bf16x8*)(lds + PG8_SB(b, h) + boff + n * 2048 + k * 1024); } while (0)
; #define PG8_MMA(ai, bj, At, Bt) do { __builtin_amdgcn_s_setprio(1); _Pragma("unroll") for (int m = 0; m < 4; ++m) _Pragma("unroll") for (int n = 0; n < 2; ++n) _Pragma("unroll") for (int k = 0; k < 2; ++k) \
;         acc[ai][bj][m][n] = __builtin_amdgcn_mfma_f32_16x16x32_bf16(Bt[n][k], At[m][k], acc[ai][bj][m][n], 0, 0, 0); __builtin_amdgcn_s_setprio(0); } while (0)
; #define PG8_WAIT_V(n) asm volatile("s_waitcnt vmcnt(" #n ")" ::: "memory")
; #define PG8_WAIT_L(n) asm volatile("s_waitcnt lgkmcnt(" #n ")" ::: "memory")
; template <class Epi, class Sched, bool ALIGN_EPI = false, bool SP2 = false>
; __device__ __forceinline__ void gemm_phase(PG8_LAS unsigned char* lds, const Gemm g, const Sched& S, const Epi& E, const int wid) {
;     ...
;             const bool last = (t == nt - 2);
;             const char* a1 = cA + (size_t)(t + 1) * kstep;
;             const char* a2 = last ? nA : cA + (size_t)(t + 2) * kstep; const char* b2 = last ? nB : cB + (size_t)(t + 2) * kstep;
;             const char* a3 = a2 + kstep; const char* b3 = b2 + kstep;
;             if (last && has_next) S.a_ready(nxt);
;             if constexpr (SP2) {
;             PG8_LDB(B0, 0, 0); PG8_LDB(B1, 0, 1); PG8_SCHED; PG8_LDA(At, 0, 0); PG8_STAGE(PG8_SA(1, 1), a1 + hstep, voffA);
;             PG8_WAIT_V(8); PG8_WAIT_L(0); PG8_BAR; PG8_MMA(0, 0, At, B0); PG8_MMA(0, 1, At, B1); PG8_BAR; PG8_SCHED;
;             PG8_LDA(At, 0, 1); PG8_STAGE(PG8_SB(0, 0), b2, voffB); PG8_STAGE(PG8_SB(0, 1), b2 + hstep, voffB); PG8_STAGE(PG8_SA(0, 0), a2, voffA);
;             PG8_WAIT_V(8); PG8_WAIT_L(0); PG8_BAR; PG8_MMA(1, 0, At, B0); PG8_MMA(1, 1, At, B1); PG8_BAR; PG8_SCHED;
.LBB0_1615:
	ds_read_b128 v[128:131], v167
	ds_read_b128 v[132:135], v167 offset:1024
	ds_read_b128 v[136:139], v167 offset:2048
	ds_read_b128 v[140:143], v167 offset:3072
	ds_read_b128 v[174:177], v169
	ds_read_b128 v[178:181], v169 offset:1024
	ds_read_b128 v[182:185], v169 offset:2048
	ds_read_b128 v[186:189], v169 offset:3072
	s_add_u32 s8, s12, 0xfff80080
	s_addc_u32 s9, s13, -1
	s_cmp_eq_u32 s70, 28
	s_cselect_b32 s51, s11, s9
	s_cselect_b32 s50, s31, s8
	s_cselect_b32 s49, s29, s69
	s_cselect_b32 s48, s67, s68
	v_lshl_add_u64 v[222:223], s[12:13], 0, v[154:155]
	s_add_i32 m0, s53, 0xc000
	ds_read_b128 v[190:193], v171
	ds_read_b128 v[194:197], v171 offset:1024
	ds_read_b128 v[198:201], v171 offset:2048
	ds_read_b128 v[202:205], v171 offset:3072
	ds_read_b128 v[206:209], v171 offset:4096
	ds_read_b128 v[210:213], v171 offset:5120
	ds_read_b128 v[214:217], v171 offset:6144
	ds_read_b128 v[218:221], v171 offset:7168
	global_load_lds_dwordx4 v[222:223], off
	v_lshl_add_u64 v[222:223], s[12:13], 0, v[152:153]
	s_add_i32 m0, s53, 0xe000
	s_nop 0
	global_load_lds_dwordx4 v[222:223], off
	s_waitcnt vmcnt(8)
	s_waitcnt lgkmcnt(0)
	s_setprio 1
	s_barrier
	v_mfma_f32_16x16x32_bf16 v[124:127], v[128:131], v[190:193], v[124:127]
	v_mfma_f32_16x16x32_bf16 v[120:123], v[136:139], v[190:193], v[120:123]
	v_mfma_f32_16x16x32_bf16 v[116:119], v[128:131], v[198:201], v[116:119]
	v_mfma_f32_16x16x32_bf16 v[112:115], v[136:139], v[198:201], v[112:115]
	v_mfma_f32_16x16x32_bf16 v[108:111], v[128:131], v[206:209], v[108:111]
	v_mfma_f32_16x16x32_bf16 v[104:107], v[136:139], v[206:209], v[104:107]
	v_mfma_f32_16x16x32_bf16 v[100:103], v[128:131], v[214:217], v[100:103]
	v_mfma_f32_16x16x32_bf16 v[96:99], v[136:139], v[214:217], v[96:99]
	v_mfma_f32_16x16x32_bf16 v[124:127], v[132:135], v[194:197], v[124:127]
	v_mfma_f32_16x16x32_bf16 v[120:123], v[140:143], v[194:197], v[120:123]
	v_mfma_f32_16x16x32_bf16 v[116:119], v[132:135], v[202:205], v[116:119]
	v_mfma_f32_16x16x32_bf16 v[112:115], v[140:143], v[202:205], v[112:115]
	v_mfma_f32_16x16x32_bf16 v[108:111], v[132:135], v[210:213], v[108:111]
	v_mfma_f32_16x16x32_bf16 v[104:107], v[140:143], v[210:213], v[104:107]
	v_mfma_f32_16x16x32_bf16 v[100:103], v[132:135], v[218:221], v[100:103]
	v_mfma_f32_16x16x32_bf16 v[96:99], v[140:143], v[218:221], v[96:99]
	s_setprio 0
	s_setprio 1
	v_mfma_f32_16x16x32_bf16 v[68:71], v[174:177], v[190:193], v[68:71]
	v_mfma_f32_16x16x32_bf16 v[60:63], v[182:185], v[190:193], v[60:63]
	v_mfma_f32_16x16x32_bf16 v[52:55], v[174:177], v[198:201], v[52:55]
	v_mfma_f32_16x16x32_bf16 v[48:51], v[182:185], v[198:201], v[48:51]
	v_mfma_f32_16x16x32_bf16 v[44:47], v[174:177], v[206:209], v[44:47]
	v_mfma_f32_16x16x32_bf16 v[40:43], v[182:185], v[206:209], v[40:43]
	v_mfma_f32_16x16x32_bf16 v[36:39], v[174:177], v[214:217], v[36:39]
	v_mfma_f32_16x16x32_bf16 v[32:35], v[182:185], v[214:217], v[32:35]
	v_mfma_f32_16x16x32_bf16 v[68:71], v[178:181], v[194:197], v[68:71]
	v_mfma_f32_16x16x32_bf16 v[60:63], v[186:189], v[194:197], v[60:63]
	v_mfma_f32_16x16x32_bf16 v[52:55], v[178:181], v[202:205], v[52:55]
	v_mfma_f32_16x16x32_bf16 v[48:51], v[186:189], v[202:205], v[48:51]
	v_mfma_f32_16x16x32_bf16 v[44:47], v[178:181], v[210:213], v[44:47]
	v_mfma_f32_16x16x32_bf16 v[40:43], v[186:189], v[210:213], v[40:43]
	v_mfma_f32_16x16x32_bf16 v[36:39], v[178:181], v[218:221], v[36:39]
	v_mfma_f32_16x16x32_bf16 v[32:35], v[186:189], v[218:221], v[32:35]
	s_barrier
	s_setprio 0
	s_add_i32 s8, s61, s3
	v_lshl_add_u64 v[222:223], s[48:49], 0, v[148:149]
	s_mov_b32 m0, s8
	ds_read_b128 v[190:193], v171 offset:16384
	ds_read_b128 v[194:197], v171 offset:17408
	ds_read_b128 v[198:201], v171 offset:18432
	ds_read_b128 v[202:205], v171 offset:19456
	ds_read_b128 v[206:209], v171 offset:20480
	ds_read_b128 v[210:213], v171 offset:21504
	ds_read_b128 v[214:217], v171 offset:22528
	ds_read_b128 v[218:221], v171 offset:23552
	global_load_lds_dwordx4 v[222:223], off
	s_add_i32 m0, s8, 0x2000
	s_add_u32 s8, s48, 0x80000
	v_lshl_add_u64 v[224:225], s[48:49], 0, v[144:145]
	s_addc_u32 s9, s49, 0
	s_add_i32 s37, s62, s3
	global_load_lds_dwordx4 v[224:225], off
	v_lshl_add_u64 v[226:227], s[8:9], 0, v[148:149]
	s_mov_b32 m0, s37
	v_lshl_add_u64 v[228:229], s[50:51], 0, v[146:147]
	global_load_lds_dwordx4 v[226:227], off
	v_lshl_add_u64 v[226:227], s[8:9], 0, v[144:145]
	s_add_i32 m0, s37, 0x2000
	s_nop 0
	global_load_lds_dwordx4 v[226:227], off
	v_lshl_add_u64 v[226:227], s[50:51], 0, v[150:151]
	s_mov_b32 m0, s53
	s_nop 0
	global_load_lds_dwordx4 v[226:227], off
	s_mov_b32 m0, s54
	s_nop 0
	global_load_lds_dwordx4 v[228:229], off
	s_waitcnt vmcnt(8)
	s_waitcnt lgkmcnt(0)
	s_setprio 1
	s_barrier
; #define PG8_STAGE(bufoff, gbase, voff) do { _Pragma("unroll") for (int _i = 0; _i < 2; ++_i) \
;         __builtin_amdgcn_global_load_lds((const unsigned*)((const char*)(gbase) + (voff)[_i]), (PG8_LAS unsigned*)(lds + (bufoff) + ldsw + _i * 8192), 16, 0, 0); } while (0)
; #define PG8_LDA(dst, b, h) do { _Pragma("unroll") for (int m = 0; m < 4; ++m) _Pragma("unroll") for (int k = 0; k < 2; ++k) dst[m][k] = *(const PG8_LAS bf16x8*)(lds + PG8_SA(b, h) + aoff + m * 2048 + k * 1024); } while (0)
; #define PG8_LDB(dst, b, h) do { _Pragma("unroll") for (int n = 0; n < 2; ++n) _Pragma("unroll") for (int k = 0; k < 2; ++k) dst[n][k] = *(const PG8_LAS bf16x8*)(lds + PG8_SB(b, h) + boff + n * 2048 + k * 1024); } while (0)
; #define PG8_MMA(ai, bj, At, Bt) do { __builtin_amdgcn_s_setprio(1); _Pragma("unroll") for (int m = 0; m < 4; ++m) _Pragma("unroll") for (int n = 0; n < 2; ++n) _Pragma("unroll") for (int k = 0; k < 2; ++k) \
;         acc[ai][bj][m][n] = __builtin_amdgcn_mfma_f32_16x16x32_bf16(Bt[n][k], At[m][k], acc[ai][bj][m][n], 0, 0, 0); __builtin_amdgcn_s_setprio(0); } while (0)
; #define PG8_WAIT_V(n) asm volatile("s_waitcnt vmcnt(" #n ")" ::: "memory")
; #define PG8_WAIT_L(n) asm volatile("s_waitcnt lgkmcnt(" #n ")" ::: "memory")
; #define PG8_BAR __builtin_amdgcn_s_barrier()
; #define PG8_SCHED __builtin_amdgcn_sched_barrier(0)
; template <class Epi, class Sched, bool ALIGN_EPI = false, bool SP2 = false>
; __device__ __forceinline__ void gemm_phase(PG8_LAS unsigned char* lds, const Gemm g, const Sched& S, const Epi& E, const int wid) {
;     ...
;             PG8_WAIT_V(8); PG8_WAIT_L(0); PG8_BAR; PG8_MMA(1, 0, At, B0); PG8_MMA(1, 1, At, B1); PG8_BAR; PG8_SCHED;
;             PG8_LDB(B0, 1, 0); PG8_LDB(B1, 1, 1); PG8_SCHED; PG8_LDA(At, 1, 0); PG8_STAGE(PG8_SA(0, 1), a2 + hstep, voffA);
;             PG8_WAIT_V(8); PG8_WAIT_L(0); PG8_BAR; PG8_MMA(0, 0, At, B0); PG8_MMA(0, 1, At, B1); PG8_BAR; PG8_SCHED;
	v_mfma_f32_16x16x32_bf16 v[92:95], v[128:131], v[190:193], v[92:95]
	v_mfma_f32_16x16x32_bf16 v[88:91], v[136:139], v[190:193], v[88:91]
	v_mfma_f32_16x16x32_bf16 v[84:87], v[128:131], v[198:201], v[84:87]
	v_mfma_f32_16x16x32_bf16 v[80:83], v[136:139], v[198:201], v[80:83]
	v_mfma_f32_16x16x32_bf16 v[76:79], v[128:131], v[206:209], v[76:79]
	v_mfma_f32_16x16x32_bf16 v[72:75], v[136:139], v[206:209], v[72:75]
	v_mfma_f32_16x16x32_bf16 v[64:67], v[128:131], v[214:217], v[64:67]
	v_mfma_f32_16x16x32_bf16 v[56:59], v[136:139], v[214:217], v[56:59]
	v_mfma_f32_16x16x32_bf16 v[92:95], v[132:135], v[194:197], v[92:95]
	v_mfma_f32_16x16x32_bf16 v[88:91], v[140:143], v[194:197], v[88:91]
	v_mfma_f32_16x16x32_bf16 v[84:87], v[132:135], v[202:205], v[84:87]
	v_mfma_f32_16x16x32_bf16 v[80:83], v[140:143], v[202:205], v[80:83]
	v_mfma_f32_16x16x32_bf16 v[76:79], v[132:135], v[210:213], v[76:79]
	v_mfma_f32_16x16x32_bf16 v[72:75], v[140:143], v[210:213], v[72:75]
	v_mfma_f32_16x16x32_bf16 v[64:67], v[132:135], v[218:221], v[64:67]
	v_mfma_f32_16x16x32_bf16 v[56:59], v[140:143], v[218:221], v[56:59]
	s_setprio 0
	s_setprio 1
	v_mfma_f32_16x16x32_bf16 v[28:31], v[174:177], v[190:193], v[28:31]
	v_mfma_f32_16x16x32_bf16 v[24:27], v[182:185], v[190:193], v[24:27]
	v_mfma_f32_16x16x32_bf16 v[20:23], v[174:177], v[198:201], v[20:23]
	v_mfma_f32_16x16x32_bf16 v[16:19], v[182:185], v[198:201], v[16:19]
	v_mfma_f32_16x16x32_bf16 v[12:15], v[174:177], v[206:209], v[12:15]
	v_mfma_f32_16x16x32_bf16 v[8:11], v[182:185], v[206:209], v[8:11]
	v_mfma_f32_16x16x32_bf16 v[4:7], v[174:177], v[214:217], v[4:7]
	v_mfma_f32_16x16x32_bf16 v[0:3], v[182:185], v[214:217], v[0:3]
	v_mfma_f32_16x16x32_bf16 v[28:31], v[178:181], v[194:197], v[28:31]
	v_mfma_f32_16x16x32_bf16 v[24:27], v[186:189], v[194:197], v[24:27]
	v_mfma_f32_16x16x32_bf16 v[20:23], v[178:181], v[202:205], v[20:23]
	v_mfma_f32_16x16x32_bf16 v[16:19], v[186:189], v[202:205], v[16:19]
	v_mfma_f32_16x16x32_bf16 v[12:15], v[178:181], v[210:213], v[12:15]
	v_mfma_f32_16x16x32_bf16 v[8:11], v[186:189], v[210:213], v[8:11]
	v_mfma_f32_16x16x32_bf16 v[4:7], v[178:181], v[218:221], v[4:7]
	v_mfma_f32_16x16x32_bf16 v[0:3], v[186:189], v[218:221], v[0:3]
	s_barrier
	s_setprio 0
	s_add_i32 s37, 0, 0x18000
	s_add_i32 s71, 0, 0x1c000
	v_add_u32_e32 v140, s37, v163
	v_add_u32_e32 v160, s71, v163
	ds_read_b128 v[128:131], v140
	ds_read_b128 v[132:135], v140 offset:1024
	ds_read_b128 v[136:139], v140 offset:2048
	ds_read_b128 v[140:143], v140 offset:3072
	ds_read_b128 v[174:177], v160
	ds_read_b128 v[178:181], v160 offset:1024
	ds_read_b128 v[182:185], v160 offset:2048
	ds_read_b128 v[186:189], v160 offset:3072
	s_add_u32 s8, s50, 0x80000
	s_addc_u32 s9, s51, 0
	s_mov_b32 m0, s55
	v_lshl_add_u64 v[230:231], s[8:9], 0, v[150:151]
	ds_read_b128 v[190:193], v171 offset:32768
	ds_read_b128 v[194:197], v171 offset:33792
	ds_read_b128 v[198:201], v171 offset:34816
	ds_read_b128 v[202:205], v171 offset:35840
	ds_read_b128 v[206:209], v171 offset:36864
	ds_read_b128 v[210:213], v171 offset:37888
	ds_read_b128 v[214:217], v171 offset:38912
	ds_read_b128 v[218:221], v171 offset:39936
	global_load_lds_dwordx4 v[230:231], off
	v_lshl_add_u64 v[230:231], s[8:9], 0, v[146:147]
	s_mov_b32 m0, s56
	s_nop 0
	global_load_lds_dwordx4 v[230:231], off
	s_waitcnt vmcnt(8)
	s_waitcnt lgkmcnt(0)
	s_setprio 1
	s_barrier
	v_mfma_f32_16x16x32_bf16 v[124:127], v[128:131], v[190:193], v[124:127]
	v_mfma_f32_16x16x32_bf16 v[120:123], v[136:139], v[190:193], v[120:123]
	v_mfma_f32_16x16x32_bf16 v[116:119], v[128:131], v[198:201], v[116:119]
	v_mfma_f32_16x16x32_bf16 v[112:115], v[136:139], v[198:201], v[112:115]
	v_mfma_f32_16x16x32_bf16 v[108:111], v[128:131], v[206:209], v[108:111]
	v_mfma_f32_16x16x32_bf16 v[104:107], v[136:139], v[206:209], v[104:107]
	v_mfma_f32_16x16x32_bf16 v[100:103], v[128:131], v[214:217], v[100:103]
	v_mfma_f32_16x16x32_bf16 v[96:99], v[136:139], v[214:217], v[96:99]
	v_mfma_f32_16x16x32_bf16 v[124:127], v[132:135], v[194:197], v[124:127]
	v_mfma_f32_16x16x32_bf16 v[120:123], v[140:143], v[194:197], v[120:123]
	v_mfma_f32_16x16x32_bf16 v[116:119], v[132:135], v[202:205], v[116:119]
	v_mfma_f32_16x16x32_bf16 v[112:115], v[140:143], v[202:205], v[112:115]
	v_mfma_f32_16x16x32_bf16 v[108:111], v[132:135], v[210:213], v[108:111]
	v_mfma_f32_16x16x32_bf16 v[104:107], v[140:143], v[210:213], v[104:107]
	v_mfma_f32_16x16x32_bf16 v[100:103], v[132:135], v[218:221], v[100:103]
	v_mfma_f32_16x16x32_bf16 v[96:99], v[140:143], v[218:221], v[96:99]
	s_setprio 0
	s_setprio 1
	v_mfma_f32_16x16x32_bf16 v[68:71], v[174:177], v[190:193], v[68:71]
	v_mfma_f32_16x16x32_bf16 v[60:63], v[182:185], v[190:193], v[60:63]
	v_mfma_f32_16x16x32_bf16 v[52:55], v[174:177], v[198:201], v[52:55]
	v_mfma_f32_16x16x32_bf16 v[48:51], v[182:185], v[198:201], v[48:51]
	v_mfma_f32_16x16x32_bf16 v[44:47], v[174:177], v[206:209], v[44:47]
	v_mfma_f32_16x16x32_bf16 v[40:43], v[182:185], v[206:209], v[40:43]
	v_mfma_f32_16x16x32_bf16 v[36:39], v[174:177], v[214:217], v[36:39]
	v_mfma_f32_16x16x32_bf16 v[32:35], v[182:185], v[214:217], v[32:35]
	v_mfma_f32_16x16x32_bf16 v[68:71], v[178:181], v[194:197], v[68:71]
	v_mfma_f32_16x16x32_bf16 v[60:63], v[186:189], v[194:197], v[60:63]
	v_mfma_f32_16x16x32_bf16 v[52:55], v[178:181], v[202:205], v[52:55]
	v_mfma_f32_16x16x32_bf16 v[48:51], v[186:189], v[202:205], v[48:51]
	v_mfma_f32_16x16x32_bf16 v[44:47], v[178:181], v[210:213], v[44:47]
	v_mfma_f32_16x16x32_bf16 v[40:43], v[186:189], v[210:213], v[40:43]
	v_mfma_f32_16x16x32_bf16 v[36:39], v[178:181], v[218:221], v[36:39]
	v_mfma_f32_16x16x32_bf16 v[32:35], v[186:189], v[218:221], v[32:35]
	s_barrier
; #define PG8_STAGE(bufoff, gbase, voff) do { _Pragma("unroll") for (int _i = 0; _i < 2; ++_i) \
;         __builtin_amdgcn_global_load_lds((const unsigned*)((const char*)(gbase) + (voff)[_i]), (PG8_LAS unsigned*)(lds + (bufoff) + ldsw + _i * 8192), 16, 0, 0); } while (0)
; #define PG8_LDA(dst, b, h) do { _Pragma("unroll") for (int m = 0; m < 4; ++m) _Pragma("unroll") for (int k = 0; k < 2; ++k) dst[m][k] = *(const PG8_LAS bf16x8*)(lds + PG8_SA(b, h) + aoff + m * 2048 + k * 1024); } while (0)
; #define PG8_MMA(ai, bj, At, Bt) do { __builtin_amdgcn_s_setprio(1); _Pragma("unroll") for (int m = 0; m < 4; ++m) _Pragma("unroll") for (int n = 0; n < 2; ++n) _Pragma("unroll") for (int k = 0; k < 2; ++k) \
;         acc[ai][bj][m][n] = __builtin_amdgcn_mfma_f32_16x16x32_bf16(Bt[n][k], At[m][k], acc[ai][bj][m][n], 0, 0, 0); __builtin_amdgcn_s_setprio(0); } while (0)
; #define PG8_WAIT_V(n) asm volatile("s_waitcnt vmcnt(" #n ")" ::: "memory")
; #define PG8_WAIT_L(n) asm volatile("s_waitcnt lgkmcnt(" #n ")" ::: "memory")
; #define PG8_BAR __builtin_amdgcn_s_barrier()
; #define PG8_SCHED __builtin_amdgcn_sched_barrier(0)
; template <class Epi, class Sched, bool ALIGN_EPI = false, bool SP2 = false>
; __device__ __forceinline__ void gemm_phase(PG8_LAS unsigned char* lds, const Gemm g, const Sched& S, const Epi& E, const int wid) {
;     ...
;             PG8_LDA(At, 1, 1); PG8_STAGE(PG8_SB(1, 0), b3, voffB); PG8_STAGE(PG8_SB(1, 1), b3 + hstep, voffB); PG8_STAGE(PG8_SA(1, 0), a3, voffA);
;             PG8_WAIT_V(8); PG8_WAIT_L(0); PG8_BAR; PG8_MMA(1, 0, At, B0); PG8_MMA(1, 1, At, B1); PG8_BAR; PG8_SCHED;
;     ...
;         if constexpr (ALIGN_EPI) { if (wr == 0) PG8_BAR; }
	s_setprio 0
	s_add_i32 s8, s37, s3
	v_lshl_add_u64 v[222:223], v[222:223], 0, s[24:25]
	s_mov_b32 m0, s8
	ds_read_b128 v[190:193], v171 offset:49152
	ds_read_b128 v[194:197], v171 offset:50176
	ds_read_b128 v[198:201], v171 offset:51200
	ds_read_b128 v[202:205], v171 offset:52224
	ds_read_b128 v[206:209], v171 offset:53248
	ds_read_b128 v[210:213], v171 offset:54272
	ds_read_b128 v[214:217], v171 offset:55296
	ds_read_b128 v[218:221], v171 offset:56320
	global_load_lds_dwordx4 v[222:223], off
	s_add_i32 m0, s8, 0x2000
	s_add_u32 s8, s48, 0x80080
	v_lshl_add_u64 v[222:223], v[224:225], 0, s[24:25]
	s_addc_u32 s9, s49, 0
	s_add_i32 s37, s71, s3
	global_load_lds_dwordx4 v[222:223], off
	v_lshl_add_u64 v[222:223], s[8:9], 0, v[148:149]
	s_mov_b32 m0, s37
	s_nop 0
	global_load_lds_dwordx4 v[222:223], off
	v_lshl_add_u64 v[222:223], s[8:9], 0, v[144:145]
	s_add_i32 m0, s37, 0x2000
	s_nop 0
	global_load_lds_dwordx4 v[222:223], off
	v_lshl_add_u64 v[222:223], v[226:227], 0, s[24:25]
	s_mov_b32 m0, s58
	s_nop 0
	global_load_lds_dwordx4 v[222:223], off
	v_lshl_add_u64 v[222:223], v[228:229], 0, s[24:25]
	s_mov_b32 m0, s59
	s_nop 0
	global_load_lds_dwordx4 v[222:223], off
	s_waitcnt vmcnt(8)
	s_waitcnt lgkmcnt(0)
	s_setprio 1
	s_barrier
	v_mfma_f32_16x16x32_bf16 v[92:95], v[128:131], v[190:193], v[92:95]
	v_mfma_f32_16x16x32_bf16 v[88:91], v[136:139], v[190:193], v[88:91]
	v_mfma_f32_16x16x32_bf16 v[84:87], v[128:131], v[198:201], v[84:87]
	v_mfma_f32_16x16x32_bf16 v[80:83], v[136:139], v[198:201], v[80:83]
	v_mfma_f32_16x16x32_bf16 v[76:79], v[128:131], v[206:209], v[76:79]
	v_mfma_f32_16x16x32_bf16 v[72:75], v[136:139], v[206:209], v[72:75]
	v_mfma_f32_16x16x32_bf16 v[64:67], v[128:131], v[214:217], v[64:67]
	v_mfma_f32_16x16x32_bf16 v[56:59], v[136:139], v[214:217], v[56:59]
	v_mfma_f32_16x16x32_bf16 v[92:95], v[132:135], v[194:197], v[92:95]
	v_mfma_f32_16x16x32_bf16 v[88:91], v[140:143], v[194:197], v[88:91]
	v_mfma_f32_16x16x32_bf16 v[84:87], v[132:135], v[202:205], v[84:87]
	v_mfma_f32_16x16x32_bf16 v[80:83], v[140:143], v[202:205], v[80:83]
	v_mfma_f32_16x16x32_bf16 v[76:79], v[132:135], v[210:213], v[76:79]
	v_mfma_f32_16x16x32_bf16 v[72:75], v[140:143], v[210:213], v[72:75]
	v_mfma_f32_16x16x32_bf16 v[64:67], v[132:135], v[218:221], v[64:67]
	v_mfma_f32_16x16x32_bf16 v[56:59], v[140:143], v[218:221], v[56:59]
	s_setprio 0
	s_setprio 1
	v_mfma_f32_16x16x32_bf16 v[28:31], v[174:177], v[190:193], v[28:31]
	v_mfma_f32_16x16x32_bf16 v[24:27], v[182:185], v[190:193], v[24:27]
	v_mfma_f32_16x16x32_bf16 v[20:23], v[174:177], v[198:201], v[20:23]
	v_mfma_f32_16x16x32_bf16 v[16:19], v[182:185], v[198:201], v[16:19]
	v_mfma_f32_16x16x32_bf16 v[12:15], v[174:177], v[206:209], v[12:15]
	v_mfma_f32_16x16x32_bf16 v[8:11], v[182:185], v[206:209], v[8:11]
	v_mfma_f32_16x16x32_bf16 v[4:7], v[174:177], v[214:217], v[4:7]
	v_mfma_f32_16x16x32_bf16 v[0:3], v[182:185], v[214:217], v[0:3]
	v_mfma_f32_16x16x32_bf16 v[28:31], v[178:181], v[194:197], v[28:31]
	v_mfma_f32_16x16x32_bf16 v[24:27], v[186:189], v[194:197], v[24:27]
	v_mfma_f32_16x16x32_bf16 v[20:23], v[178:181], v[202:205], v[20:23]
	v_mfma_f32_16x16x32_bf16 v[16:19], v[186:189], v[202:205], v[16:19]
	v_mfma_f32_16x16x32_bf16 v[12:15], v[178:181], v[210:213], v[12:15]
	v_mfma_f32_16x16x32_bf16 v[8:11], v[186:189], v[210:213], v[8:11]
	v_mfma_f32_16x16x32_bf16 v[4:7], v[178:181], v[218:221], v[4:7]
	v_mfma_f32_16x16x32_bf16 v[0:3], v[186:189], v[218:221], v[0:3]
	s_barrier
	s_setprio 0
	s_add_i32 s70, s70, 2
	s_add_u32 s68, s68, 0x100
	s_addc_u32 s69, s69, 0
	s_add_u32 s12, s12, 0x100
	s_addc_u32 s13, s13, 0
	s_cmp_lt_u32 s70, 30
	s_cbranch_scc1 .LBB0_1615
	s_andn2_b64 vcc, exec, s[20:21]
	s_cbranch_vccnz .LBB0_1618
	s_barrier

; #define PG8_STAGE(bufoff, gbase, voff) do { _Pragma("unroll") for (int _i = 0; _i < 2; ++_i) \
;         __builtin_amdgcn_global_load_lds((const unsigned*)((const char*)(gbase) + (voff)[_i]), (PG8_LAS unsigned*)(lds + (bufoff) + ldsw + _i * 8192), 16, 0, 0); } while (0)
; #define PG8_LDA(dst, b, h) do { _Pragma("unroll") for (int m = 0; m < 4; ++m) _Pragma("unroll") for (int k = 0; k < 2; ++k) dst[m][k] = *(const PG8_LAS bf16x8*)(lds + PG8_SA(b, h) + aoff + m * 2048 + k * 1024); } while (0)
; #define PG8_LDB(dst, b, h) do { _Pragma("unroll") for (int n = 0; n < 2; ++n) _Pragma("unroll") for (int k = 0; k < 2; ++k) dst[n][k] = *(const PG8_LAS bf16x8*)(lds + PG8_SB(b, h) + boff + n * 2048 + k * 1024); } while (0)
; #define PG8_MMA(ai, bj, At, Bt) do { __builtin_amdgcn_s_setprio(1); _Pragma("unroll") for (int m = 0; m < 4; ++m) _Pragma("unroll") for (int n = 0; n < 2; ++n) _Pragma("unroll") for (int k = 0; k < 2; ++k) \
;         acc[ai][bj][m][n] = __builtin_amdgcn_mfma_f32_16x16x32_bf16(Bt[n][k], At[m][k], acc[ai][bj][m][n], 0, 0, 0); __builtin_amdgcn_s_setprio(0); } while (0)
; #define PG8_WAIT_V(n) asm volatile("s_waitcnt vmcnt(" #n ")" ::: "memory")
; #define PG8_WAIT_L(n) asm volatile("s_waitcnt lgkmcnt(" #n ")" ::: "memory")
; template <class Epi, class Sched, bool ALIGN_EPI = false, bool SP2 = false>
; __device__ __forceinline__ void gemm_phase(PG8_LAS unsigned char* lds, const Gemm g, const Sched& S, const Epi& E, const int wid) {
;     ...
;             const bool last = (t == nt - 2);
;             const char* a1 = cA + (size_t)(t + 1) * kstep;
;             const char* a2 = last ? nA : cA + (size_t)(t + 2) * kstep; const char* b2 = last ? nB : cB + (size_t)(t + 2) * kstep;
;             const char* a3 = a2 + kstep; const char* b3 = b2 + kstep;
;             if (last && has_next) S.a_ready(nxt);
;             if constexpr (SP2) {
;             PG8_LDB(B0, 0, 0); PG8_LDB(B1, 0, 1); PG8_SCHED; PG8_LDA(At, 0, 0); PG8_STAGE(PG8_SA(1, 1), a1 + hstep, voffA);
;             PG8_WAIT_V(8); PG8_WAIT_L(0); PG8_BAR; PG8_MMA(0, 0, At, B0); PG8_MMA(0, 1, At, B1); PG8_BAR; PG8_SCHED;
;             PG8_LDA(At, 0, 1); PG8_STAGE(PG8_SB(0, 0), b2, voffB); PG8_STAGE(PG8_SB(0, 1), b2 + hstep, voffB); PG8_STAGE(PG8_SA(0, 0), a2, voffA);
;             PG8_WAIT_V(8); PG8_WAIT_L(0); PG8_BAR; PG8_MMA(1, 0, At, B0); PG8_MMA(1, 1, At, B1); PG8_BAR; PG8_SCHED;
.LBB0_1685:
	ds_read_b128 v[128:131], v209
	ds_read_b128 v[132:135], v209 offset:1024
	ds_read_b128 v[136:139], v209 offset:2048
	ds_read_b128 v[140:143], v209 offset:3072
	ds_read_b128 v[144:147], v210
	ds_read_b128 v[148:151], v210 offset:1024
	ds_read_b128 v[152:155], v210 offset:2048
	ds_read_b128 v[156:159], v210 offset:3072
	s_add_u32 s48, s8, 0xffe00080
	s_addc_u32 s49, s9, -1
	s_cmpk_eq_i32 s67, 0x7c
	s_cselect_b32 s51, s31, s49
	s_cselect_b32 s50, s63, s48
	s_cselect_b32 s49, s29, s66
	s_cselect_b32 s48, s64, s65
	v_lshl_add_u64 v[204:205], s[8:9], 0, v[178:179]
	s_add_i32 m0, s47, 0xc000
	ds_read_b128 v[160:163], v211
	ds_read_b128 v[164:167], v211 offset:1024
	ds_read_b128 v[184:187], v211 offset:2048
	ds_read_b128 v[188:191], v211 offset:3072
	ds_read_b128 v[192:195], v211 offset:4096
	ds_read_b128 v[196:199], v211 offset:5120
	ds_read_b128 v[200:203], v211 offset:6144
	ds_read_b128 v[214:217], v211 offset:7168
	global_load_lds_dwordx4 v[204:205], off
	v_lshl_add_u64 v[204:205], s[8:9], 0, v[176:177]
	s_add_i32 m0, s47, 0xe000
	s_nop 0
	global_load_lds_dwordx4 v[204:205], off
	s_waitcnt vmcnt(8)
	s_waitcnt lgkmcnt(0)
	s_setprio 1
	s_barrier
	v_mfma_f32_16x16x32_bf16 v[124:127], v[128:131], v[160:163], v[124:127]
	v_mfma_f32_16x16x32_bf16 v[120:123], v[136:139], v[160:163], v[120:123]
	v_mfma_f32_16x16x32_bf16 v[116:119], v[128:131], v[184:187], v[116:119]
	v_mfma_f32_16x16x32_bf16 v[112:115], v[136:139], v[184:187], v[112:115]
	v_mfma_f32_16x16x32_bf16 v[108:111], v[128:131], v[192:195], v[108:111]
	v_mfma_f32_16x16x32_bf16 v[104:107], v[136:139], v[192:195], v[104:107]
	v_mfma_f32_16x16x32_bf16 v[100:103], v[128:131], v[200:203], v[100:103]
	v_mfma_f32_16x16x32_bf16 v[96:99], v[136:139], v[200:203], v[96:99]
	v_mfma_f32_16x16x32_bf16 v[124:127], v[132:135], v[164:167], v[124:127]
	v_mfma_f32_16x16x32_bf16 v[120:123], v[140:143], v[164:167], v[120:123]
	v_mfma_f32_16x16x32_bf16 v[116:119], v[132:135], v[188:191], v[116:119]
	v_mfma_f32_16x16x32_bf16 v[112:115], v[140:143], v[188:191], v[112:115]
	v_mfma_f32_16x16x32_bf16 v[108:111], v[132:135], v[196:199], v[108:111]
	v_mfma_f32_16x16x32_bf16 v[104:107], v[140:143], v[196:199], v[104:107]
	v_mfma_f32_16x16x32_bf16 v[100:103], v[132:135], v[214:217], v[100:103]
	v_mfma_f32_16x16x32_bf16 v[96:99], v[140:143], v[214:217], v[96:99]
	s_setprio 0
	s_setprio 1
	v_mfma_f32_16x16x32_bf16 v[60:63], v[144:147], v[160:163], v[60:63]
	v_mfma_f32_16x16x32_bf16 v[56:59], v[152:155], v[160:163], v[56:59]
	v_mfma_f32_16x16x32_bf16 v[52:55], v[144:147], v[184:187], v[52:55]
	v_mfma_f32_16x16x32_bf16 v[48:51], v[152:155], v[184:187], v[48:51]
	v_mfma_f32_16x16x32_bf16 v[44:47], v[144:147], v[192:195], v[44:47]
	v_mfma_f32_16x16x32_bf16 v[40:43], v[152:155], v[192:195], v[40:43]
	v_mfma_f32_16x16x32_bf16 v[36:39], v[144:147], v[200:203], v[36:39]
	v_mfma_f32_16x16x32_bf16 v[32:35], v[152:155], v[200:203], v[32:35]
	v_mfma_f32_16x16x32_bf16 v[60:63], v[148:151], v[164:167], v[60:63]
	v_mfma_f32_16x16x32_bf16 v[56:59], v[156:159], v[164:167], v[56:59]
	v_mfma_f32_16x16x32_bf16 v[52:55], v[148:151], v[188:191], v[52:55]
	v_mfma_f32_16x16x32_bf16 v[48:51], v[156:159], v[188:191], v[48:51]
	v_mfma_f32_16x16x32_bf16 v[44:47], v[148:151], v[196:199], v[44:47]
	v_mfma_f32_16x16x32_bf16 v[40:43], v[156:159], v[196:199], v[40:43]
	v_mfma_f32_16x16x32_bf16 v[36:39], v[148:151], v[214:217], v[36:39]
	v_mfma_f32_16x16x32_bf16 v[32:35], v[156:159], v[214:217], v[32:35]
	s_barrier
	s_setprio 0
	s_add_i32 s68, s37, s3
	v_lshl_add_u64 v[204:205], s[48:49], 0, v[172:173]
	s_mov_b32 m0, s68
	ds_read_b128 v[160:163], v211 offset:16384
	ds_read_b128 v[164:167], v211 offset:17408
	ds_read_b128 v[184:187], v211 offset:18432
	ds_read_b128 v[188:191], v211 offset:19456
	ds_read_b128 v[192:195], v211 offset:20480
	ds_read_b128 v[196:199], v211 offset:21504
	ds_read_b128 v[200:203], v211 offset:22528
	ds_read_b128 v[214:217], v211 offset:23552
	global_load_lds_dwordx4 v[204:205], off
	s_add_i32 m0, s68, 0x2000
	s_add_u32 s68, s48, 0x200000
	v_lshl_add_u64 v[218:219], s[48:49], 0, v[168:169]
	s_addc_u32 s69, s49, 0
	s_add_i32 s70, s58, s3
	global_load_lds_dwordx4 v[218:219], off
	v_lshl_add_u64 v[220:221], s[68:69], 0, v[172:173]
	s_mov_b32 m0, s70
	v_lshl_add_u64 v[222:223], s[50:51], 0, v[170:171]
	global_load_lds_dwordx4 v[220:221], off
	v_lshl_add_u64 v[220:221], s[68:69], 0, v[168:169]
	s_add_i32 m0, s70, 0x2000
	s_nop 0
	global_load_lds_dwordx4 v[220:221], off
	v_lshl_add_u64 v[220:221], s[50:51], 0, v[174:175]
	s_mov_b32 m0, s47
	s_nop 0
	global_load_lds_dwordx4 v[220:221], off
	s_mov_b32 m0, s52
	s_nop 0
	global_load_lds_dwordx4 v[222:223], off
	s_waitcnt vmcnt(8)
	s_waitcnt lgkmcnt(0)
	s_setprio 1
	s_barrier
; #define PG8_STAGE(bufoff, gbase, voff) do { _Pragma("unroll") for (int _i = 0; _i < 2; ++_i) \
;         __builtin_amdgcn_global_load_lds((const unsigned*)((const char*)(gbase) + (voff)[_i]), (PG8_LAS unsigned*)(lds + (bufoff) + ldsw + _i * 8192), 16, 0, 0); } while (0)
; #define PG8_LDA(dst, b, h) do { _Pragma("unroll") for (int m = 0; m < 4; ++m) _Pragma("unroll") for (int k = 0; k < 2; ++k) dst[m][k] = *(const PG8_LAS bf16x8*)(lds + PG8_SA(b, h) + aoff + m * 2048 + k * 1024); } while (0)
; #define PG8_LDB(dst, b, h) do { _Pragma("unroll") for (int n = 0; n < 2; ++n) _Pragma("unroll") for (int k = 0; k < 2; ++k) dst[n][k] = *(const PG8_LAS bf16x8*)(lds + PG8_SB(b, h) + boff + n * 2048 + k * 1024); } while (0)
; #define PG8_MMA(ai, bj, At, Bt) do { __builtin_amdgcn_s_setprio(1); _Pragma("unroll") for (int m = 0; m < 4; ++m) _Pragma("unroll") for (int n = 0; n < 2; ++n) _Pragma("unroll") for (int k = 0; k < 2; ++k) \
;         acc[ai][bj][m][n] = __builtin_amdgcn_mfma_f32_16x16x32_bf16(Bt[n][k], At[m][k], acc[ai][bj][m][n], 0, 0, 0); __builtin_amdgcn_s_setprio(0); } while (0)
; #define PG8_WAIT_V(n) asm volatile("s_waitcnt vmcnt(" #n ")" ::: "memory")
; #define PG8_WAIT_L(n) asm volatile("s_waitcnt lgkmcnt(" #n ")" ::: "memory")
; #define PG8_BAR __builtin_amdgcn_s_barrier()
; #define PG8_SCHED __builtin_amdgcn_sched_barrier(0)
; template <class Epi, class Sched, bool ALIGN_EPI = false, bool SP2 = false>
; __device__ __forceinline__ void gemm_phase(PG8_LAS unsigned char* lds, const Gemm g, const Sched& S, const Epi& E, const int wid) {
;     ...
;             PG8_WAIT_V(8); PG8_WAIT_L(0); PG8_BAR; PG8_MMA(1, 0, At, B0); PG8_MMA(1, 1, At, B1); PG8_BAR; PG8_SCHED;
;             PG8_LDB(B0, 1, 0); PG8_LDB(B1, 1, 1); PG8_SCHED; PG8_LDA(At, 1, 0); PG8_STAGE(PG8_SA(0, 1), a2 + hstep, voffA);
;             PG8_WAIT_V(8); PG8_WAIT_L(0); PG8_BAR; PG8_MMA(0, 0, At, B0); PG8_MMA(0, 1, At, B1); PG8_BAR; PG8_SCHED;
	v_mfma_f32_16x16x32_bf16 v[92:95], v[128:131], v[160:163], v[92:95]
	v_mfma_f32_16x16x32_bf16 v[88:91], v[136:139], v[160:163], v[88:91]
	v_mfma_f32_16x16x32_bf16 v[84:87], v[128:131], v[184:187], v[84:87]
	v_mfma_f32_16x16x32_bf16 v[80:83], v[136:139], v[184:187], v[80:83]
	v_mfma_f32_16x16x32_bf16 v[76:79], v[128:131], v[192:195], v[76:79]
	v_mfma_f32_16x16x32_bf16 v[72:75], v[136:139], v[192:195], v[72:75]
	v_mfma_f32_16x16x32_bf16 v[68:71], v[128:131], v[200:203], v[68:71]
	v_mfma_f32_16x16x32_bf16 v[64:67], v[136:139], v[200:203], v[64:67]
	v_mfma_f32_16x16x32_bf16 v[92:95], v[132:135], v[164:167], v[92:95]
	v_mfma_f32_16x16x32_bf16 v[88:91], v[140:143], v[164:167], v[88:91]
	v_mfma_f32_16x16x32_bf16 v[84:87], v[132:135], v[188:191], v[84:87]
	v_mfma_f32_16x16x32_bf16 v[80:83], v[140:143], v[188:191], v[80:83]
	v_mfma_f32_16x16x32_bf16 v[76:79], v[132:135], v[196:199], v[76:79]
	v_mfma_f32_16x16x32_bf16 v[72:75], v[140:143], v[196:199], v[72:75]
	v_mfma_f32_16x16x32_bf16 v[68:71], v[132:135], v[214:217], v[68:71]
	v_mfma_f32_16x16x32_bf16 v[64:67], v[140:143], v[214:217], v[64:67]
	s_setprio 0
	s_setprio 1
	v_mfma_f32_16x16x32_bf16 v[28:31], v[144:147], v[160:163], v[28:31]
	v_mfma_f32_16x16x32_bf16 v[24:27], v[152:155], v[160:163], v[24:27]
	v_mfma_f32_16x16x32_bf16 v[20:23], v[144:147], v[184:187], v[20:23]
	v_mfma_f32_16x16x32_bf16 v[16:19], v[152:155], v[184:187], v[16:19]
	v_mfma_f32_16x16x32_bf16 v[12:15], v[144:147], v[192:195], v[12:15]
	v_mfma_f32_16x16x32_bf16 v[8:11], v[152:155], v[192:195], v[8:11]
	v_mfma_f32_16x16x32_bf16 v[4:7], v[144:147], v[200:203], v[4:7]
	v_mfma_f32_16x16x32_bf16 v[0:3], v[152:155], v[200:203], v[0:3]
	v_mfma_f32_16x16x32_bf16 v[28:31], v[148:151], v[164:167], v[28:31]
	v_mfma_f32_16x16x32_bf16 v[24:27], v[156:159], v[164:167], v[24:27]
	v_mfma_f32_16x16x32_bf16 v[20:23], v[148:151], v[188:191], v[20:23]
	v_mfma_f32_16x16x32_bf16 v[16:19], v[156:159], v[188:191], v[16:19]
	v_mfma_f32_16x16x32_bf16 v[12:15], v[148:151], v[196:199], v[12:15]
	v_mfma_f32_16x16x32_bf16 v[8:11], v[156:159], v[196:199], v[8:11]
	v_mfma_f32_16x16x32_bf16 v[4:7], v[148:151], v[214:217], v[4:7]
	v_mfma_f32_16x16x32_bf16 v[0:3], v[156:159], v[214:217], v[0:3]
	s_barrier
	s_setprio 0
	s_add_i32 s68, 0, 0x18000
	s_add_i32 s69, 0, 0x1c000
	v_add_u32_e32 v140, s68, v206
	v_add_u32_e32 v156, s69, v206
	ds_read_b128 v[128:131], v140
	ds_read_b128 v[132:135], v140 offset:1024
	ds_read_b128 v[136:139], v140 offset:2048
	ds_read_b128 v[140:143], v140 offset:3072
	ds_read_b128 v[144:147], v156
	ds_read_b128 v[148:151], v156 offset:1024
	ds_read_b128 v[152:155], v156 offset:2048
	ds_read_b128 v[156:159], v156 offset:3072
	s_add_u32 s50, s50, 0x200000
	s_addc_u32 s51, s51, 0
	s_mov_b32 m0, s53
	v_lshl_add_u64 v[224:225], s[50:51], 0, v[174:175]
	ds_read_b128 v[160:163], v211 offset:32768
	ds_read_b128 v[164:167], v211 offset:33792
	ds_read_b128 v[184:187], v211 offset:34816
	ds_read_b128 v[188:191], v211 offset:35840
	ds_read_b128 v[192:195], v211 offset:36864
	ds_read_b128 v[196:199], v211 offset:37888
	ds_read_b128 v[200:203], v211 offset:38912
	ds_read_b128 v[214:217], v211 offset:39936
	global_load_lds_dwordx4 v[224:225], off
	v_lshl_add_u64 v[224:225], s[50:51], 0, v[170:171]
	s_mov_b32 m0, s54
	s_nop 0
	global_load_lds_dwordx4 v[224:225], off
	s_waitcnt vmcnt(8)
	s_waitcnt lgkmcnt(0)
	s_setprio 1
	s_barrier
	v_mfma_f32_16x16x32_bf16 v[124:127], v[128:131], v[160:163], v[124:127]
	v_mfma_f32_16x16x32_bf16 v[120:123], v[136:139], v[160:163], v[120:123]
	v_mfma_f32_16x16x32_bf16 v[116:119], v[128:131], v[184:187], v[116:119]
	v_mfma_f32_16x16x32_bf16 v[112:115], v[136:139], v[184:187], v[112:115]
	v_mfma_f32_16x16x32_bf16 v[108:111], v[128:131], v[192:195], v[108:111]
	v_mfma_f32_16x16x32_bf16 v[104:107], v[136:139], v[192:195], v[104:107]
	v_mfma_f32_16x16x32_bf16 v[100:103], v[128:131], v[200:203], v[100:103]
	v_mfma_f32_16x16x32_bf16 v[96:99], v[136:139], v[200:203], v[96:99]
	v_mfma_f32_16x16x32_bf16 v[124:127], v[132:135], v[164:167], v[124:127]
	v_mfma_f32_16x16x32_bf16 v[120:123], v[140:143], v[164:167], v[120:123]
	v_mfma_f32_16x16x32_bf16 v[116:119], v[132:135], v[188:191], v[116:119]
	v_mfma_f32_16x16x32_bf16 v[112:115], v[140:143], v[188:191], v[112:115]
	v_mfma_f32_16x16x32_bf16 v[108:111], v[132:135], v[196:199], v[108:111]
	v_mfma_f32_16x16x32_bf16 v[104:107], v[140:143], v[196:199], v[104:107]
	v_mfma_f32_16x16x32_bf16 v[100:103], v[132:135], v[214:217], v[100:103]
	v_mfma_f32_16x16x32_bf16 v[96:99], v[140:143], v[214:217], v[96:99]
	s_setprio 0
	s_setprio 1
	v_mfma_f32_16x16x32_bf16 v[60:63], v[144:147], v[160:163], v[60:63]
	v_mfma_f32_16x16x32_bf16 v[56:59], v[152:155], v[160:163], v[56:59]
	v_mfma_f32_16x16x32_bf16 v[52:55], v[144:147], v[184:187], v[52:55]
	v_mfma_f32_16x16x32_bf16 v[48:51], v[152:155], v[184:187], v[48:51]
	v_mfma_f32_16x16x32_bf16 v[44:47], v[144:147], v[192:195], v[44:47]
	v_mfma_f32_16x16x32_bf16 v[40:43], v[152:155], v[192:195], v[40:43]
	v_mfma_f32_16x16x32_bf16 v[36:39], v[144:147], v[200:203], v[36:39]
	v_mfma_f32_16x16x32_bf16 v[32:35], v[152:155], v[200:203], v[32:35]
	v_mfma_f32_16x16x32_bf16 v[60:63], v[148:151], v[164:167], v[60:63]
	v_mfma_f32_16x16x32_bf16 v[56:59], v[156:159], v[164:167], v[56:59]
	v_mfma_f32_16x16x32_bf16 v[52:55], v[148:151], v[188:191], v[52:55]
	v_mfma_f32_16x16x32_bf16 v[48:51], v[156:159], v[188:191], v[48:51]
	v_mfma_f32_16x16x32_bf16 v[44:47], v[148:151], v[196:199], v[44:47]
	v_mfma_f32_16x16x32_bf16 v[40:43], v[156:159], v[196:199], v[40:43]
	v_mfma_f32_16x16x32_bf16 v[36:39], v[148:151], v[214:217], v[36:39]
	v_mfma_f32_16x16x32_bf16 v[32:35], v[156:159], v[214:217], v[32:35]
	s_barrier
; #define PG8_STAGE(bufoff, gbase, voff) do { _Pragma("unroll") for (int _i = 0; _i < 2; ++_i) \
;         __builtin_amdgcn_global_load_lds((const unsigned*)((const char*)(gbase) + (voff)[_i]), (PG8_LAS unsigned*)(lds + (bufoff) + ldsw + _i * 8192), 16, 0, 0); } while (0)
; #define PG8_LDA(dst, b, h) do { _Pragma("unroll") for (int m = 0; m < 4; ++m) _Pragma("unroll") for (int k = 0; k < 2; ++k) dst[m][k] = *(const PG8_LAS bf16x8*)(lds + PG8_SA(b, h) + aoff + m * 2048 + k * 1024); } while (0)
; #define PG8_MMA(ai, bj, At, Bt) do { __builtin_amdgcn_s_setprio(1); _Pragma("unroll") for (int m = 0; m < 4; ++m) _Pragma("unroll") for (int n = 0; n < 2; ++n) _Pragma("unroll") for (int k = 0; k < 2; ++k) \
;         acc[ai][bj][m][n] = __builtin_amdgcn_mfma_f32_16x16x32_bf16(Bt[n][k], At[m][k], acc[ai][bj][m][n], 0, 0, 0); __builtin_amdgcn_s_setprio(0); } while (0)
; #define PG8_WAIT_V(n) asm volatile("s_waitcnt vmcnt(" #n ")" ::: "memory")
; #define PG8_WAIT_L(n) asm volatile("s_waitcnt lgkmcnt(" #n ")" ::: "memory")
; #define PG8_BAR __builtin_amdgcn_s_barrier()
; #define PG8_SCHED __builtin_amdgcn_sched_barrier(0)
; template <class Epi, class Sched, bool ALIGN_EPI = false, bool SP2 = false>
; __device__ __forceinline__ void gemm_phase(PG8_LAS unsigned char* lds, const Gemm g, const Sched& S, const Epi& E, const int wid) {
;     ...
;             PG8_LDA(At, 1, 1); PG8_STAGE(PG8_SB(1, 0), b3, voffB); PG8_STAGE(PG8_SB(1, 1), b3 + hstep, voffB); PG8_STAGE(PG8_SA(1, 0), a3, voffA);
;             PG8_WAIT_V(8); PG8_WAIT_L(0); PG8_BAR; PG8_MMA(1, 0, At, B0); PG8_MMA(1, 1, At, B1); PG8_BAR; PG8_SCHED;
;     ...
;         if constexpr (ALIGN_EPI) { if (wr == 0) PG8_BAR; }
	s_setprio 0
	s_add_i32 s50, s68, s3
	v_lshl_add_u64 v[204:205], v[204:205], 0, s[24:25]
	s_mov_b32 m0, s50
	ds_read_b128 v[160:163], v211 offset:49152
	ds_read_b128 v[164:167], v211 offset:50176
	ds_read_b128 v[184:187], v211 offset:51200
	ds_read_b128 v[188:191], v211 offset:52224
	ds_read_b128 v[192:195], v211 offset:53248
	ds_read_b128 v[196:199], v211 offset:54272
	ds_read_b128 v[200:203], v211 offset:55296
	ds_read_b128 v[214:217], v211 offset:56320
	global_load_lds_dwordx4 v[204:205], off
	s_add_i32 m0, s50, 0x2000
	s_add_u32 s48, s48, 0x200080
	v_lshl_add_u64 v[204:205], v[218:219], 0, s[24:25]
	s_addc_u32 s49, s49, 0
	s_add_i32 s50, s69, s3
	global_load_lds_dwordx4 v[204:205], off
	v_lshl_add_u64 v[204:205], s[48:49], 0, v[172:173]
	s_mov_b32 m0, s50
	s_nop 0
	global_load_lds_dwordx4 v[204:205], off
	v_lshl_add_u64 v[204:205], s[48:49], 0, v[168:169]
	s_add_i32 m0, s50, 0x2000
	s_nop 0
	global_load_lds_dwordx4 v[204:205], off
	v_lshl_add_u64 v[204:205], v[220:221], 0, s[24:25]
	s_mov_b32 m0, s56
	s_nop 0
	global_load_lds_dwordx4 v[204:205], off
	v_lshl_add_u64 v[204:205], v[222:223], 0, s[24:25]
	s_mov_b32 m0, s57
	s_nop 0
	global_load_lds_dwordx4 v[204:205], off
	s_waitcnt vmcnt(8)
	s_waitcnt lgkmcnt(0)
	s_setprio 1
	s_barrier
	v_mfma_f32_16x16x32_bf16 v[92:95], v[128:131], v[160:163], v[92:95]
	v_mfma_f32_16x16x32_bf16 v[88:91], v[136:139], v[160:163], v[88:91]
	v_mfma_f32_16x16x32_bf16 v[84:87], v[128:131], v[184:187], v[84:87]
	v_mfma_f32_16x16x32_bf16 v[80:83], v[136:139], v[184:187], v[80:83]
	v_mfma_f32_16x16x32_bf16 v[76:79], v[128:131], v[192:195], v[76:79]
	v_mfma_f32_16x16x32_bf16 v[72:75], v[136:139], v[192:195], v[72:75]
	v_mfma_f32_16x16x32_bf16 v[68:71], v[128:131], v[200:203], v[68:71]
	v_mfma_f32_16x16x32_bf16 v[64:67], v[136:139], v[200:203], v[64:67]
	v_mfma_f32_16x16x32_bf16 v[92:95], v[132:135], v[164:167], v[92:95]
	v_mfma_f32_16x16x32_bf16 v[88:91], v[140:143], v[164:167], v[88:91]
	v_mfma_f32_16x16x32_bf16 v[84:87], v[132:135], v[188:191], v[84:87]
	v_mfma_f32_16x16x32_bf16 v[80:83], v[140:143], v[188:191], v[80:83]
	v_mfma_f32_16x16x32_bf16 v[76:79], v[132:135], v[196:199], v[76:79]
	v_mfma_f32_16x16x32_bf16 v[72:75], v[140:143], v[196:199], v[72:75]
	v_mfma_f32_16x16x32_bf16 v[68:71], v[132:135], v[214:217], v[68:71]
	v_mfma_f32_16x16x32_bf16 v[64:67], v[140:143], v[214:217], v[64:67]
	s_setprio 0
	s_setprio 1
	v_mfma_f32_16x16x32_bf16 v[28:31], v[144:147], v[160:163], v[28:31]
	v_mfma_f32_16x16x32_bf16 v[24:27], v[152:155], v[160:163], v[24:27]
	v_mfma_f32_16x16x32_bf16 v[20:23], v[144:147], v[184:187], v[20:23]
	v_mfma_f32_16x16x32_bf16 v[16:19], v[152:155], v[184:187], v[16:19]
	v_mfma_f32_16x16x32_bf16 v[12:15], v[144:147], v[192:195], v[12:15]
	v_mfma_f32_16x16x32_bf16 v[8:11], v[152:155], v[192:195], v[8:11]
	v_mfma_f32_16x16x32_bf16 v[4:7], v[144:147], v[200:203], v[4:7]
	v_mfma_f32_16x16x32_bf16 v[0:3], v[152:155], v[200:203], v[0:3]
	v_mfma_f32_16x16x32_bf16 v[28:31], v[148:151], v[164:167], v[28:31]
	v_mfma_f32_16x16x32_bf16 v[24:27], v[156:159], v[164:167], v[24:27]
	v_mfma_f32_16x16x32_bf16 v[20:23], v[148:151], v[188:191], v[20:23]
	v_mfma_f32_16x16x32_bf16 v[16:19], v[156:159], v[188:191], v[16:19]
	v_mfma_f32_16x16x32_bf16 v[12:15], v[148:151], v[196:199], v[12:15]
	v_mfma_f32_16x16x32_bf16 v[8:11], v[156:159], v[196:199], v[8:11]
	v_mfma_f32_16x16x32_bf16 v[4:7], v[148:151], v[214:217], v[4:7]
	v_mfma_f32_16x16x32_bf16 v[0:3], v[156:159], v[214:217], v[0:3]
	s_barrier
	s_setprio 0
	s_add_i32 s67, s67, 2
	s_add_u32 s65, s65, 0x100
	s_addc_u32 s66, s66, 0
	s_add_u32 s8, s8, 0x100
	s_addc_u32 s9, s9, 0
	s_cmpk_lt_u32 s67, 0x7e
	s_cbranch_scc1 .LBB0_1685
	s_andn2_b64 vcc, exec, s[20:21]
	s_cbranch_vccnz .LBB0_1688
	s_barrier
